# strategy 4: one static s_setprio 1 for the younger wave half in the GEMM phases, per-segment priority flips deleted
# baseline (speedup 1.0000x reference)
.LBB0_50:
	s_cmp_gt_i32 s91, 1
	s_cselect_b64 s[2:3], -1, 0
	s_and_b64 s[0:1], s[4:5], s[2:3]
	s_andn2_b64 vcc, exec, s[0:1]
	s_cbranch_vccnz .LBB0_104
	s_waitcnt vmcnt(0)
	s_setprio 0
	s_barrier
	s_and_saveexec_b64 s[0:1], s[92:93]
	s_cbranch_execz .LBB0_103
	s_add_i32 s4, 0, 0x27ff0
	v_mov_b32_e32 v0, s4
	s_waitcnt vmcnt(0) expcnt(0) lgkmcnt(0)
	ds_read_b32 v2, v0
	s_add_i32 s4, 0, 0x27ff4
	v_mov_b32_e32 v0, s4
	ds_read_b32 v0, v0
	s_waitcnt lgkmcnt(1)
	v_cmp_ne_u32_e32 vcc, 0, v2
	s_cbranch_vccnz .LBB0_67
	s_add_u32 s4, s30, 0x38200
	s_addc_u32 s5, s31, 0
	s_add_u32 s6, s30, 0x38400
	s_addc_u32 s7, s31, 0
	s_add_u32 s10, s30, 0x38500
	s_addc_u32 s11, s31, 0
	s_add_u32 s12, s30, 0x38600
	s_addc_u32 s13, s31, 0
	s_add_u32 s14, s30, 0x38700
	s_addc_u32 s15, s31, 0
	s_add_u32 s16, s30, 0x38800
	s_addc_u32 s17, s31, 0
	s_add_u32 s18, s30, 0x38900
	s_addc_u32 s19, s31, 0
	s_add_u32 s20, s30, 0x38a00
	s_addc_u32 s21, s31, 0
	s_add_u32 s22, s30, 0x38b00
	s_addc_u32 s23, s31, 0
	s_add_u32 s24, s30, 0x38c00
	s_addc_u32 s25, s31, 0
	s_add_u32 s26, s30, 0x38d00
	s_addc_u32 s27, s31, 0
	s_add_u32 s34, s30, 0x38e00
	s_addc_u32 s35, s31, 0
	s_add_u32 s38, s30, 0x38f00
	s_addc_u32 s39, s31, 0
	s_add_u32 s42, s30, 0x39000
	s_addc_u32 s43, s31, 0
	s_add_u32 s46, s30, 0x39100
	s_addc_u32 s47, s31, 0
	s_add_u32 s48, s30, 0x39200
	s_addc_u32 s49, s31, 0
	s_mul_i32 s33, s89, s9
	s_add_u32 s56, s30, 0x39300
	s_mul_i32 s33, s33, s88
	s_addc_u32 s57, s31, 0
	s_mov_b32 s64, 1
	v_mov_b32_e32 v16, 0
	s_branch .LBB0_55

.LBB0_148:
	s_cmp_gt_i32 s91, 2
	s_cselect_b64 s[2:3], -1, 0
	s_and_b64 s[0:1], s[0:1], s[2:3]
	s_andn2_b64 vcc, exec, s[0:1]
	s_cbranch_vccnz .LBB0_202
	s_waitcnt vmcnt(0)
	s_waitcnt lgkmcnt(0)
	s_setprio 0
	s_barrier
	s_and_saveexec_b64 s[0:1], s[92:93]
	s_cbranch_execz .LBB0_201
	s_add_i32 s4, 0, 0x27ff0
	v_mov_b32_e32 v0, s4
	s_waitcnt vmcnt(0) expcnt(0) lgkmcnt(0)
	ds_read_b32 v2, v0
	s_add_i32 s4, 0, 0x27ff4
	v_mov_b32_e32 v0, s4
	ds_read_b32 v0, v0
	s_waitcnt lgkmcnt(1)
	v_cmp_ne_u32_e32 vcc, 0, v2
	s_cbranch_vccnz .LBB0_165
	s_add_u32 s4, s30, 0x38200
	s_addc_u32 s5, s31, 0
	s_add_u32 s6, s30, 0x38400
	s_addc_u32 s7, s31, 0
	s_add_u32 s10, s30, 0x38500
	s_addc_u32 s11, s31, 0
	s_add_u32 s12, s30, 0x38600
	s_addc_u32 s13, s31, 0
	s_add_u32 s14, s30, 0x38700
	s_addc_u32 s15, s31, 0
	s_add_u32 s16, s30, 0x38800
	s_addc_u32 s17, s31, 0
	s_add_u32 s18, s30, 0x38900
	s_addc_u32 s19, s31, 0
	s_add_u32 s20, s30, 0x38a00
	s_addc_u32 s21, s31, 0
	s_add_u32 s22, s30, 0x38b00
	s_addc_u32 s23, s31, 0
	s_add_u32 s24, s30, 0x38c00
	s_addc_u32 s25, s31, 0
	s_add_u32 s26, s30, 0x38d00
	s_addc_u32 s27, s31, 0
	s_add_u32 s34, s30, 0x38e00
	s_addc_u32 s35, s31, 0
	s_add_u32 s36, s30, 0x38f00
	s_addc_u32 s37, s31, 0
	s_add_u32 s40, s30, 0x39000
	s_addc_u32 s41, s31, 0
	s_add_u32 s44, s30, 0x39100
	s_addc_u32 s45, s31, 0
	s_add_u32 s46, s30, 0x39200
	s_addc_u32 s47, s31, 0
	s_mul_i32 s33, s89, s9
	s_add_u32 s48, s30, 0x39300
	s_mul_i32 s33, s33, s88
	s_addc_u32 s49, s31, 0
	s_mov_b32 s62, 1
	v_mov_b32_e32 v16, 0
	s_branch .LBB0_153

.LBB0_208:
	v_ashrrev_i32_e32 v1, 31, v8
	v_lshrrev_b32_e32 v1, 26, v1
	v_add_u32_e32 v1, v8, v1
	v_ashrrev_i32_e32 v9, 6, v1
	v_bfe_i32 v1, v8, 27, 1
	v_lshlrev_b32_e32 v0, 4, v8
	v_lshrrev_b32_e32 v1, 22, v1
	v_add_u32_e32 v1, v0, v1
	v_and_b32_e32 v1, 0xfffffc00, v1
	v_sub_u32_e32 v1, v0, v1
	v_lshrrev_b32_e32 v2, 4, v1
	v_bitop3_b32 v1, v2, v1, 32 bitop3:0x6c
	v_ashrrev_i32_e32 v3, 31, v1
	v_lshrrev_b32_e32 v3, 26, v3
	v_add_u32_e32 v3, v1, v3
	v_lshlrev_b32_e32 v2, 3, v9
	v_ashrrev_i32_e32 v10, 6, v3
	v_and_b32_e32 v3, 0xc0, v3
	v_and_b32_e32 v2, -16, v2
	v_sub_u32_e32 v1, v1, v3
	v_mov_b32_e32 v3, 1
	v_add_u32_e32 v2, v10, v2
	v_ashrrev_i16_sdwa v1, v3, sext(v1) dst_sel:DWORD dst_unused:UNUSED_PAD src0_sel:DWORD src1_sel:BYTE_0
	s_ashr_i32 s2, s5, 3
	v_lshlrev_b32_e32 v4, 5, v9
	v_bfe_i32 v11, v1, 0, 16
	v_lshlrev_b32_e32 v1, 1, v2
	v_lshrrev_b32_e32 v5, 2, v2
	v_and_b32_e32 v6, 3, v10
	s_mov_b32 s5, 0x1fffe0
	v_and_b32_e32 v4, 32, v4
	v_and_b32_e32 v1, 24, v1
	v_and_b32_e32 v5, 4, v5
	v_and_or_b32 v6, v2, s5, v6
	v_or3_b32 v1, v6, v5, v1
	v_add_lshl_u32 v4, v4, v11, 1
	v_add_u32_e32 v0, 0x2000, v0
	v_lshl_add_u32 v146, v1, 11, v4
	v_ashrrev_i32_e32 v1, 31, v0
	v_lshrrev_b32_e32 v1, 22, v1
	v_add_u32_e32 v1, v0, v1
	v_ashrrev_i32_e32 v12, 10, v1
	v_mul_i32_i24_e32 v1, 0x400, v12
	v_sub_u32_e32 v0, v0, v1
	v_lshrrev_b32_e32 v1, 4, v0
	v_bitop3_b32 v0, v1, v0, 32 bitop3:0x6c
	v_lshl_add_u32 v144, v2, 11, v4
	v_ashrrev_i32_e32 v2, 31, v0
	v_lshrrev_b32_e32 v2, 26, v2
	v_add_u32_e32 v2, v0, v2
	s_add_u32 s40, s30, 0x200000
	v_lshlrev_b32_e32 v1, 3, v12
	v_ashrrev_i32_e32 v13, 6, v2
	v_and_b32_e32 v2, 0xc0, v2
	s_addc_u32 s41, s31, 0
	v_and_b32_e32 v1, -16, v1
	v_sub_u32_e32 v0, v0, v2
	s_add_i32 s2, s4, s2
	v_add_u32_e32 v1, v13, v1
	v_ashrrev_i16_sdwa v0, v3, sext(v0) dst_sel:DWORD dst_unused:UNUSED_PAD src0_sel:DWORD src1_sel:BYTE_0
	v_and_b32_e32 v3, 3, v13
	s_mul_hi_i32 s4, s2, 0x2e8ba2e9
	v_and_or_b32 v3, v1, s5, v3
	s_lshr_b32 s5, s4, 31
	s_ashr_i32 s4, s4, 5
	s_add_i32 s4, s4, s5
	v_lshlrev_b32_e32 v4, 5, v12
	v_bfe_i32 v14, v0, 0, 16
	v_lshlrev_b32_e32 v0, 1, v1
	v_lshrrev_b32_e32 v2, 2, v1
	s_lshl_b32 s6, s4, 3
	v_and_b32_e32 v4, 32, v4
	v_and_b32_e32 v0, 24, v0
	v_and_b32_e32 v2, 4, v2
	s_sub_i32 s5, 0x42, s6
	s_mulk_i32 s4, 0xb0
	v_or3_b32 v0, v3, v2, v0
	v_add_lshl_u32 v2, v4, v14, 1
	s_min_u32 s7, s5, 8
	s_sub_i32 s11, s2, s4
	v_lshl_add_u32 v148, v1, 11, v2
	s_sext_i32_i16 s2, s11
	v_cvt_f32_ubyte0_e32 v1, s7
	v_lshl_add_u32 v150, v0, 11, v2
	v_cvt_f32_i32_e32 v0, s2
	v_rcp_iflag_f32_e32 v2, v1
	s_ashr_i32 s10, s12, 6
	s_ashr_i32 s2, s2, 30
	s_ashr_i32 s3, s12, 8
	v_mul_f32_e32 v2, v0, v2
	v_trunc_f32_e32 v2, v2
	v_fma_f32 v0, -v2, v1, v0
	v_cvt_i32_f32_e32 v2, v2
	s_lshl_b32 s44, s10, 10
	s_or_b32 s2, s2, 1
	v_cmp_ge_f32_e64 s[4:5], |v0|, v1
	s_and_b64 s[4:5], s[4:5], exec
	s_cselect_b32 s2, s2, 0
	v_readfirstlane_b32 s4, v2
	s_add_i32 s2, s4, s2
	s_mul_i32 s4, s2, s7
	s_sub_i32 s4, s11, s4
	s_sext_i32_i16 s4, s4
	s_add_i32 s22, s6, s4
	s_ashr_i32 s23, s22, 31
	s_bfe_i64 s[6:7], s[2:3], 0x100000
	s_lshl_b64 s[4:5], s[22:23], 19
	s_lshl_b64 s[6:7], s[6:7], 19
	s_add_u32 s26, s40, s6
	s_addc_u32 s27, s41, s7
	s_add_i32 s23, s44, 0
	s_add_i32 m0, s23, 0x10000
	v_mov_b32_e32 v147, 0
	global_load_lds_dwordx4 v146, s[26:27]
	s_add_i32 m0, s23, 0x12000
	s_add_u32 s6, s26, 0x40000
	global_load_lds_dwordx4 v150, s[26:27]
	s_addc_u32 s7, s27, 0
	s_add_i32 m0, s23, 0x14000
	v_mov_b32_e32 v151, v147
	global_load_lds_dwordx4 v146, s[6:7]
	s_add_i32 m0, s23, 0x16000
	s_add_u32 s24, s42, s4
	s_addc_u32 s25, s43, s5
	s_add_i32 s45, s23, 0x2000
	global_load_lds_dwordx4 v150, s[6:7]
	s_mov_b32 m0, s23
	s_add_u32 s4, s24, 0x40000
	global_load_lds_dwordx4 v144, s[24:25]
	s_mov_b32 m0, s45
	s_addc_u32 s5, s25, 0
	s_add_i32 s46, s23, 0x4000
	global_load_lds_dwordx4 v148, s[24:25]
	s_mov_b32 m0, s46
	s_add_i32 s47, s23, 0x6000
	global_load_lds_dwordx4 v144, s[4:5]
	s_mov_b32 m0, s47
	v_mov_b32_e32 v145, v147
	global_load_lds_dwordx4 v148, s[4:5]
	v_mov_b32_e32 v149, v147
	s_cmp_eq_u32 s3, 1
	s_mov_b32 s48, 0
	v_lshl_add_u64 v[6:7], s[26:27], 0, v[146:147]
	v_lshl_add_u64 v[4:5], s[26:27], 0, v[150:151]
	v_lshl_add_u64 v[0:1], s[24:25], 0, v[144:145]
	s_cselect_b64 s[4:5], -1, 0
	s_cmp_lg_u32 s3, 1
	v_lshl_add_u64 v[2:3], s[24:25], 0, v[148:149]
	s_cbranch_scc1 .LBB0_210
	s_barrier
	s_setprio 1

.LBB0_220:
	ds_read_b128 v[104:107], v171
	ds_read_b128 v[108:111], v171 offset:1024
	ds_read_b128 v[112:115], v171 offset:2048
	ds_read_b128 v[116:119], v171 offset:3072
	ds_read_b128 v[160:163], v172
	ds_read_b128 v[164:167], v172 offset:1024
	ds_read_b128 v[178:181], v172 offset:2048
	ds_read_b128 v[182:185], v172 offset:3072
	s_add_u32 s26, s24, 0xfffc0080
	s_addc_u32 s27, s25, -1
	s_cmp_eq_u32 s69, 12
	s_cselect_b32 s35, s17, s27
	s_cselect_b32 s34, s65, s26
	s_cselect_b32 s27, s15, s68
	s_cselect_b32 s26, s66, s67
	v_lshl_add_u64 v[202:203], s[24:25], 0, v[152:153]
	s_add_i32 m0, s23, 0xc000
	ds_read_b128 v[186:189], v173
	ds_read_b128 v[190:193], v173 offset:1024
	ds_read_b128 v[194:197], v173 offset:2048
	ds_read_b128 v[198:201], v173 offset:3072
	ds_read_b128 v[206:209], v173 offset:4096
	ds_read_b128 v[210:213], v173 offset:5120
	ds_read_b128 v[214:217], v173 offset:6144
	ds_read_b128 v[218:221], v173 offset:7168
	global_load_lds_dwordx4 v[202:203], off
	v_lshl_add_u64 v[202:203], s[24:25], 0, v[154:155]
	s_add_i32 m0, s23, 0xe000
	s_nop 0
	global_load_lds_dwordx4 v[202:203], off
	s_waitcnt vmcnt(8)
	s_waitcnt lgkmcnt(0)
	s_barrier
	s_waitcnt lgkmcnt(0)
	v_mfma_f32_16x16x32_f16 v[140:143], v[104:107], v[186:189], v[140:143]
	v_mfma_f32_16x16x32_f16 v[136:139], v[112:115], v[186:189], v[136:139]
	v_mfma_f32_16x16x32_f16 v[124:127], v[104:107], v[194:197], v[124:127]
	v_mfma_f32_16x16x32_f16 v[120:123], v[112:115], v[194:197], v[120:123]
	v_mfma_f32_16x16x32_f16 v[92:95], v[104:107], v[206:209], v[92:95]
	v_mfma_f32_16x16x32_f16 v[88:91], v[112:115], v[206:209], v[88:91]
	v_mfma_f32_16x16x32_f16 v[76:79], v[104:107], v[214:217], v[76:79]
	v_mfma_f32_16x16x32_f16 v[72:75], v[112:115], v[214:217], v[72:75]
	v_mfma_f32_16x16x32_f16 v[140:143], v[108:111], v[190:193], v[140:143]
	v_mfma_f32_16x16x32_f16 v[136:139], v[116:119], v[190:193], v[136:139]
	v_mfma_f32_16x16x32_f16 v[124:127], v[108:111], v[198:201], v[124:127]
	v_mfma_f32_16x16x32_f16 v[120:123], v[116:119], v[198:201], v[120:123]
	v_mfma_f32_16x16x32_f16 v[92:95], v[108:111], v[210:213], v[92:95]
	v_mfma_f32_16x16x32_f16 v[88:91], v[116:119], v[210:213], v[88:91]
	v_mfma_f32_16x16x32_f16 v[76:79], v[108:111], v[218:221], v[76:79]
	v_mfma_f32_16x16x32_f16 v[72:75], v[116:119], v[218:221], v[72:75]
	v_mfma_f32_16x16x32_f16 v[132:135], v[160:163], v[186:189], v[132:135]
	v_mfma_f32_16x16x32_f16 v[128:131], v[178:181], v[186:189], v[128:131]
	v_mfma_f32_16x16x32_f16 v[100:103], v[160:163], v[194:197], v[100:103]
	v_mfma_f32_16x16x32_f16 v[96:99], v[178:181], v[194:197], v[96:99]
	v_mfma_f32_16x16x32_f16 v[84:87], v[160:163], v[206:209], v[84:87]
	v_mfma_f32_16x16x32_f16 v[80:83], v[178:181], v[206:209], v[80:83]
	v_mfma_f32_16x16x32_f16 v[68:71], v[160:163], v[214:217], v[68:71]
	v_mfma_f32_16x16x32_f16 v[64:67], v[178:181], v[214:217], v[64:67]
	v_mfma_f32_16x16x32_f16 v[132:135], v[164:167], v[190:193], v[132:135]
	v_mfma_f32_16x16x32_f16 v[128:131], v[182:185], v[190:193], v[128:131]
	v_mfma_f32_16x16x32_f16 v[100:103], v[164:167], v[198:201], v[100:103]
	v_mfma_f32_16x16x32_f16 v[96:99], v[182:185], v[198:201], v[96:99]
	v_mfma_f32_16x16x32_f16 v[84:87], v[164:167], v[210:213], v[84:87]
	v_mfma_f32_16x16x32_f16 v[80:83], v[182:185], v[210:213], v[80:83]
	v_mfma_f32_16x16x32_f16 v[68:71], v[164:167], v[218:221], v[68:71]
	v_mfma_f32_16x16x32_f16 v[64:67], v[182:185], v[218:221], v[64:67]
	s_barrier
	s_add_i32 s70, s60, s44
	v_lshl_add_u64 v[202:203], s[26:27], 0, v[146:147]
	s_mov_b32 m0, s70
	ds_read_b128 v[186:189], v173 offset:16384
	ds_read_b128 v[190:193], v173 offset:17408
	ds_read_b128 v[194:197], v173 offset:18432
	ds_read_b128 v[198:201], v173 offset:19456
	ds_read_b128 v[206:209], v173 offset:20480
	ds_read_b128 v[210:213], v173 offset:21504
	ds_read_b128 v[214:217], v173 offset:22528
	ds_read_b128 v[218:221], v173 offset:23552
	global_load_lds_dwordx4 v[202:203], off
	s_add_i32 m0, s70, 0x2000
	s_add_u32 s70, s26, 0x40000
	v_lshl_add_u64 v[222:223], s[26:27], 0, v[150:151]
	s_addc_u32 s71, s27, 0
	s_add_i32 s72, s61, s44
	global_load_lds_dwordx4 v[222:223], off
	v_lshl_add_u64 v[224:225], s[70:71], 0, v[146:147]
	s_mov_b32 m0, s72
	v_lshl_add_u64 v[226:227], s[34:35], 0, v[148:149]
	global_load_lds_dwordx4 v[224:225], off
	v_lshl_add_u64 v[224:225], s[70:71], 0, v[150:151]
	s_add_i32 m0, s72, 0x2000
	s_nop 0
	global_load_lds_dwordx4 v[224:225], off
	v_lshl_add_u64 v[224:225], s[34:35], 0, v[144:145]
	s_mov_b32 m0, s23
	s_nop 0
	global_load_lds_dwordx4 v[224:225], off
	s_mov_b32 m0, s45
	s_nop 0
	global_load_lds_dwordx4 v[226:227], off
	s_waitcnt vmcnt(8)
	s_waitcnt lgkmcnt(0)
	s_barrier
	s_waitcnt lgkmcnt(0)
	v_mfma_f32_16x16x32_f16 v[60:63], v[104:107], v[186:189], v[60:63]
	v_mfma_f32_16x16x32_f16 v[56:59], v[112:115], v[186:189], v[56:59]
	v_mfma_f32_16x16x32_f16 v[44:47], v[104:107], v[194:197], v[44:47]
	v_mfma_f32_16x16x32_f16 v[40:43], v[112:115], v[194:197], v[40:43]
	v_mfma_f32_16x16x32_f16 v[28:31], v[104:107], v[206:209], v[28:31]
	v_mfma_f32_16x16x32_f16 v[24:27], v[112:115], v[206:209], v[24:27]
	v_mfma_f32_16x16x32_f16 v[12:15], v[104:107], v[214:217], v[12:15]
	v_mfma_f32_16x16x32_f16 v[8:11], v[112:115], v[214:217], v[8:11]
	v_mfma_f32_16x16x32_f16 v[60:63], v[108:111], v[190:193], v[60:63]
	v_mfma_f32_16x16x32_f16 v[56:59], v[116:119], v[190:193], v[56:59]
	v_mfma_f32_16x16x32_f16 v[44:47], v[108:111], v[198:201], v[44:47]
	v_mfma_f32_16x16x32_f16 v[40:43], v[116:119], v[198:201], v[40:43]
	v_mfma_f32_16x16x32_f16 v[28:31], v[108:111], v[210:213], v[28:31]
	v_mfma_f32_16x16x32_f16 v[24:27], v[116:119], v[210:213], v[24:27]
	v_mfma_f32_16x16x32_f16 v[12:15], v[108:111], v[218:221], v[12:15]
	v_mfma_f32_16x16x32_f16 v[8:11], v[116:119], v[218:221], v[8:11]
	v_mfma_f32_16x16x32_f16 v[52:55], v[160:163], v[186:189], v[52:55]
	v_mfma_f32_16x16x32_f16 v[48:51], v[178:181], v[186:189], v[48:51]
	v_mfma_f32_16x16x32_f16 v[36:39], v[160:163], v[194:197], v[36:39]
	v_mfma_f32_16x16x32_f16 v[32:35], v[178:181], v[194:197], v[32:35]
	v_mfma_f32_16x16x32_f16 v[20:23], v[160:163], v[206:209], v[20:23]
	v_mfma_f32_16x16x32_f16 v[16:19], v[178:181], v[206:209], v[16:19]
	v_mfma_f32_16x16x32_f16 v[4:7], v[160:163], v[214:217], v[4:7]
	v_mfma_f32_16x16x32_f16 v[0:3], v[178:181], v[214:217], v[0:3]
	v_mfma_f32_16x16x32_f16 v[52:55], v[164:167], v[190:193], v[52:55]
	v_mfma_f32_16x16x32_f16 v[48:51], v[182:185], v[190:193], v[48:51]
	v_mfma_f32_16x16x32_f16 v[36:39], v[164:167], v[198:201], v[36:39]
	v_mfma_f32_16x16x32_f16 v[32:35], v[182:185], v[198:201], v[32:35]
	v_mfma_f32_16x16x32_f16 v[20:23], v[164:167], v[210:213], v[20:23]
	v_mfma_f32_16x16x32_f16 v[16:19], v[182:185], v[210:213], v[16:19]
	v_mfma_f32_16x16x32_f16 v[4:7], v[164:167], v[218:221], v[4:7]
	v_mfma_f32_16x16x32_f16 v[0:3], v[182:185], v[218:221], v[0:3]
	s_barrier
	s_add_i32 s70, 0, 0x18000
	s_add_i32 s71, 0, 0x1c000
	v_add_u32_e32 v116, s70, v169
	v_add_u32_e32 v177, s71, v169
	ds_read_b128 v[104:107], v116
	ds_read_b128 v[108:111], v116 offset:1024
	ds_read_b128 v[112:115], v116 offset:2048
	ds_read_b128 v[116:119], v116 offset:3072
	ds_read_b128 v[160:163], v177
	ds_read_b128 v[164:167], v177 offset:1024
	ds_read_b128 v[178:181], v177 offset:2048
	ds_read_b128 v[182:185], v177 offset:3072
	s_add_u32 s34, s34, 0x40000
	s_addc_u32 s35, s35, 0
	s_mov_b32 m0, s46
	v_lshl_add_u64 v[228:229], s[34:35], 0, v[144:145]
	ds_read_b128 v[186:189], v173 offset:32768
	ds_read_b128 v[190:193], v173 offset:33792
	ds_read_b128 v[194:197], v173 offset:34816
	ds_read_b128 v[198:201], v173 offset:35840
	ds_read_b128 v[206:209], v173 offset:36864
	ds_read_b128 v[210:213], v173 offset:37888
	ds_read_b128 v[214:217], v173 offset:38912
	ds_read_b128 v[218:221], v173 offset:39936
	global_load_lds_dwordx4 v[228:229], off
	v_lshl_add_u64 v[228:229], s[34:35], 0, v[148:149]
	s_mov_b32 m0, s47
	s_nop 0
	global_load_lds_dwordx4 v[228:229], off
	s_waitcnt vmcnt(8)
	s_waitcnt lgkmcnt(0)
	s_barrier
	s_waitcnt lgkmcnt(0)
	v_mfma_f32_16x16x32_f16 v[140:143], v[104:107], v[186:189], v[140:143]
	v_mfma_f32_16x16x32_f16 v[136:139], v[112:115], v[186:189], v[136:139]
	v_mfma_f32_16x16x32_f16 v[124:127], v[104:107], v[194:197], v[124:127]
	v_mfma_f32_16x16x32_f16 v[120:123], v[112:115], v[194:197], v[120:123]
	v_mfma_f32_16x16x32_f16 v[92:95], v[104:107], v[206:209], v[92:95]
	v_mfma_f32_16x16x32_f16 v[88:91], v[112:115], v[206:209], v[88:91]
	v_mfma_f32_16x16x32_f16 v[76:79], v[104:107], v[214:217], v[76:79]
	v_mfma_f32_16x16x32_f16 v[72:75], v[112:115], v[214:217], v[72:75]
	v_mfma_f32_16x16x32_f16 v[140:143], v[108:111], v[190:193], v[140:143]
	v_mfma_f32_16x16x32_f16 v[136:139], v[116:119], v[190:193], v[136:139]
	v_mfma_f32_16x16x32_f16 v[124:127], v[108:111], v[198:201], v[124:127]
	v_mfma_f32_16x16x32_f16 v[120:123], v[116:119], v[198:201], v[120:123]
	v_mfma_f32_16x16x32_f16 v[92:95], v[108:111], v[210:213], v[92:95]
	v_mfma_f32_16x16x32_f16 v[88:91], v[116:119], v[210:213], v[88:91]
	v_mfma_f32_16x16x32_f16 v[76:79], v[108:111], v[218:221], v[76:79]
	v_mfma_f32_16x16x32_f16 v[72:75], v[116:119], v[218:221], v[72:75]
	v_mfma_f32_16x16x32_f16 v[132:135], v[160:163], v[186:189], v[132:135]
	v_mfma_f32_16x16x32_f16 v[128:131], v[178:181], v[186:189], v[128:131]
	v_mfma_f32_16x16x32_f16 v[100:103], v[160:163], v[194:197], v[100:103]
	v_mfma_f32_16x16x32_f16 v[96:99], v[178:181], v[194:197], v[96:99]
	v_mfma_f32_16x16x32_f16 v[84:87], v[160:163], v[206:209], v[84:87]
	v_mfma_f32_16x16x32_f16 v[80:83], v[178:181], v[206:209], v[80:83]
	v_mfma_f32_16x16x32_f16 v[68:71], v[160:163], v[214:217], v[68:71]
	v_mfma_f32_16x16x32_f16 v[64:67], v[178:181], v[214:217], v[64:67]
	v_mfma_f32_16x16x32_f16 v[132:135], v[164:167], v[190:193], v[132:135]
	v_mfma_f32_16x16x32_f16 v[128:131], v[182:185], v[190:193], v[128:131]
	v_mfma_f32_16x16x32_f16 v[100:103], v[164:167], v[198:201], v[100:103]
	v_mfma_f32_16x16x32_f16 v[96:99], v[182:185], v[198:201], v[96:99]
	v_mfma_f32_16x16x32_f16 v[84:87], v[164:167], v[210:213], v[84:87]
	v_mfma_f32_16x16x32_f16 v[80:83], v[182:185], v[210:213], v[80:83]
	v_mfma_f32_16x16x32_f16 v[68:71], v[164:167], v[218:221], v[68:71]
	v_mfma_f32_16x16x32_f16 v[64:67], v[182:185], v[218:221], v[64:67]
	s_barrier
	s_add_i32 s34, s70, s44
	v_lshl_add_u64 v[202:203], v[202:203], 0, s[10:11]
	s_mov_b32 m0, s34
	ds_read_b128 v[186:189], v173 offset:49152
	ds_read_b128 v[190:193], v173 offset:50176
	ds_read_b128 v[194:197], v173 offset:51200
	ds_read_b128 v[198:201], v173 offset:52224
	ds_read_b128 v[206:209], v173 offset:53248
	ds_read_b128 v[210:213], v173 offset:54272
	ds_read_b128 v[214:217], v173 offset:55296
	ds_read_b128 v[218:221], v173 offset:56320
	global_load_lds_dwordx4 v[202:203], off
	s_add_i32 m0, s34, 0x2000
	s_add_u32 s26, s26, 0x40080
	v_lshl_add_u64 v[202:203], v[222:223], 0, s[10:11]
	s_addc_u32 s27, s27, 0
	s_add_i32 s34, s71, s44
	global_load_lds_dwordx4 v[202:203], off
	v_lshl_add_u64 v[202:203], s[26:27], 0, v[146:147]
	s_mov_b32 m0, s34
	s_nop 0
	global_load_lds_dwordx4 v[202:203], off
	v_lshl_add_u64 v[202:203], s[26:27], 0, v[150:151]
	s_add_i32 m0, s34, 0x2000
	s_nop 0
	global_load_lds_dwordx4 v[202:203], off
	v_lshl_add_u64 v[202:203], v[224:225], 0, s[10:11]
	s_mov_b32 m0, s57
	s_nop 0
	global_load_lds_dwordx4 v[202:203], off
	v_lshl_add_u64 v[202:203], v[226:227], 0, s[10:11]
	s_mov_b32 m0, s58
	s_nop 0
	global_load_lds_dwordx4 v[202:203], off
	s_waitcnt vmcnt(8)
	s_waitcnt lgkmcnt(0)
	s_barrier
	s_waitcnt lgkmcnt(0)
	v_mfma_f32_16x16x32_f16 v[60:63], v[104:107], v[186:189], v[60:63]
	v_mfma_f32_16x16x32_f16 v[56:59], v[112:115], v[186:189], v[56:59]
	v_mfma_f32_16x16x32_f16 v[44:47], v[104:107], v[194:197], v[44:47]
	v_mfma_f32_16x16x32_f16 v[40:43], v[112:115], v[194:197], v[40:43]
	v_mfma_f32_16x16x32_f16 v[28:31], v[104:107], v[206:209], v[28:31]
	v_mfma_f32_16x16x32_f16 v[24:27], v[112:115], v[206:209], v[24:27]
	v_mfma_f32_16x16x32_f16 v[12:15], v[104:107], v[214:217], v[12:15]
	v_mfma_f32_16x16x32_f16 v[8:11], v[112:115], v[214:217], v[8:11]
	v_mfma_f32_16x16x32_f16 v[60:63], v[108:111], v[190:193], v[60:63]
	v_mfma_f32_16x16x32_f16 v[56:59], v[116:119], v[190:193], v[56:59]
	v_mfma_f32_16x16x32_f16 v[44:47], v[108:111], v[198:201], v[44:47]
	v_mfma_f32_16x16x32_f16 v[40:43], v[116:119], v[198:201], v[40:43]
	v_mfma_f32_16x16x32_f16 v[28:31], v[108:111], v[210:213], v[28:31]
	v_mfma_f32_16x16x32_f16 v[24:27], v[116:119], v[210:213], v[24:27]
	v_mfma_f32_16x16x32_f16 v[12:15], v[108:111], v[218:221], v[12:15]
	v_mfma_f32_16x16x32_f16 v[8:11], v[116:119], v[218:221], v[8:11]
	v_mfma_f32_16x16x32_f16 v[52:55], v[160:163], v[186:189], v[52:55]
	v_mfma_f32_16x16x32_f16 v[48:51], v[178:181], v[186:189], v[48:51]
	v_mfma_f32_16x16x32_f16 v[36:39], v[160:163], v[194:197], v[36:39]
	v_mfma_f32_16x16x32_f16 v[32:35], v[178:181], v[194:197], v[32:35]
	v_mfma_f32_16x16x32_f16 v[20:23], v[160:163], v[206:209], v[20:23]
	v_mfma_f32_16x16x32_f16 v[16:19], v[178:181], v[206:209], v[16:19]
	v_mfma_f32_16x16x32_f16 v[4:7], v[160:163], v[214:217], v[4:7]
	v_mfma_f32_16x16x32_f16 v[0:3], v[178:181], v[214:217], v[0:3]
	v_mfma_f32_16x16x32_f16 v[52:55], v[164:167], v[190:193], v[52:55]
	v_mfma_f32_16x16x32_f16 v[48:51], v[182:185], v[190:193], v[48:51]
	v_mfma_f32_16x16x32_f16 v[36:39], v[164:167], v[198:201], v[36:39]
	v_mfma_f32_16x16x32_f16 v[32:35], v[182:185], v[198:201], v[32:35]
	v_mfma_f32_16x16x32_f16 v[20:23], v[164:167], v[210:213], v[20:23]
	v_mfma_f32_16x16x32_f16 v[16:19], v[182:185], v[210:213], v[16:19]
	v_mfma_f32_16x16x32_f16 v[4:7], v[164:167], v[218:221], v[4:7]
	v_mfma_f32_16x16x32_f16 v[0:3], v[182:185], v[218:221], v[0:3]
	s_barrier
	s_add_i32 s69, s69, 2
	s_add_u32 s24, s24, 0x100
	s_addc_u32 s25, s25, 0
	s_add_u32 s67, s67, 0x100
	s_addc_u32 s68, s68, 0
	s_cmp_gt_u32 s69, 13
	s_cbranch_scc0 .LBB0_220
	s_and_b64 vcc, exec, s[12:13]
	s_cbranch_vccz .LBB0_223
	s_barrier

.LBB0_261:
	s_cmp_gt_i32 s91, 3
	s_cselect_b64 s[2:3], -1, 0
	s_and_b64 s[0:1], s[0:1], s[2:3]
	s_andn2_b64 vcc, exec, s[0:1]
	s_cbranch_vccnz .LBB0_315
	s_waitcnt vmcnt(0)
	s_waitcnt lgkmcnt(0)
	s_setprio 0
	s_barrier
	s_and_saveexec_b64 s[0:1], s[92:93]
	s_cbranch_execz .LBB0_314
	s_add_i32 s4, 0, 0x27ff0
	v_mov_b32_e32 v0, s4
	s_waitcnt vmcnt(0) expcnt(0) lgkmcnt(0)
	ds_read_b32 v2, v0
	s_add_i32 s4, 0, 0x27ff4
	v_mov_b32_e32 v0, s4
	ds_read_b32 v0, v0
	s_waitcnt lgkmcnt(1)
	v_cmp_ne_u32_e32 vcc, 0, v2
	s_cbranch_vccnz .LBB0_278
	s_add_u32 s4, s30, 0x38200
	s_addc_u32 s5, s31, 0
	s_add_u32 s6, s30, 0x38400
	s_addc_u32 s7, s31, 0
	s_add_u32 s10, s30, 0x38500
	s_addc_u32 s11, s31, 0
	s_add_u32 s12, s30, 0x38600
	s_addc_u32 s13, s31, 0
	s_add_u32 s14, s30, 0x38700
	s_addc_u32 s15, s31, 0
	s_add_u32 s16, s30, 0x38800
	s_addc_u32 s17, s31, 0
	s_add_u32 s18, s30, 0x38900
	s_addc_u32 s19, s31, 0
	s_add_u32 s20, s30, 0x38a00
	s_addc_u32 s21, s31, 0
	s_add_u32 s22, s30, 0x38b00
	s_addc_u32 s23, s31, 0
	s_add_u32 s24, s30, 0x38c00
	s_addc_u32 s25, s31, 0
	s_add_u32 s26, s30, 0x38d00
	s_addc_u32 s27, s31, 0
	s_add_u32 s34, s30, 0x38e00
	s_addc_u32 s35, s31, 0
	s_add_u32 s40, s30, 0x38f00
	s_addc_u32 s41, s31, 0
	s_add_u32 s44, s30, 0x39000
	s_addc_u32 s45, s31, 0
	s_add_u32 s46, s30, 0x39100
	s_addc_u32 s47, s31, 0
	s_add_u32 s48, s30, 0x39200
	s_addc_u32 s49, s31, 0
	s_mul_i32 s33, s89, s9
	s_add_u32 s54, s30, 0x39300
	s_mul_i32 s33, s33, s88
	s_addc_u32 s55, s31, 0
	s_mov_b32 s62, 1
	v_mov_b32_e32 v16, 0
	s_branch .LBB0_266

.LBB0_324:
.LBB0_325:
	v_ashrrev_i32_e32 v1, 31, v8
	v_lshrrev_b32_e32 v1, 26, v1
	v_add_u32_e32 v1, v8, v1
	v_ashrrev_i32_e32 v9, 6, v1
	v_bfe_i32 v1, v8, 27, 1
	v_lshlrev_b32_e32 v0, 4, v8
	v_lshrrev_b32_e32 v1, 22, v1
	v_add_u32_e32 v1, v0, v1
	v_and_b32_e32 v1, 0xfffffc00, v1
	v_sub_u32_e32 v1, v0, v1
	v_lshrrev_b32_e32 v2, 4, v1
	v_bitop3_b32 v1, v2, v1, 32 bitop3:0x6c
	v_ashrrev_i32_e32 v3, 31, v1
	v_lshrrev_b32_e32 v3, 26, v3
	v_lshlrev_b32_e32 v2, 3, v9
	v_add_u32_e32 v3, v1, v3
	v_and_b32_e32 v2, -16, v2
	v_ashrrev_i32_e32 v11, 6, v3
	v_and_b32_e32 v3, 0xc0, v3
	v_add_u32_e32 v2, v11, v2
	v_lshlrev_b32_e32 v4, 5, v9
	v_sub_u32_e32 v1, v1, v3
	v_mov_b32_e32 v3, 1
	v_and_b32_e32 v10, 32, v4
	v_ashrrev_i16_sdwa v1, v3, sext(v1) dst_sel:DWORD dst_unused:UNUSED_PAD src0_sel:DWORD src1_sel:BYTE_0
	v_lshlrev_b32_e32 v4, 1, v2
	v_lshrrev_b32_e32 v5, 2, v2
	v_and_b32_e32 v6, 3, v11
	s_mov_b32 s2, 0xffffe0
	v_bfe_i32 v12, v1, 0, 16
	v_and_b32_e32 v4, 24, v4
	v_and_b32_e32 v5, 4, v5
	v_and_or_b32 v6, v2, s2, v6
	s_movk_i32 s1, 0xb00
	v_add_u32_e32 v1, v10, v12
	v_or3_b32 v4, v6, v5, v4
	v_mul_lo_u32 v2, v2, s1
	v_add_lshl_u32 v160, v1, v2, 1
	v_mul_u32_u24_e32 v2, 0xb00, v4
	v_add_u32_e32 v0, 0x2000, v0
	v_add_lshl_u32 v162, v2, v1, 1
	v_ashrrev_i32_e32 v1, 31, v0
	v_lshrrev_b32_e32 v1, 22, v1
	v_add_u32_e32 v1, v0, v1
	v_ashrrev_i32_e32 v13, 10, v1
	v_mul_i32_i24_e32 v1, 0x400, v13
	v_sub_u32_e32 v0, v0, v1
	v_lshrrev_b32_e32 v1, 4, v0
	v_bitop3_b32 v0, v1, v0, 32 bitop3:0x6c
	v_ashrrev_i32_e32 v2, 31, v0
	v_lshrrev_b32_e32 v2, 26, v2
	v_lshlrev_b32_e32 v1, 3, v13
	v_add_u32_e32 v2, v0, v2
	v_and_b32_e32 v1, -16, v1
	v_ashrrev_i32_e32 v14, 6, v2
	v_lshlrev_b32_e32 v4, 5, v13
	s_add_u32 s10, s30, 0x2e00000
	v_add_u32_e32 v1, v14, v1
	v_and_b32_e32 v15, 32, v4
	v_and_b32_e32 v4, 3, v14
	s_addc_u32 s11, s31, 0
	v_and_b32_e32 v2, 0xc0, v2
	v_and_or_b32 v4, v1, s2, v4
	s_ashr_i32 s2, s4, 6
	s_ashr_i32 s0, s4, 8
	v_sub_u32_e32 v0, v0, v2
	s_lshl_b32 s33, s2, 10
	s_mul_i32 s13, s64, 0x160000
	v_ashrrev_i16_sdwa v0, v3, sext(v0) dst_sel:DWORD dst_unused:UNUSED_PAD src0_sel:DWORD src1_sel:BYTE_0
	v_lshlrev_b32_e32 v2, 1, v1
	v_lshrrev_b32_e32 v3, 2, v1
	s_mul_hi_i32 s12, s64, 0x160000
	s_add_u32 s24, s10, s13
	v_bfe_i32 v16, v0, 0, 16
	v_and_b32_e32 v2, 24, v2
	v_and_b32_e32 v3, 4, v3
	s_addc_u32 s25, s11, s12
	s_add_i32 s40, s33, 0
	v_add_u32_e32 v0, v15, v16
	v_or3_b32 v2, v4, v3, v2
	v_mul_lo_u32 v1, v1, s1
	s_add_i32 m0, s40, 0x10000
	v_add_lshl_u32 v164, v0, v1, 1
	v_mul_u32_u24_e32 v1, 0xb00, v2
	global_load_lds_dwordx4 v162, s[24:25]
	s_add_i32 m0, s40, 0x12000
	v_add_lshl_u32 v166, v1, v0, 1
	s_add_u32 s12, s24, 0xb0000
	global_load_lds_dwordx4 v166, s[24:25]
	s_addc_u32 s13, s25, 0
	s_add_i32 m0, s40, 0x14000
	s_mul_i32 s5, s63, 0x160000
	global_load_lds_dwordx4 v162, s[12:13]
	s_add_i32 m0, s40, 0x16000
	s_mul_hi_i32 s3, s63, 0x160000
	s_add_u32 s22, s36, s5
	s_addc_u32 s23, s37, s3
	s_add_i32 s41, s40, 0x2000
	global_load_lds_dwordx4 v166, s[12:13]
	s_mov_b32 m0, s40
	s_add_u32 s12, s22, 0xb0000
	global_load_lds_dwordx4 v160, s[22:23]
	s_mov_b32 m0, s41
	s_addc_u32 s13, s23, 0
	s_add_i32 s44, s40, 0x4000
	global_load_lds_dwordx4 v164, s[22:23]
	s_mov_b32 m0, s44
	s_add_i32 s45, s40, 0x6000
	global_load_lds_dwordx4 v160, s[12:13]
	s_mov_b32 m0, s45
	v_mov_b32_e32 v163, 0
	global_load_lds_dwordx4 v164, s[12:13]
	v_mov_b32_e32 v167, v163
	v_mov_b32_e32 v161, v163
	v_mov_b32_e32 v165, v163
	s_cmp_eq_u32 s0, 1
	s_mov_b32 s46, 0
	v_lshl_add_u64 v[6:7], s[24:25], 0, v[162:163]
	v_lshl_add_u64 v[4:5], s[24:25], 0, v[166:167]
	v_lshl_add_u64 v[0:1], s[22:23], 0, v[160:161]
	s_cselect_b64 s[14:15], -1, 0
	s_cmp_lg_u32 s0, 1
	v_lshl_add_u64 v[2:3], s[22:23], 0, v[164:165]
	s_cbranch_scc1 .LBB0_327
	s_barrier
	s_setprio 1

.LBB0_341:
	ds_read_b128 v[80:83], v208
	ds_read_b128 v[84:87], v208 offset:1024
	ds_read_b128 v[92:95], v208 offset:2048
	ds_read_b128 v[96:99], v208 offset:3072
	ds_read_b128 v[144:147], v209
	ds_read_b128 v[148:151], v209 offset:1024
	ds_read_b128 v[152:155], v209 offset:2048
	ds_read_b128 v[156:159], v209 offset:3072
	s_add_u32 s24, s22, 0x100
	s_addc_u32 s25, s23, 0
	s_cmp_eq_u32 s67, 40
	s_cselect_b32 s35, s1, s25
	s_cselect_b32 s34, s0, s24
	s_cselect_b32 s27, s21, s66
	s_cselect_b32 s26, s20, s65
	v_lshl_add_u64 v[202:203], s[22:23], 0, v[168:169]
	s_add_i32 m0, s40, 0xc000
	ds_read_b128 v[178:181], v210
	ds_read_b128 v[182:185], v210 offset:1024
	ds_read_b128 v[186:189], v210 offset:2048
	ds_read_b128 v[190:193], v210 offset:3072
	ds_read_b128 v[194:197], v210 offset:4096
	ds_read_b128 v[198:201], v210 offset:5120
	ds_read_b128 v[212:215], v210 offset:6144
	ds_read_b128 v[216:219], v210 offset:7168
	global_load_lds_dwordx4 v[202:203], off
	v_lshl_add_u64 v[202:203], s[22:23], 0, v[170:171]
	s_add_i32 m0, s40, 0xe000
	s_nop 0
	global_load_lds_dwordx4 v[202:203], off
	s_waitcnt vmcnt(8)
	s_waitcnt lgkmcnt(0)
	s_barrier
	s_waitcnt lgkmcnt(0)
	v_mfma_f32_16x16x32_f16 v[140:143], v[80:83], v[178:181], v[140:143]
	v_mfma_f32_16x16x32_f16 v[136:139], v[92:95], v[178:181], v[136:139]
	v_mfma_f32_16x16x32_f16 v[124:127], v[80:83], v[186:189], v[124:127]
	v_mfma_f32_16x16x32_f16 v[120:123], v[92:95], v[186:189], v[120:123]
	v_mfma_f32_16x16x32_f16 v[108:111], v[80:83], v[194:197], v[108:111]
	v_mfma_f32_16x16x32_f16 v[104:107], v[92:95], v[194:197], v[104:107]
	v_mfma_f32_16x16x32_f16 v[76:79], v[80:83], v[212:215], v[76:79]
	v_mfma_f32_16x16x32_f16 v[72:75], v[92:95], v[212:215], v[72:75]
	v_mfma_f32_16x16x32_f16 v[140:143], v[84:87], v[182:185], v[140:143]
	v_mfma_f32_16x16x32_f16 v[136:139], v[96:99], v[182:185], v[136:139]
	v_mfma_f32_16x16x32_f16 v[124:127], v[84:87], v[190:193], v[124:127]
	v_mfma_f32_16x16x32_f16 v[120:123], v[96:99], v[190:193], v[120:123]
	v_mfma_f32_16x16x32_f16 v[108:111], v[84:87], v[198:201], v[108:111]
	v_mfma_f32_16x16x32_f16 v[104:107], v[96:99], v[198:201], v[104:107]
	v_mfma_f32_16x16x32_f16 v[76:79], v[84:87], v[216:219], v[76:79]
	v_mfma_f32_16x16x32_f16 v[72:75], v[96:99], v[216:219], v[72:75]
	v_mfma_f32_16x16x32_f16 v[132:135], v[144:147], v[178:181], v[132:135]
	v_mfma_f32_16x16x32_f16 v[128:131], v[152:155], v[178:181], v[128:131]
	v_mfma_f32_16x16x32_f16 v[116:119], v[144:147], v[186:189], v[116:119]
	v_mfma_f32_16x16x32_f16 v[112:115], v[152:155], v[186:189], v[112:115]
	v_mfma_f32_16x16x32_f16 v[100:103], v[144:147], v[194:197], v[100:103]
	v_mfma_f32_16x16x32_f16 v[88:91], v[152:155], v[194:197], v[88:91]
	v_mfma_f32_16x16x32_f16 v[68:71], v[144:147], v[212:215], v[68:71]
	v_mfma_f32_16x16x32_f16 v[64:67], v[152:155], v[212:215], v[64:67]
	v_mfma_f32_16x16x32_f16 v[132:135], v[148:151], v[182:185], v[132:135]
	v_mfma_f32_16x16x32_f16 v[128:131], v[156:159], v[182:185], v[128:131]
	v_mfma_f32_16x16x32_f16 v[116:119], v[148:151], v[190:193], v[116:119]
	v_mfma_f32_16x16x32_f16 v[112:115], v[156:159], v[190:193], v[112:115]
	v_mfma_f32_16x16x32_f16 v[100:103], v[148:151], v[198:201], v[100:103]
	v_mfma_f32_16x16x32_f16 v[88:91], v[156:159], v[198:201], v[88:91]
	v_mfma_f32_16x16x32_f16 v[68:71], v[148:151], v[216:219], v[68:71]
	v_mfma_f32_16x16x32_f16 v[64:67], v[156:159], v[216:219], v[64:67]
	s_barrier
	s_add_i32 s22, s59, s33
	v_lshl_add_u64 v[202:203], s[26:27], 0, v[162:163]
	s_mov_b32 m0, s22
	ds_read_b128 v[178:181], v210 offset:16384
	ds_read_b128 v[182:185], v210 offset:17408
	ds_read_b128 v[186:189], v210 offset:18432
	ds_read_b128 v[190:193], v210 offset:19456
	ds_read_b128 v[194:197], v210 offset:20480
	ds_read_b128 v[198:201], v210 offset:21504
	ds_read_b128 v[212:215], v210 offset:22528
	ds_read_b128 v[216:219], v210 offset:23552
	global_load_lds_dwordx4 v[202:203], off
	s_add_i32 m0, s22, 0x2000
	s_add_u32 s22, s26, 0xb0000
	v_lshl_add_u64 v[220:221], s[26:27], 0, v[166:167]
	s_addc_u32 s23, s27, 0
	s_add_i32 s68, s60, s33
	global_load_lds_dwordx4 v[220:221], off
	v_lshl_add_u64 v[222:223], s[22:23], 0, v[162:163]
	s_mov_b32 m0, s68
	v_lshl_add_u64 v[224:225], s[34:35], 0, v[164:165]
	global_load_lds_dwordx4 v[222:223], off
	v_lshl_add_u64 v[222:223], s[22:23], 0, v[166:167]
	s_add_i32 m0, s68, 0x2000
	s_nop 0
	global_load_lds_dwordx4 v[222:223], off
	v_lshl_add_u64 v[222:223], s[34:35], 0, v[160:161]
	s_mov_b32 m0, s40
	s_nop 0
	global_load_lds_dwordx4 v[222:223], off
	s_mov_b32 m0, s41
	s_nop 0
	global_load_lds_dwordx4 v[224:225], off
	s_waitcnt vmcnt(8)
	s_waitcnt lgkmcnt(0)
	s_barrier
	s_waitcnt lgkmcnt(0)
	v_mfma_f32_16x16x32_f16 v[60:63], v[80:83], v[178:181], v[60:63]
	v_mfma_f32_16x16x32_f16 v[56:59], v[92:95], v[178:181], v[56:59]
	v_mfma_f32_16x16x32_f16 v[44:47], v[80:83], v[186:189], v[44:47]
	v_mfma_f32_16x16x32_f16 v[40:43], v[92:95], v[186:189], v[40:43]
	v_mfma_f32_16x16x32_f16 v[28:31], v[80:83], v[194:197], v[28:31]
	v_mfma_f32_16x16x32_f16 v[24:27], v[92:95], v[194:197], v[24:27]
	v_mfma_f32_16x16x32_f16 v[12:15], v[80:83], v[212:215], v[12:15]
	v_mfma_f32_16x16x32_f16 v[8:11], v[92:95], v[212:215], v[8:11]
	v_mfma_f32_16x16x32_f16 v[60:63], v[84:87], v[182:185], v[60:63]
	v_mfma_f32_16x16x32_f16 v[56:59], v[96:99], v[182:185], v[56:59]
	v_mfma_f32_16x16x32_f16 v[44:47], v[84:87], v[190:193], v[44:47]
	v_mfma_f32_16x16x32_f16 v[40:43], v[96:99], v[190:193], v[40:43]
	v_mfma_f32_16x16x32_f16 v[28:31], v[84:87], v[198:201], v[28:31]
	v_mfma_f32_16x16x32_f16 v[24:27], v[96:99], v[198:201], v[24:27]
	v_mfma_f32_16x16x32_f16 v[12:15], v[84:87], v[216:219], v[12:15]
	v_mfma_f32_16x16x32_f16 v[8:11], v[96:99], v[216:219], v[8:11]
	v_mfma_f32_16x16x32_f16 v[52:55], v[144:147], v[178:181], v[52:55]
	v_mfma_f32_16x16x32_f16 v[48:51], v[152:155], v[178:181], v[48:51]
	v_mfma_f32_16x16x32_f16 v[36:39], v[144:147], v[186:189], v[36:39]
	v_mfma_f32_16x16x32_f16 v[32:35], v[152:155], v[186:189], v[32:35]
	v_mfma_f32_16x16x32_f16 v[20:23], v[144:147], v[194:197], v[20:23]
	v_mfma_f32_16x16x32_f16 v[16:19], v[152:155], v[194:197], v[16:19]
	v_mfma_f32_16x16x32_f16 v[4:7], v[144:147], v[212:215], v[4:7]
	v_mfma_f32_16x16x32_f16 v[0:3], v[152:155], v[212:215], v[0:3]
	v_mfma_f32_16x16x32_f16 v[52:55], v[148:151], v[182:185], v[52:55]
	v_mfma_f32_16x16x32_f16 v[48:51], v[156:159], v[182:185], v[48:51]
	v_mfma_f32_16x16x32_f16 v[36:39], v[148:151], v[190:193], v[36:39]
	v_mfma_f32_16x16x32_f16 v[32:35], v[156:159], v[190:193], v[32:35]
	v_mfma_f32_16x16x32_f16 v[20:23], v[148:151], v[198:201], v[20:23]
	v_mfma_f32_16x16x32_f16 v[16:19], v[156:159], v[198:201], v[16:19]
	v_mfma_f32_16x16x32_f16 v[4:7], v[148:151], v[216:219], v[4:7]
	v_mfma_f32_16x16x32_f16 v[0:3], v[156:159], v[216:219], v[0:3]
	s_barrier
	s_add_i32 s68, 0, 0x18000
	s_add_i32 s69, 0, 0x1c000
	v_add_u32_e32 v96, s68, v206
	v_add_u32_e32 v156, s69, v206
	ds_read_b128 v[80:83], v96
	ds_read_b128 v[84:87], v96 offset:1024
	ds_read_b128 v[92:95], v96 offset:2048
	ds_read_b128 v[96:99], v96 offset:3072
	ds_read_b128 v[144:147], v156
	ds_read_b128 v[148:151], v156 offset:1024
	ds_read_b128 v[152:155], v156 offset:2048
	ds_read_b128 v[156:159], v156 offset:3072
	s_add_u32 s22, s34, 0xb0000
	s_addc_u32 s23, s35, 0
	s_mov_b32 m0, s44
	v_lshl_add_u64 v[226:227], s[22:23], 0, v[160:161]
	ds_read_b128 v[178:181], v210 offset:32768
	ds_read_b128 v[182:185], v210 offset:33792
	ds_read_b128 v[186:189], v210 offset:34816
	ds_read_b128 v[190:193], v210 offset:35840
	ds_read_b128 v[194:197], v210 offset:36864
	ds_read_b128 v[198:201], v210 offset:37888
	ds_read_b128 v[212:215], v210 offset:38912
	ds_read_b128 v[216:219], v210 offset:39936
	global_load_lds_dwordx4 v[226:227], off
	v_lshl_add_u64 v[226:227], s[22:23], 0, v[164:165]
	s_mov_b32 m0, s45
	s_nop 0
	global_load_lds_dwordx4 v[226:227], off
	s_waitcnt vmcnt(8)
	s_waitcnt lgkmcnt(0)
	s_barrier
	s_waitcnt lgkmcnt(0)
	v_mfma_f32_16x16x32_f16 v[140:143], v[80:83], v[178:181], v[140:143]
	v_mfma_f32_16x16x32_f16 v[136:139], v[92:95], v[178:181], v[136:139]
	v_mfma_f32_16x16x32_f16 v[124:127], v[80:83], v[186:189], v[124:127]
	v_mfma_f32_16x16x32_f16 v[120:123], v[92:95], v[186:189], v[120:123]
	v_mfma_f32_16x16x32_f16 v[108:111], v[80:83], v[194:197], v[108:111]
	v_mfma_f32_16x16x32_f16 v[104:107], v[92:95], v[194:197], v[104:107]
	v_mfma_f32_16x16x32_f16 v[76:79], v[80:83], v[212:215], v[76:79]
	v_mfma_f32_16x16x32_f16 v[72:75], v[92:95], v[212:215], v[72:75]
	v_mfma_f32_16x16x32_f16 v[140:143], v[84:87], v[182:185], v[140:143]
	v_mfma_f32_16x16x32_f16 v[136:139], v[96:99], v[182:185], v[136:139]
	v_mfma_f32_16x16x32_f16 v[124:127], v[84:87], v[190:193], v[124:127]
	v_mfma_f32_16x16x32_f16 v[120:123], v[96:99], v[190:193], v[120:123]
	v_mfma_f32_16x16x32_f16 v[108:111], v[84:87], v[198:201], v[108:111]
	v_mfma_f32_16x16x32_f16 v[104:107], v[96:99], v[198:201], v[104:107]
	v_mfma_f32_16x16x32_f16 v[76:79], v[84:87], v[216:219], v[76:79]
	v_mfma_f32_16x16x32_f16 v[72:75], v[96:99], v[216:219], v[72:75]
	v_mfma_f32_16x16x32_f16 v[132:135], v[144:147], v[178:181], v[132:135]
	v_mfma_f32_16x16x32_f16 v[128:131], v[152:155], v[178:181], v[128:131]
	v_mfma_f32_16x16x32_f16 v[116:119], v[144:147], v[186:189], v[116:119]
	v_mfma_f32_16x16x32_f16 v[112:115], v[152:155], v[186:189], v[112:115]
	v_mfma_f32_16x16x32_f16 v[100:103], v[144:147], v[194:197], v[100:103]
	v_mfma_f32_16x16x32_f16 v[88:91], v[152:155], v[194:197], v[88:91]
	v_mfma_f32_16x16x32_f16 v[68:71], v[144:147], v[212:215], v[68:71]
	v_mfma_f32_16x16x32_f16 v[64:67], v[152:155], v[212:215], v[64:67]
	v_mfma_f32_16x16x32_f16 v[132:135], v[148:151], v[182:185], v[132:135]
	v_mfma_f32_16x16x32_f16 v[128:131], v[156:159], v[182:185], v[128:131]
	v_mfma_f32_16x16x32_f16 v[116:119], v[148:151], v[190:193], v[116:119]
	v_mfma_f32_16x16x32_f16 v[112:115], v[156:159], v[190:193], v[112:115]
	v_mfma_f32_16x16x32_f16 v[100:103], v[148:151], v[198:201], v[100:103]
	v_mfma_f32_16x16x32_f16 v[88:91], v[156:159], v[198:201], v[88:91]
	v_mfma_f32_16x16x32_f16 v[68:71], v[148:151], v[216:219], v[68:71]
	v_mfma_f32_16x16x32_f16 v[64:67], v[156:159], v[216:219], v[64:67]
	s_barrier
	s_add_i32 s22, s68, s33
	v_lshl_add_u64 v[202:203], v[202:203], 0, s[16:17]
	s_mov_b32 m0, s22
	ds_read_b128 v[178:181], v210 offset:49152
	ds_read_b128 v[182:185], v210 offset:50176
	ds_read_b128 v[186:189], v210 offset:51200
	ds_read_b128 v[190:193], v210 offset:52224
	ds_read_b128 v[194:197], v210 offset:53248
	ds_read_b128 v[198:201], v210 offset:54272
	ds_read_b128 v[212:215], v210 offset:55296
	ds_read_b128 v[216:219], v210 offset:56320
	global_load_lds_dwordx4 v[202:203], off
	s_add_i32 m0, s22, 0x2000
	s_add_u32 s22, s26, 0xb0080
	v_lshl_add_u64 v[202:203], v[220:221], 0, s[16:17]
	s_addc_u32 s23, s27, 0
	s_add_i32 s26, s69, s33
	global_load_lds_dwordx4 v[202:203], off
	v_lshl_add_u64 v[202:203], s[22:23], 0, v[162:163]
	s_mov_b32 m0, s26
	s_nop 0
	global_load_lds_dwordx4 v[202:203], off
	v_lshl_add_u64 v[202:203], s[22:23], 0, v[166:167]
	s_add_i32 m0, s26, 0x2000
	s_nop 0
	global_load_lds_dwordx4 v[202:203], off
	v_lshl_add_u64 v[202:203], v[222:223], 0, s[16:17]
	s_mov_b32 m0, s55
	s_nop 0
	global_load_lds_dwordx4 v[202:203], off
	v_lshl_add_u64 v[202:203], v[224:225], 0, s[16:17]
	s_mov_b32 m0, s56
	s_nop 0
	global_load_lds_dwordx4 v[202:203], off
	s_waitcnt vmcnt(8)
	s_waitcnt lgkmcnt(0)
	s_barrier
	s_waitcnt lgkmcnt(0)
	v_mfma_f32_16x16x32_f16 v[60:63], v[80:83], v[178:181], v[60:63]
	v_mfma_f32_16x16x32_f16 v[56:59], v[92:95], v[178:181], v[56:59]
	v_mfma_f32_16x16x32_f16 v[44:47], v[80:83], v[186:189], v[44:47]
	v_mfma_f32_16x16x32_f16 v[40:43], v[92:95], v[186:189], v[40:43]
	v_mfma_f32_16x16x32_f16 v[28:31], v[80:83], v[194:197], v[28:31]
	v_mfma_f32_16x16x32_f16 v[24:27], v[92:95], v[194:197], v[24:27]
	v_mfma_f32_16x16x32_f16 v[12:15], v[80:83], v[212:215], v[12:15]
	v_mfma_f32_16x16x32_f16 v[8:11], v[92:95], v[212:215], v[8:11]
	v_mfma_f32_16x16x32_f16 v[60:63], v[84:87], v[182:185], v[60:63]
	v_mfma_f32_16x16x32_f16 v[56:59], v[96:99], v[182:185], v[56:59]
	v_mfma_f32_16x16x32_f16 v[44:47], v[84:87], v[190:193], v[44:47]
	v_mfma_f32_16x16x32_f16 v[40:43], v[96:99], v[190:193], v[40:43]
	v_mfma_f32_16x16x32_f16 v[28:31], v[84:87], v[198:201], v[28:31]
	v_mfma_f32_16x16x32_f16 v[24:27], v[96:99], v[198:201], v[24:27]
	v_mfma_f32_16x16x32_f16 v[12:15], v[84:87], v[216:219], v[12:15]
	v_mfma_f32_16x16x32_f16 v[8:11], v[96:99], v[216:219], v[8:11]
	v_mfma_f32_16x16x32_f16 v[52:55], v[144:147], v[178:181], v[52:55]
	v_mfma_f32_16x16x32_f16 v[48:51], v[152:155], v[178:181], v[48:51]
	v_mfma_f32_16x16x32_f16 v[36:39], v[144:147], v[186:189], v[36:39]
	v_mfma_f32_16x16x32_f16 v[32:35], v[152:155], v[186:189], v[32:35]
	v_mfma_f32_16x16x32_f16 v[20:23], v[144:147], v[194:197], v[20:23]
	v_mfma_f32_16x16x32_f16 v[16:19], v[152:155], v[194:197], v[16:19]
	v_mfma_f32_16x16x32_f16 v[4:7], v[144:147], v[212:215], v[4:7]
	v_mfma_f32_16x16x32_f16 v[0:3], v[152:155], v[212:215], v[0:3]
	v_mfma_f32_16x16x32_f16 v[52:55], v[148:151], v[182:185], v[52:55]
	v_mfma_f32_16x16x32_f16 v[48:51], v[156:159], v[182:185], v[48:51]
	v_mfma_f32_16x16x32_f16 v[36:39], v[148:151], v[190:193], v[36:39]
	v_mfma_f32_16x16x32_f16 v[32:35], v[156:159], v[190:193], v[32:35]
	v_mfma_f32_16x16x32_f16 v[20:23], v[148:151], v[198:201], v[20:23]
	v_mfma_f32_16x16x32_f16 v[16:19], v[156:159], v[198:201], v[16:19]
	v_mfma_f32_16x16x32_f16 v[4:7], v[148:151], v[216:219], v[4:7]
	v_mfma_f32_16x16x32_f16 v[0:3], v[156:159], v[216:219], v[0:3]
	s_barrier
	s_add_i32 s67, s67, 2
	s_add_u32 s65, s65, 0x100
	s_addc_u32 s66, s66, 0
	s_cmp_gt_u32 s67, 41
	s_mov_b64 s[22:23], s[24:25]
	s_cbranch_scc0 .LBB0_341
	s_and_b64 vcc, exec, s[18:19]
	s_cbranch_vccz .LBB0_344
	s_barrier

.LBB0_392:
	s_cmp_lt_i32 s91, 5
	s_cselect_b64 s[0:1], -1, 0
	s_xor_b64 s[2:3], s[6:7], -1
	s_or_b64 s[0:1], s[2:3], s[0:1]
	s_and_b64 vcc, exec, s[0:1]
	s_cbranch_vccnz .LBB0_446
	s_waitcnt vmcnt(0)
	s_waitcnt lgkmcnt(0)
	s_setprio 0
	s_barrier
	s_and_saveexec_b64 s[0:1], s[92:93]
	s_cbranch_execz .LBB0_445
	s_add_i32 s2, 0, 0x27ff0
	v_mov_b32_e32 v0, s2
	s_waitcnt vmcnt(0) expcnt(0) lgkmcnt(0)
	ds_read_b32 v2, v0
	s_add_i32 s2, 0, 0x27ff4
	v_mov_b32_e32 v0, s2
	ds_read_b32 v0, v0
	s_waitcnt lgkmcnt(1)
	v_cmp_ne_u32_e32 vcc, 0, v2
	s_cbranch_vccnz .LBB0_409
	s_add_u32 s2, s30, 0x38200
	s_addc_u32 s3, s31, 0
	s_add_u32 s4, s30, 0x38400
	s_addc_u32 s5, s31, 0
	s_add_u32 s6, s30, 0x38500
	s_addc_u32 s7, s31, 0
	s_add_u32 s10, s30, 0x38600
	s_addc_u32 s11, s31, 0
	s_add_u32 s12, s30, 0x38700
	s_addc_u32 s13, s31, 0
	s_add_u32 s14, s30, 0x38800
	s_addc_u32 s15, s31, 0
	s_add_u32 s16, s30, 0x38900
	s_addc_u32 s17, s31, 0
	s_add_u32 s18, s30, 0x38a00
	s_addc_u32 s19, s31, 0
	s_add_u32 s20, s30, 0x38b00
	s_addc_u32 s21, s31, 0
	s_add_u32 s22, s30, 0x38c00
	s_addc_u32 s23, s31, 0
	s_add_u32 s24, s30, 0x38d00
	s_addc_u32 s25, s31, 0
	s_add_u32 s26, s30, 0x38e00
	s_addc_u32 s27, s31, 0
	s_add_u32 s34, s30, 0x38f00
	s_addc_u32 s35, s31, 0
	s_add_u32 s40, s30, 0x39000
	s_addc_u32 s41, s31, 0
	s_add_u32 s44, s30, 0x39100
	s_addc_u32 s45, s31, 0
	s_add_u32 s46, s30, 0x39200
	s_addc_u32 s47, s31, 0
	s_mul_i32 s33, s89, s9
	s_add_u32 s48, s30, 0x39300
	s_mul_i32 s33, s33, s88
	s_addc_u32 s49, s31, 0
	s_mov_b32 s60, 1
	v_mov_b32_e32 v16, 0
	s_branch .LBB0_397

.LBB0_452:
	v_ashrrev_i32_e32 v1, 31, v8
	v_lshrrev_b32_e32 v1, 26, v1
	v_add_u32_e32 v1, v8, v1
	v_ashrrev_i32_e32 v9, 6, v1
	v_bfe_i32 v1, v8, 27, 1
	v_lshlrev_b32_e32 v0, 4, v8
	v_lshrrev_b32_e32 v1, 22, v1
	v_add_u32_e32 v1, v0, v1
	v_and_b32_e32 v1, 0xfffffc00, v1
	v_sub_u32_e32 v1, v0, v1
	v_lshrrev_b32_e32 v2, 4, v1
	v_bitop3_b32 v1, v2, v1, 32 bitop3:0x6c
	v_ashrrev_i32_e32 v3, 31, v1
	v_lshrrev_b32_e32 v3, 26, v3
	v_add_u32_e32 v3, v1, v3
	v_lshlrev_b32_e32 v2, 3, v9
	v_ashrrev_i32_e32 v10, 6, v3
	v_and_b32_e32 v3, 0xc0, v3
	v_and_b32_e32 v2, -16, v2
	v_sub_u32_e32 v1, v1, v3
	v_mov_b32_e32 v3, 1
	v_add_u32_e32 v2, v10, v2
	v_ashrrev_i16_sdwa v1, v3, sext(v1) dst_sel:DWORD dst_unused:UNUSED_PAD src0_sel:DWORD src1_sel:BYTE_0
	v_lshlrev_b32_e32 v4, 5, v9
	v_bfe_i32 v11, v1, 0, 16
	v_lshlrev_b32_e32 v1, 1, v2
	v_lshrrev_b32_e32 v5, 2, v2
	v_and_b32_e32 v6, 3, v10
	s_mov_b32 s1, 0x1fffe0
	v_and_b32_e32 v4, 32, v4
	v_and_b32_e32 v1, 24, v1
	v_and_b32_e32 v5, 4, v5
	v_and_or_b32 v6, v2, s1, v6
	v_or3_b32 v1, v6, v5, v1
	v_add_lshl_u32 v4, v4, v11, 1
	v_add_u32_e32 v0, 0x2000, v0
	v_lshl_add_u32 v146, v1, 11, v4
	v_ashrrev_i32_e32 v1, 31, v0
	v_lshrrev_b32_e32 v1, 22, v1
	v_add_u32_e32 v1, v0, v1
	v_ashrrev_i32_e32 v12, 10, v1
	v_mul_i32_i24_e32 v1, 0x400, v12
	v_sub_u32_e32 v0, v0, v1
	v_lshrrev_b32_e32 v1, 4, v0
	v_bitop3_b32 v0, v1, v0, 32 bitop3:0x6c
	v_lshl_add_u32 v144, v2, 11, v4
	v_ashrrev_i32_e32 v2, 31, v0
	v_lshrrev_b32_e32 v2, 26, v2
	v_add_u32_e32 v2, v0, v2
	s_ashr_i32 s0, s4, 3
	v_lshlrev_b32_e32 v1, 3, v12
	v_ashrrev_i32_e32 v13, 6, v2
	v_and_b32_e32 v2, 0xc0, v2
	s_add_u32 s12, s30, 0x4400000
	v_and_b32_e32 v1, -16, v1
	v_sub_u32_e32 v0, v0, v2
	s_addc_u32 s13, s31, 0
	v_add_u32_e32 v1, v13, v1
	v_ashrrev_i16_sdwa v0, v3, sext(v0) dst_sel:DWORD dst_unused:UNUSED_PAD src0_sel:DWORD src1_sel:BYTE_0
	v_and_b32_e32 v3, 3, v13
	s_add_i32 s0, s2, s0
	v_and_or_b32 v3, v1, s1, v3
	s_ashr_i32 s1, s0, 31
	s_lshr_b32 s1, s1, 27
	s_add_i32 s1, s0, s1
	s_ashr_i32 s2, s1, 5
	s_andn2_b32 s1, s1, 31
	s_sub_i32 s0, s0, s1
	s_bfe_i32 s1, s0, 0x80000
	s_bfe_u32 s1, s1, 0x3000c
	s_add_i32 s1, s0, s1
	s_lshl_b32 s5, s2, 3
	s_bfe_i32 s2, s1, 0x80000
	s_and_b32 s1, s1, 0xf8
	s_sub_i32 s0, s0, s1
	s_sext_i32_i16 s2, s2
	s_sext_i32_i8 s0, s0
	s_lshr_b32 s2, s2, 3
	s_add_i32 s34, s5, s0
	s_ashr_i32 s4, s3, 6
	s_ashr_i32 s35, s34, 31
	s_bfe_i64 s[14:15], s[2:3], 0x100000
	s_ashr_i32 s10, s3, 8
	s_lshl_b32 s48, s4, 10
	s_lshl_b64 s[0:1], s[34:35], 19
	s_lshl_b64 s[14:15], s[14:15], 19
	s_add_u32 s44, s12, s14
	v_lshlrev_b32_e32 v4, 5, v12
	v_bfe_i32 v14, v0, 0, 16
	v_lshlrev_b32_e32 v0, 1, v1
	v_lshrrev_b32_e32 v2, 2, v1
	s_addc_u32 s45, s13, s15
	s_add_i32 s35, s48, 0
	v_and_b32_e32 v4, 32, v4
	v_and_b32_e32 v0, 24, v0
	v_and_b32_e32 v2, 4, v2
	s_add_i32 m0, s35, 0x10000
	v_or3_b32 v0, v3, v2, v0
	v_add_lshl_u32 v2, v4, v14, 1
	global_load_lds_dwordx4 v146, s[44:45]
	s_add_i32 m0, s35, 0x12000
	v_lshl_add_u32 v150, v0, 11, v2
	s_add_u32 s14, s44, 0x40000
	global_load_lds_dwordx4 v150, s[44:45]
	s_addc_u32 s15, s45, 0
	s_add_i32 m0, s35, 0x14000
	v_lshl_add_u32 v148, v1, 11, v2
	global_load_lds_dwordx4 v146, s[14:15]
	s_add_i32 m0, s35, 0x16000
	s_add_u32 s40, s42, s0
	s_addc_u32 s41, s43, s1
	s_add_i32 s49, s35, 0x2000
	global_load_lds_dwordx4 v150, s[14:15]
	s_mov_b32 m0, s35
	s_add_u32 s0, s40, 0x40000
	global_load_lds_dwordx4 v144, s[40:41]
	s_mov_b32 m0, s49
	s_addc_u32 s1, s41, 0
	s_add_i32 s54, s35, 0x4000
	global_load_lds_dwordx4 v148, s[40:41]
	s_mov_b32 m0, s54
	s_add_i32 s55, s35, 0x6000
	global_load_lds_dwordx4 v144, s[0:1]
	s_mov_b32 m0, s55
	v_mov_b32_e32 v147, 0
	global_load_lds_dwordx4 v148, s[0:1]
	v_mov_b32_e32 v151, v147
	v_mov_b32_e32 v145, v147
	v_mov_b32_e32 v149, v147
	s_cmp_eq_u32 s10, 1
	s_mov_b32 s56, 0
	v_lshl_add_u64 v[6:7], s[44:45], 0, v[146:147]
	v_lshl_add_u64 v[2:3], s[44:45], 0, v[150:151]
	v_lshl_add_u64 v[0:1], s[40:41], 0, v[144:145]
	s_cselect_b64 s[0:1], -1, 0
	s_cmp_lg_u32 s10, 1
	v_lshl_add_u64 v[4:5], s[40:41], 0, v[148:149]
	s_cbranch_scc1 .LBB0_454
	s_barrier
	s_setprio 1

.LBB0_464:
	ds_read_b128 v[128:131], v167
	ds_read_b128 v[132:135], v167 offset:1024
	ds_read_b128 v[136:139], v167 offset:2048
	ds_read_b128 v[140:143], v167 offset:3072
	ds_read_b128 v[160:163], v168
	ds_read_b128 v[172:175], v168 offset:1024
	ds_read_b128 v[178:181], v168 offset:2048
	ds_read_b128 v[182:185], v168 offset:3072
	s_add_u32 s44, s40, 0xfffc0080
	s_addc_u32 s45, s41, -1
	s_cmp_eq_u32 s73, 12
	s_cselect_b32 s47, s23, s45
	s_cselect_b32 s46, s69, s44
	s_cselect_b32 s45, s21, s72
	s_cselect_b32 s44, s70, s71
	v_lshl_add_u64 v[202:203], s[40:41], 0, v[152:153]
	s_add_i32 m0, s35, 0xc000
	ds_read_b128 v[186:189], v169
	ds_read_b128 v[190:193], v169 offset:1024
	ds_read_b128 v[194:197], v169 offset:2048
	ds_read_b128 v[198:201], v169 offset:3072
	ds_read_b128 v[206:209], v169 offset:4096
	ds_read_b128 v[210:213], v169 offset:5120
	ds_read_b128 v[214:217], v169 offset:6144
	ds_read_b128 v[218:221], v169 offset:7168
	global_load_lds_dwordx4 v[202:203], off
	v_lshl_add_u64 v[202:203], s[40:41], 0, v[154:155]
	s_add_i32 m0, s35, 0xe000
	s_nop 0
	global_load_lds_dwordx4 v[202:203], off
	s_waitcnt vmcnt(8)
	s_waitcnt lgkmcnt(0)
	s_barrier
	s_waitcnt lgkmcnt(0)
	v_mfma_f32_16x16x32_f16 v[124:127], v[128:131], v[186:189], v[124:127]
	v_mfma_f32_16x16x32_f16 v[120:123], v[136:139], v[186:189], v[120:123]
	v_mfma_f32_16x16x32_f16 v[108:111], v[128:131], v[194:197], v[108:111]
	v_mfma_f32_16x16x32_f16 v[104:107], v[136:139], v[194:197], v[104:107]
	v_mfma_f32_16x16x32_f16 v[92:95], v[128:131], v[206:209], v[92:95]
	v_mfma_f32_16x16x32_f16 v[88:91], v[136:139], v[206:209], v[88:91]
	v_mfma_f32_16x16x32_f16 v[84:87], v[128:131], v[214:217], v[84:87]
	v_mfma_f32_16x16x32_f16 v[76:79], v[136:139], v[214:217], v[76:79]
	v_mfma_f32_16x16x32_f16 v[124:127], v[132:135], v[190:193], v[124:127]
	v_mfma_f32_16x16x32_f16 v[120:123], v[140:143], v[190:193], v[120:123]
	v_mfma_f32_16x16x32_f16 v[108:111], v[132:135], v[198:201], v[108:111]
	v_mfma_f32_16x16x32_f16 v[104:107], v[140:143], v[198:201], v[104:107]
	v_mfma_f32_16x16x32_f16 v[92:95], v[132:135], v[210:213], v[92:95]
	v_mfma_f32_16x16x32_f16 v[88:91], v[140:143], v[210:213], v[88:91]
	v_mfma_f32_16x16x32_f16 v[84:87], v[132:135], v[218:221], v[84:87]
	v_mfma_f32_16x16x32_f16 v[76:79], v[140:143], v[218:221], v[76:79]
	v_mfma_f32_16x16x32_f16 v[116:119], v[160:163], v[186:189], v[116:119]
	v_mfma_f32_16x16x32_f16 v[112:115], v[178:181], v[186:189], v[112:115]
	v_mfma_f32_16x16x32_f16 v[100:103], v[160:163], v[194:197], v[100:103]
	v_mfma_f32_16x16x32_f16 v[96:99], v[178:181], v[194:197], v[96:99]
	v_mfma_f32_16x16x32_f16 v[80:83], v[160:163], v[206:209], v[80:83]
	v_mfma_f32_16x16x32_f16 v[72:75], v[178:181], v[206:209], v[72:75]
	v_mfma_f32_16x16x32_f16 v[68:71], v[160:163], v[214:217], v[68:71]
	v_mfma_f32_16x16x32_f16 v[64:67], v[178:181], v[214:217], v[64:67]
	v_mfma_f32_16x16x32_f16 v[116:119], v[172:175], v[190:193], v[116:119]
	v_mfma_f32_16x16x32_f16 v[112:115], v[182:185], v[190:193], v[112:115]
	v_mfma_f32_16x16x32_f16 v[100:103], v[172:175], v[198:201], v[100:103]
	v_mfma_f32_16x16x32_f16 v[96:99], v[182:185], v[198:201], v[96:99]
	v_mfma_f32_16x16x32_f16 v[80:83], v[172:175], v[210:213], v[80:83]
	v_mfma_f32_16x16x32_f16 v[72:75], v[182:185], v[210:213], v[72:75]
	v_mfma_f32_16x16x32_f16 v[68:71], v[172:175], v[218:221], v[68:71]
	v_mfma_f32_16x16x32_f16 v[64:67], v[182:185], v[218:221], v[64:67]
	s_barrier
	s_add_i32 s74, s62, s48
	v_lshl_add_u64 v[202:203], s[44:45], 0, v[146:147]
	s_mov_b32 m0, s74
	ds_read_b128 v[186:189], v169 offset:16384
	ds_read_b128 v[190:193], v169 offset:17408
	ds_read_b128 v[194:197], v169 offset:18432
	ds_read_b128 v[198:201], v169 offset:19456
	ds_read_b128 v[206:209], v169 offset:20480
	ds_read_b128 v[210:213], v169 offset:21504
	ds_read_b128 v[214:217], v169 offset:22528
	ds_read_b128 v[218:221], v169 offset:23552
	global_load_lds_dwordx4 v[202:203], off
	s_add_i32 m0, s74, 0x2000
	s_add_u32 s74, s44, 0x40000
	v_lshl_add_u64 v[222:223], s[44:45], 0, v[150:151]
	s_addc_u32 s75, s45, 0
	s_add_i32 s76, s63, s48
	global_load_lds_dwordx4 v[222:223], off
	v_lshl_add_u64 v[224:225], s[74:75], 0, v[146:147]
	s_mov_b32 m0, s76
	v_lshl_add_u64 v[226:227], s[46:47], 0, v[148:149]
	global_load_lds_dwordx4 v[224:225], off
	v_lshl_add_u64 v[224:225], s[74:75], 0, v[150:151]
	s_add_i32 m0, s76, 0x2000
	s_nop 0
	global_load_lds_dwordx4 v[224:225], off
	v_lshl_add_u64 v[224:225], s[46:47], 0, v[144:145]
	s_mov_b32 m0, s35
	s_nop 0
	global_load_lds_dwordx4 v[224:225], off
	s_mov_b32 m0, s49
	s_nop 0
	global_load_lds_dwordx4 v[226:227], off
	s_waitcnt vmcnt(8)
	s_waitcnt lgkmcnt(0)
	s_barrier
	s_waitcnt lgkmcnt(0)
	v_mfma_f32_16x16x32_f16 v[60:63], v[128:131], v[186:189], v[60:63]
	v_mfma_f32_16x16x32_f16 v[56:59], v[136:139], v[186:189], v[56:59]
	v_mfma_f32_16x16x32_f16 v[44:47], v[128:131], v[194:197], v[44:47]
	v_mfma_f32_16x16x32_f16 v[40:43], v[136:139], v[194:197], v[40:43]
	v_mfma_f32_16x16x32_f16 v[28:31], v[128:131], v[206:209], v[28:31]
	v_mfma_f32_16x16x32_f16 v[24:27], v[136:139], v[206:209], v[24:27]
	v_mfma_f32_16x16x32_f16 v[12:15], v[128:131], v[214:217], v[12:15]
	v_mfma_f32_16x16x32_f16 v[8:11], v[136:139], v[214:217], v[8:11]
	v_mfma_f32_16x16x32_f16 v[60:63], v[132:135], v[190:193], v[60:63]
	v_mfma_f32_16x16x32_f16 v[56:59], v[140:143], v[190:193], v[56:59]
	v_mfma_f32_16x16x32_f16 v[44:47], v[132:135], v[198:201], v[44:47]
	v_mfma_f32_16x16x32_f16 v[40:43], v[140:143], v[198:201], v[40:43]
	v_mfma_f32_16x16x32_f16 v[28:31], v[132:135], v[210:213], v[28:31]
	v_mfma_f32_16x16x32_f16 v[24:27], v[140:143], v[210:213], v[24:27]
	v_mfma_f32_16x16x32_f16 v[12:15], v[132:135], v[218:221], v[12:15]
	v_mfma_f32_16x16x32_f16 v[8:11], v[140:143], v[218:221], v[8:11]
	v_mfma_f32_16x16x32_f16 v[52:55], v[160:163], v[186:189], v[52:55]
	v_mfma_f32_16x16x32_f16 v[48:51], v[178:181], v[186:189], v[48:51]
	v_mfma_f32_16x16x32_f16 v[36:39], v[160:163], v[194:197], v[36:39]
	v_mfma_f32_16x16x32_f16 v[32:35], v[178:181], v[194:197], v[32:35]
	v_mfma_f32_16x16x32_f16 v[20:23], v[160:163], v[206:209], v[20:23]
	v_mfma_f32_16x16x32_f16 v[16:19], v[178:181], v[206:209], v[16:19]
	v_mfma_f32_16x16x32_f16 v[4:7], v[160:163], v[214:217], v[4:7]
	v_mfma_f32_16x16x32_f16 v[0:3], v[178:181], v[214:217], v[0:3]
	v_mfma_f32_16x16x32_f16 v[52:55], v[172:175], v[190:193], v[52:55]
	v_mfma_f32_16x16x32_f16 v[48:51], v[182:185], v[190:193], v[48:51]
	v_mfma_f32_16x16x32_f16 v[36:39], v[172:175], v[198:201], v[36:39]
	v_mfma_f32_16x16x32_f16 v[32:35], v[182:185], v[198:201], v[32:35]
	v_mfma_f32_16x16x32_f16 v[20:23], v[172:175], v[210:213], v[20:23]
	v_mfma_f32_16x16x32_f16 v[16:19], v[182:185], v[210:213], v[16:19]
	v_mfma_f32_16x16x32_f16 v[4:7], v[172:175], v[218:221], v[4:7]
	v_mfma_f32_16x16x32_f16 v[0:3], v[182:185], v[218:221], v[0:3]
	s_barrier
	s_add_i32 s74, 0, 0x18000
	s_add_i32 s75, 0, 0x1c000
	v_add_u32_e32 v140, s74, v165
	v_add_u32_e32 v177, s75, v165
	ds_read_b128 v[128:131], v140
	ds_read_b128 v[132:135], v140 offset:1024
	ds_read_b128 v[136:139], v140 offset:2048
	ds_read_b128 v[140:143], v140 offset:3072
	ds_read_b128 v[160:163], v177
	ds_read_b128 v[172:175], v177 offset:1024
	ds_read_b128 v[178:181], v177 offset:2048
	ds_read_b128 v[182:185], v177 offset:3072
	s_add_u32 s46, s46, 0x40000
	s_addc_u32 s47, s47, 0
	s_mov_b32 m0, s54
	v_lshl_add_u64 v[228:229], s[46:47], 0, v[144:145]
	ds_read_b128 v[186:189], v169 offset:32768
	ds_read_b128 v[190:193], v169 offset:33792
	ds_read_b128 v[194:197], v169 offset:34816
	ds_read_b128 v[198:201], v169 offset:35840
	ds_read_b128 v[206:209], v169 offset:36864
	ds_read_b128 v[210:213], v169 offset:37888
	ds_read_b128 v[214:217], v169 offset:38912
	ds_read_b128 v[218:221], v169 offset:39936
	global_load_lds_dwordx4 v[228:229], off
	v_lshl_add_u64 v[228:229], s[46:47], 0, v[148:149]
	s_mov_b32 m0, s55
	s_nop 0
	global_load_lds_dwordx4 v[228:229], off
	s_waitcnt vmcnt(8)
	s_waitcnt lgkmcnt(0)
	s_barrier
	s_waitcnt lgkmcnt(0)
	v_mfma_f32_16x16x32_f16 v[124:127], v[128:131], v[186:189], v[124:127]
	v_mfma_f32_16x16x32_f16 v[120:123], v[136:139], v[186:189], v[120:123]
	v_mfma_f32_16x16x32_f16 v[108:111], v[128:131], v[194:197], v[108:111]
	v_mfma_f32_16x16x32_f16 v[104:107], v[136:139], v[194:197], v[104:107]
	v_mfma_f32_16x16x32_f16 v[92:95], v[128:131], v[206:209], v[92:95]
	v_mfma_f32_16x16x32_f16 v[88:91], v[136:139], v[206:209], v[88:91]
	v_mfma_f32_16x16x32_f16 v[84:87], v[128:131], v[214:217], v[84:87]
	v_mfma_f32_16x16x32_f16 v[76:79], v[136:139], v[214:217], v[76:79]
	v_mfma_f32_16x16x32_f16 v[124:127], v[132:135], v[190:193], v[124:127]
	v_mfma_f32_16x16x32_f16 v[120:123], v[140:143], v[190:193], v[120:123]
	v_mfma_f32_16x16x32_f16 v[108:111], v[132:135], v[198:201], v[108:111]
	v_mfma_f32_16x16x32_f16 v[104:107], v[140:143], v[198:201], v[104:107]
	v_mfma_f32_16x16x32_f16 v[92:95], v[132:135], v[210:213], v[92:95]
	v_mfma_f32_16x16x32_f16 v[88:91], v[140:143], v[210:213], v[88:91]
	v_mfma_f32_16x16x32_f16 v[84:87], v[132:135], v[218:221], v[84:87]
	v_mfma_f32_16x16x32_f16 v[76:79], v[140:143], v[218:221], v[76:79]
	v_mfma_f32_16x16x32_f16 v[116:119], v[160:163], v[186:189], v[116:119]
	v_mfma_f32_16x16x32_f16 v[112:115], v[178:181], v[186:189], v[112:115]
	v_mfma_f32_16x16x32_f16 v[100:103], v[160:163], v[194:197], v[100:103]
	v_mfma_f32_16x16x32_f16 v[96:99], v[178:181], v[194:197], v[96:99]
	v_mfma_f32_16x16x32_f16 v[80:83], v[160:163], v[206:209], v[80:83]
	v_mfma_f32_16x16x32_f16 v[72:75], v[178:181], v[206:209], v[72:75]
	v_mfma_f32_16x16x32_f16 v[68:71], v[160:163], v[214:217], v[68:71]
	v_mfma_f32_16x16x32_f16 v[64:67], v[178:181], v[214:217], v[64:67]
	v_mfma_f32_16x16x32_f16 v[116:119], v[172:175], v[190:193], v[116:119]
	v_mfma_f32_16x16x32_f16 v[112:115], v[182:185], v[190:193], v[112:115]
	v_mfma_f32_16x16x32_f16 v[100:103], v[172:175], v[198:201], v[100:103]
	v_mfma_f32_16x16x32_f16 v[96:99], v[182:185], v[198:201], v[96:99]
	v_mfma_f32_16x16x32_f16 v[80:83], v[172:175], v[210:213], v[80:83]
	v_mfma_f32_16x16x32_f16 v[72:75], v[182:185], v[210:213], v[72:75]
	v_mfma_f32_16x16x32_f16 v[68:71], v[172:175], v[218:221], v[68:71]
	v_mfma_f32_16x16x32_f16 v[64:67], v[182:185], v[218:221], v[64:67]
	s_barrier
	s_add_i32 s46, s74, s48
	v_lshl_add_u64 v[202:203], v[202:203], 0, s[4:5]
	s_mov_b32 m0, s46
	ds_read_b128 v[186:189], v169 offset:49152
	ds_read_b128 v[190:193], v169 offset:50176
	ds_read_b128 v[194:197], v169 offset:51200
	ds_read_b128 v[198:201], v169 offset:52224
	ds_read_b128 v[206:209], v169 offset:53248
	ds_read_b128 v[210:213], v169 offset:54272
	ds_read_b128 v[214:217], v169 offset:55296
	ds_read_b128 v[218:221], v169 offset:56320
	global_load_lds_dwordx4 v[202:203], off
	s_add_i32 m0, s46, 0x2000
	s_add_u32 s44, s44, 0x40080
	v_lshl_add_u64 v[202:203], v[222:223], 0, s[4:5]
	s_addc_u32 s45, s45, 0
	s_add_i32 s46, s75, s48
	global_load_lds_dwordx4 v[202:203], off
	v_lshl_add_u64 v[202:203], s[44:45], 0, v[146:147]
	s_mov_b32 m0, s46
	s_nop 0
	global_load_lds_dwordx4 v[202:203], off
	v_lshl_add_u64 v[202:203], s[44:45], 0, v[150:151]
	s_add_i32 m0, s46, 0x2000
	s_nop 0
	global_load_lds_dwordx4 v[202:203], off
	v_lshl_add_u64 v[202:203], v[224:225], 0, s[4:5]
	s_mov_b32 m0, s59
	s_nop 0
	global_load_lds_dwordx4 v[202:203], off
	v_lshl_add_u64 v[202:203], v[226:227], 0, s[4:5]
	s_mov_b32 m0, s60
	s_nop 0
	global_load_lds_dwordx4 v[202:203], off
	s_waitcnt vmcnt(8)
	s_waitcnt lgkmcnt(0)
	s_barrier
	s_waitcnt lgkmcnt(0)
	v_mfma_f32_16x16x32_f16 v[60:63], v[128:131], v[186:189], v[60:63]
	v_mfma_f32_16x16x32_f16 v[56:59], v[136:139], v[186:189], v[56:59]
	v_mfma_f32_16x16x32_f16 v[44:47], v[128:131], v[194:197], v[44:47]
	v_mfma_f32_16x16x32_f16 v[40:43], v[136:139], v[194:197], v[40:43]
	v_mfma_f32_16x16x32_f16 v[28:31], v[128:131], v[206:209], v[28:31]
	v_mfma_f32_16x16x32_f16 v[24:27], v[136:139], v[206:209], v[24:27]
	v_mfma_f32_16x16x32_f16 v[12:15], v[128:131], v[214:217], v[12:15]
	v_mfma_f32_16x16x32_f16 v[8:11], v[136:139], v[214:217], v[8:11]
	v_mfma_f32_16x16x32_f16 v[60:63], v[132:135], v[190:193], v[60:63]
	v_mfma_f32_16x16x32_f16 v[56:59], v[140:143], v[190:193], v[56:59]
	v_mfma_f32_16x16x32_f16 v[44:47], v[132:135], v[198:201], v[44:47]
	v_mfma_f32_16x16x32_f16 v[40:43], v[140:143], v[198:201], v[40:43]
	v_mfma_f32_16x16x32_f16 v[28:31], v[132:135], v[210:213], v[28:31]
	v_mfma_f32_16x16x32_f16 v[24:27], v[140:143], v[210:213], v[24:27]
	v_mfma_f32_16x16x32_f16 v[12:15], v[132:135], v[218:221], v[12:15]
	v_mfma_f32_16x16x32_f16 v[8:11], v[140:143], v[218:221], v[8:11]
	v_mfma_f32_16x16x32_f16 v[52:55], v[160:163], v[186:189], v[52:55]
	v_mfma_f32_16x16x32_f16 v[48:51], v[178:181], v[186:189], v[48:51]
	v_mfma_f32_16x16x32_f16 v[36:39], v[160:163], v[194:197], v[36:39]
	v_mfma_f32_16x16x32_f16 v[32:35], v[178:181], v[194:197], v[32:35]
	v_mfma_f32_16x16x32_f16 v[20:23], v[160:163], v[206:209], v[20:23]
	v_mfma_f32_16x16x32_f16 v[16:19], v[178:181], v[206:209], v[16:19]
	v_mfma_f32_16x16x32_f16 v[4:7], v[160:163], v[214:217], v[4:7]
	v_mfma_f32_16x16x32_f16 v[0:3], v[178:181], v[214:217], v[0:3]
	v_mfma_f32_16x16x32_f16 v[52:55], v[172:175], v[190:193], v[52:55]
	v_mfma_f32_16x16x32_f16 v[48:51], v[182:185], v[190:193], v[48:51]
	v_mfma_f32_16x16x32_f16 v[36:39], v[172:175], v[198:201], v[36:39]
	v_mfma_f32_16x16x32_f16 v[32:35], v[182:185], v[198:201], v[32:35]
	v_mfma_f32_16x16x32_f16 v[20:23], v[172:175], v[210:213], v[20:23]
	v_mfma_f32_16x16x32_f16 v[16:19], v[182:185], v[210:213], v[16:19]
	v_mfma_f32_16x16x32_f16 v[4:7], v[172:175], v[218:221], v[4:7]
	v_mfma_f32_16x16x32_f16 v[0:3], v[182:185], v[218:221], v[0:3]
	s_barrier
	s_add_i32 s73, s73, 2
	s_add_u32 s40, s40, 0x100
	s_addc_u32 s41, s41, 0
	s_add_u32 s71, s71, 0x100
	s_addc_u32 s72, s72, 0
	s_cmp_gt_u32 s73, 13
	s_cbranch_scc0 .LBB0_464
	s_and_b64 vcc, exec, s[10:11]
	s_cbranch_vccz .LBB0_467
	s_barrier

.LBB0_472:
	s_cmp_gt_i32 s91, 6
	s_cselect_b64 s[2:3], -1, 0
	s_and_b64 s[0:1], s[6:7], s[2:3]
	s_andn2_b64 vcc, exec, s[0:1]
	s_cbranch_vccnz .LBB0_526
	s_waitcnt vmcnt(0)
	s_waitcnt lgkmcnt(0)
	s_setprio 0
	s_barrier
	s_and_saveexec_b64 s[0:1], s[92:93]
	s_cbranch_execz .LBB0_525
	s_add_i32 s4, 0, 0x27ff0
	v_mov_b32_e32 v0, s4
	s_waitcnt vmcnt(0) expcnt(0) lgkmcnt(0)
	ds_read_b32 v2, v0
	s_add_i32 s4, 0, 0x27ff4
	v_mov_b32_e32 v0, s4
	ds_read_b32 v0, v0
	s_waitcnt lgkmcnt(1)
	v_cmp_ne_u32_e32 vcc, 0, v2
	s_cbranch_vccnz .LBB0_489
	s_add_u32 s4, s30, 0x38200
	s_addc_u32 s5, s31, 0
	s_add_u32 s6, s30, 0x38400
	s_addc_u32 s7, s31, 0
	s_add_u32 s10, s30, 0x38500
	s_addc_u32 s11, s31, 0
	s_add_u32 s12, s30, 0x38600
	s_addc_u32 s13, s31, 0
	s_add_u32 s14, s30, 0x38700
	s_addc_u32 s15, s31, 0
	s_add_u32 s16, s30, 0x38800
	s_addc_u32 s17, s31, 0
	s_add_u32 s18, s30, 0x38900
	s_addc_u32 s19, s31, 0
	s_add_u32 s20, s30, 0x38a00
	s_addc_u32 s21, s31, 0
	s_add_u32 s22, s30, 0x38b00
	s_addc_u32 s23, s31, 0
	s_add_u32 s24, s30, 0x38c00
	s_addc_u32 s25, s31, 0
	s_add_u32 s26, s30, 0x38d00
	s_addc_u32 s27, s31, 0
	s_add_u32 s34, s30, 0x38e00
	s_addc_u32 s35, s31, 0
	s_add_u32 s40, s30, 0x38f00
	s_addc_u32 s41, s31, 0
	s_add_u32 s44, s30, 0x39000
	s_addc_u32 s45, s31, 0
	s_add_u32 s46, s30, 0x39100
	s_addc_u32 s47, s31, 0
	s_add_u32 s48, s30, 0x39200
	s_addc_u32 s49, s31, 0
	s_mul_i32 s33, s89, s9
	s_add_u32 s54, s30, 0x39300
	s_mul_i32 s33, s33, s88
	s_addc_u32 s55, s31, 0
	s_mov_b32 s62, 1
	v_mov_b32_e32 v16, 0
	s_branch .LBB0_477

.Lp6_done:
.LBB0_536:
	s_cmp_gt_i32 s91, 7
	s_cselect_b64 s[2:3], -1, 0
	s_and_b64 s[0:1], s[0:1], s[2:3]
	s_andn2_b64 vcc, exec, s[0:1]
	s_cbranch_vccnz .LBB0_590
	s_waitcnt vmcnt(0)
	s_waitcnt lgkmcnt(0)
	s_setprio 0
	s_barrier
	s_and_saveexec_b64 s[0:1], s[92:93]
	s_cbranch_execz .LBB0_589
	s_add_i32 s4, 0, 0x27ff0
	v_mov_b32_e32 v0, s4
	s_waitcnt vmcnt(0) expcnt(0) lgkmcnt(0)
	ds_read_b32 v2, v0
	s_add_i32 s4, 0, 0x27ff4
	v_mov_b32_e32 v0, s4
	ds_read_b32 v0, v0
	s_waitcnt lgkmcnt(1)
	v_cmp_ne_u32_e32 vcc, 0, v2
	s_cbranch_vccnz .LBB0_553
	s_add_u32 s4, s30, 0x38200
	s_addc_u32 s5, s31, 0
	s_add_u32 s6, s30, 0x38400
	s_addc_u32 s7, s31, 0
	s_add_u32 s10, s30, 0x38500
	s_addc_u32 s11, s31, 0
	s_add_u32 s12, s30, 0x38600
	s_addc_u32 s13, s31, 0
	s_add_u32 s14, s30, 0x38700
	s_addc_u32 s15, s31, 0
	s_add_u32 s16, s30, 0x38800
	s_addc_u32 s17, s31, 0
	s_add_u32 s18, s30, 0x38900
	s_addc_u32 s19, s31, 0
	s_add_u32 s20, s30, 0x38a00
	s_addc_u32 s21, s31, 0
	s_add_u32 s22, s30, 0x38b00
	s_addc_u32 s23, s31, 0
	s_add_u32 s24, s30, 0x38c00
	s_addc_u32 s25, s31, 0
	s_add_u32 s26, s30, 0x38d00
	s_addc_u32 s27, s31, 0
	s_add_u32 s34, s30, 0x38e00
	s_addc_u32 s35, s31, 0
	s_add_u32 s40, s30, 0x38f00
	s_addc_u32 s41, s31, 0
	s_add_u32 s44, s30, 0x39000
	s_addc_u32 s45, s31, 0
	s_add_u32 s46, s30, 0x39100
	s_addc_u32 s47, s31, 0
	s_add_u32 s48, s30, 0x39200
	s_addc_u32 s49, s31, 0
	s_mul_i32 s33, s89, s9
	s_add_u32 s54, s30, 0x39300
	s_mul_i32 s33, s33, s88
	s_addc_u32 s55, s31, 0
	s_mov_b32 s62, 1
	v_mov_b32_e32 v16, 0
	s_branch .LBB0_541

.Lp7_done:
.LBB0_596:
	s_cmp_gt_i32 s91, 8
	s_cselect_b64 s[2:3], -1, 0
	s_and_b64 s[0:1], s[0:1], s[2:3]
	s_andn2_b64 vcc, exec, s[0:1]
	s_cbranch_vccnz .LBB0_650
	s_waitcnt vmcnt(0)
	s_waitcnt lgkmcnt(0)
	s_setprio 0
	s_barrier
	s_and_saveexec_b64 s[0:1], s[92:93]
	s_cbranch_execz .LBB0_649
	s_add_i32 s4, 0, 0x27ff0
	v_mov_b32_e32 v0, s4
	s_waitcnt vmcnt(0) expcnt(0) lgkmcnt(0)
	ds_read_b32 v2, v0
	s_add_i32 s4, 0, 0x27ff4
	v_mov_b32_e32 v0, s4
	ds_read_b32 v0, v0
	s_waitcnt lgkmcnt(1)
	v_cmp_ne_u32_e32 vcc, 0, v2
	s_cbranch_vccnz .LBB0_613
	s_add_u32 s4, s30, 0x38200
	s_addc_u32 s5, s31, 0
	s_add_u32 s6, s30, 0x38400
	s_addc_u32 s7, s31, 0
	s_add_u32 s10, s30, 0x38500
	s_addc_u32 s11, s31, 0
	s_add_u32 s12, s30, 0x38600
	s_addc_u32 s13, s31, 0
	s_add_u32 s14, s30, 0x38700
	s_addc_u32 s15, s31, 0
	s_add_u32 s16, s30, 0x38800
	s_addc_u32 s17, s31, 0
	s_add_u32 s18, s30, 0x38900
	s_addc_u32 s19, s31, 0
	s_add_u32 s20, s30, 0x38a00
	s_addc_u32 s21, s31, 0
	s_add_u32 s22, s30, 0x38b00
	s_addc_u32 s23, s31, 0
	s_add_u32 s24, s30, 0x38c00
	s_addc_u32 s25, s31, 0
	s_add_u32 s26, s30, 0x38d00
	s_addc_u32 s27, s31, 0
	s_add_u32 s34, s30, 0x38e00
	s_addc_u32 s35, s31, 0
	s_add_u32 s40, s30, 0x38f00
	s_addc_u32 s41, s31, 0
	s_add_u32 s44, s30, 0x39000
	s_addc_u32 s45, s31, 0
	s_add_u32 s46, s30, 0x39100
	s_addc_u32 s47, s31, 0
	s_add_u32 s48, s30, 0x39200
	s_addc_u32 s49, s31, 0
	s_mul_i32 s33, s89, s9
	s_add_u32 s54, s30, 0x39300
	s_mul_i32 s33, s33, s88
	s_addc_u32 s55, s31, 0
	s_mov_b32 s62, 1
	v_mov_b32_e32 v16, 0
	s_branch .LBB0_601

.Lp8_done:
.LBB0_659:
	s_cmp_gt_i32 s91, 9
	s_cselect_b64 s[2:3], -1, 0
	s_and_b64 s[0:1], s[0:1], s[2:3]
	s_andn2_b64 vcc, exec, s[0:1]
	s_cbranch_vccnz .LBB0_713
	s_waitcnt vmcnt(0)
	s_waitcnt lgkmcnt(0)
	s_setprio 0
	s_barrier
	s_and_saveexec_b64 s[0:1], s[92:93]
	s_cbranch_execz .LBB0_712
	s_add_i32 s4, 0, 0x27ff0
	v_mov_b32_e32 v0, s4
	s_waitcnt vmcnt(0) expcnt(0) lgkmcnt(0)
	ds_read_b32 v2, v0
	s_add_i32 s4, 0, 0x27ff4
	v_mov_b32_e32 v0, s4
	ds_read_b32 v0, v0
	s_waitcnt lgkmcnt(1)
	v_cmp_ne_u32_e32 vcc, 0, v2
	s_cbranch_vccnz .LBB0_676
	s_add_u32 s4, s30, 0x38200
	s_addc_u32 s5, s31, 0
	s_add_u32 s6, s30, 0x38400
	s_addc_u32 s7, s31, 0
	s_add_u32 s10, s30, 0x38500
	s_addc_u32 s11, s31, 0
	s_add_u32 s12, s30, 0x38600
	s_addc_u32 s13, s31, 0
	s_add_u32 s14, s30, 0x38700
	s_addc_u32 s15, s31, 0
	s_add_u32 s16, s30, 0x38800
	s_addc_u32 s17, s31, 0
	s_add_u32 s18, s30, 0x38900
	s_addc_u32 s19, s31, 0
	s_add_u32 s20, s30, 0x38a00
	s_addc_u32 s21, s31, 0
	s_add_u32 s22, s30, 0x38b00
	s_addc_u32 s23, s31, 0
	s_add_u32 s24, s30, 0x38c00
	s_addc_u32 s25, s31, 0
	s_add_u32 s26, s30, 0x38d00
	s_addc_u32 s27, s31, 0
	s_add_u32 s34, s30, 0x38e00
	s_addc_u32 s35, s31, 0
	s_add_u32 s40, s30, 0x38f00
	s_addc_u32 s41, s31, 0
	s_add_u32 s44, s30, 0x39000
	s_addc_u32 s45, s31, 0
	s_add_u32 s46, s30, 0x39100
	s_addc_u32 s47, s31, 0
	s_add_u32 s48, s30, 0x39200
	s_addc_u32 s49, s31, 0
	s_mul_i32 s33, s89, s9
	s_add_u32 s54, s30, 0x39300
	s_mul_i32 s33, s33, s88
	s_addc_u32 s55, s31, 0
	s_mov_b32 s62, 1
	v_mov_b32_e32 v16, 0
	s_branch .LBB0_664

.LBB0_722:
	v_ashrrev_i32_e32 v1, 31, v8
	v_lshrrev_b32_e32 v1, 26, v1
	v_add_u32_e32 v1, v8, v1
	v_ashrrev_i32_e32 v9, 6, v1
	v_bfe_i32 v1, v8, 27, 1
	v_lshlrev_b32_e32 v0, 4, v8
	v_lshrrev_b32_e32 v1, 22, v1
	v_add_u32_e32 v1, v0, v1
	v_and_b32_e32 v1, 0xfffffc00, v1
	v_sub_u32_e32 v1, v0, v1
	v_lshrrev_b32_e32 v2, 4, v1
	v_bitop3_b32 v1, v2, v1, 32 bitop3:0x6c
	v_ashrrev_i32_e32 v3, 31, v1
	v_lshrrev_b32_e32 v3, 26, v3
	v_add_u32_e32 v3, v1, v3
	v_lshlrev_b32_e32 v2, 3, v9
	v_ashrrev_i32_e32 v10, 6, v3
	v_and_b32_e32 v3, 0xc0, v3
	v_and_b32_e32 v2, -16, v2
	v_sub_u32_e32 v1, v1, v3
	v_mov_b32_e32 v3, 1
	v_add_u32_e32 v2, v10, v2
	v_ashrrev_i16_sdwa v1, v3, sext(v1) dst_sel:DWORD dst_unused:UNUSED_PAD src0_sel:DWORD src1_sel:BYTE_0
	v_lshlrev_b32_e32 v4, 5, v9
	v_bfe_i32 v11, v1, 0, 16
	v_lshlrev_b32_e32 v1, 1, v2
	v_lshrrev_b32_e32 v5, 2, v2
	v_and_b32_e32 v6, 3, v10
	s_mov_b32 s3, 0x1fffe0
	v_and_b32_e32 v4, 32, v4
	v_and_b32_e32 v1, 24, v1
	v_and_b32_e32 v5, 4, v5
	v_and_or_b32 v6, v2, s3, v6
	v_or3_b32 v1, v6, v5, v1
	v_add_lshl_u32 v4, v4, v11, 1
	v_add_u32_e32 v0, 0x2000, v0
	v_lshl_add_u32 v170, v1, 11, v4
	v_ashrrev_i32_e32 v1, 31, v0
	v_lshrrev_b32_e32 v1, 22, v1
	v_add_u32_e32 v1, v0, v1
	v_ashrrev_i32_e32 v12, 10, v1
	v_mul_i32_i24_e32 v1, 0x400, v12
	v_sub_u32_e32 v0, v0, v1
	v_lshrrev_b32_e32 v1, 4, v0
	v_bitop3_b32 v0, v1, v0, 32 bitop3:0x6c
	v_lshl_add_u32 v168, v2, 11, v4
	v_ashrrev_i32_e32 v2, 31, v0
	v_lshrrev_b32_e32 v2, 26, v2
	v_add_u32_e32 v2, v0, v2
	s_add_u32 s33, s30, 0xd600000
	v_lshlrev_b32_e32 v1, 3, v12
	v_ashrrev_i32_e32 v13, 6, v2
	v_and_b32_e32 v2, 0xc0, v2
	s_addc_u32 s46, s31, 0
	v_and_b32_e32 v1, -16, v1
	v_sub_u32_e32 v0, v0, v2
	s_add_u32 s47, s30, 0x4600000
	v_add_u32_e32 v1, v13, v1
	v_ashrrev_i16_sdwa v0, v3, sext(v0) dst_sel:DWORD dst_unused:UNUSED_PAD src0_sel:DWORD src1_sel:BYTE_0
	v_and_b32_e32 v3, 3, v13
	s_addc_u32 s48, s31, 0
	v_and_or_b32 v3, v1, s3, v3
	s_ashr_i32 s3, s14, 6
	s_ashr_i32 s27, s26, 31
	s_ashr_i32 s25, s24, 31
	s_ashr_i32 s2, s14, 8
	s_lshl_b32 s49, s3, 10
	s_lshl_b64 s[4:5], s[26:27], 19
	s_lshl_b64 s[10:11], s[24:25], 19
	s_add_u32 s40, s47, s10
	v_lshlrev_b32_e32 v4, 5, v12
	v_bfe_i32 v14, v0, 0, 16
	v_lshlrev_b32_e32 v0, 1, v1
	v_lshrrev_b32_e32 v2, 2, v1
	s_addc_u32 s41, s48, s11
	s_add_i32 s27, s49, 0
	v_and_b32_e32 v4, 32, v4
	v_and_b32_e32 v0, 24, v0
	v_and_b32_e32 v2, 4, v2
	s_add_i32 m0, s27, 0x10000
	v_or3_b32 v0, v3, v2, v0
	v_add_lshl_u32 v2, v4, v14, 1
	global_load_lds_dwordx4 v170, s[40:41]
	s_add_i32 m0, s27, 0x12000
	v_lshl_add_u32 v174, v0, 11, v2
	s_add_u32 s10, s40, 0x40000
	global_load_lds_dwordx4 v174, s[40:41]
	s_addc_u32 s11, s41, 0
	s_add_i32 m0, s27, 0x14000
	v_lshl_add_u32 v172, v1, 11, v2
	global_load_lds_dwordx4 v170, s[10:11]
	s_add_i32 m0, s27, 0x16000
	s_add_u32 s34, s33, s4
	s_addc_u32 s35, s46, s5
	s_add_i32 s54, s27, 0x2000
	global_load_lds_dwordx4 v174, s[10:11]
	s_mov_b32 m0, s27
	s_add_u32 s4, s34, 0x40000
	global_load_lds_dwordx4 v168, s[34:35]
	s_mov_b32 m0, s54
	s_addc_u32 s5, s35, 0
	s_add_i32 s55, s27, 0x4000
	global_load_lds_dwordx4 v172, s[34:35]
	s_mov_b32 m0, s55
	s_add_i32 s56, s27, 0x6000
	global_load_lds_dwordx4 v168, s[4:5]
	s_mov_b32 m0, s56
	v_mov_b32_e32 v171, 0
	global_load_lds_dwordx4 v172, s[4:5]
	v_mov_b32_e32 v175, v171
	v_mov_b32_e32 v169, v171
	v_mov_b32_e32 v173, v171
	s_cmp_eq_u32 s2, 1
	s_mov_b32 s57, 0
	v_lshl_add_u64 v[6:7], s[40:41], 0, v[170:171]
	v_lshl_add_u64 v[4:5], s[40:41], 0, v[174:175]
	v_lshl_add_u64 v[0:1], s[34:35], 0, v[168:169]
	s_cselect_b64 s[10:11], -1, 0
	s_cmp_lg_u32 s2, 1
	v_lshl_add_u64 v[2:3], s[34:35], 0, v[172:173]
	s_cbranch_scc1 .LBB0_724
	s_barrier
	s_setprio 1

.LBB0_734:
	ds_read_b128 v[84:87], v208
	ds_read_b128 v[88:91], v208 offset:1024
	ds_read_b128 v[92:95], v208 offset:2048
	ds_read_b128 v[100:103], v208 offset:3072
	ds_read_b128 v[144:147], v209
	ds_read_b128 v[148:151], v209 offset:1024
	ds_read_b128 v[152:155], v209 offset:2048
	ds_read_b128 v[156:159], v209 offset:3072
	s_add_u32 s40, s34, 0xfffc0080
	s_addc_u32 s41, s35, -1
	s_cmp_eq_u32 s71, 12
	s_cselect_b32 s45, s19, s41
	s_cselect_b32 s44, s25, s40
	s_cselect_b32 s41, s17, s70
	s_cselect_b32 s40, s68, s69
	v_lshl_add_u64 v[202:203], s[34:35], 0, v[178:179]
	s_add_i32 m0, s27, 0xc000
	ds_read_b128 v[160:163], v210
	ds_read_b128 v[164:167], v210 offset:1024
	ds_read_b128 v[186:189], v210 offset:2048
	ds_read_b128 v[190:193], v210 offset:3072
	ds_read_b128 v[194:197], v210 offset:4096
	ds_read_b128 v[198:201], v210 offset:5120
	ds_read_b128 v[212:215], v210 offset:6144
	ds_read_b128 v[216:219], v210 offset:7168
	global_load_lds_dwordx4 v[202:203], off
	v_lshl_add_u64 v[202:203], s[34:35], 0, v[180:181]
	s_add_i32 m0, s27, 0xe000
	s_nop 0
	global_load_lds_dwordx4 v[202:203], off
	s_waitcnt vmcnt(8)
	s_waitcnt lgkmcnt(0)
	s_barrier
	s_waitcnt lgkmcnt(0)
	v_mfma_f32_16x16x32_f16 v[136:139], v[84:87], v[160:163], v[136:139]
	v_mfma_f32_16x16x32_f16 v[128:131], v[92:95], v[160:163], v[128:131]
	v_mfma_f32_16x16x32_f16 v[124:127], v[84:87], v[186:189], v[124:127]
	v_mfma_f32_16x16x32_f16 v[116:119], v[92:95], v[186:189], v[116:119]
	v_mfma_f32_16x16x32_f16 v[108:111], v[84:87], v[194:197], v[108:111]
	v_mfma_f32_16x16x32_f16 v[96:99], v[92:95], v[194:197], v[96:99]
	v_mfma_f32_16x16x32_f16 v[76:79], v[84:87], v[212:215], v[76:79]
	v_mfma_f32_16x16x32_f16 v[68:71], v[92:95], v[212:215], v[68:71]
	v_mfma_f32_16x16x32_f16 v[136:139], v[88:91], v[164:167], v[136:139]
	v_mfma_f32_16x16x32_f16 v[128:131], v[100:103], v[164:167], v[128:131]
	v_mfma_f32_16x16x32_f16 v[124:127], v[88:91], v[190:193], v[124:127]
	v_mfma_f32_16x16x32_f16 v[116:119], v[100:103], v[190:193], v[116:119]
	v_mfma_f32_16x16x32_f16 v[108:111], v[88:91], v[198:201], v[108:111]
	v_mfma_f32_16x16x32_f16 v[96:99], v[100:103], v[198:201], v[96:99]
	v_mfma_f32_16x16x32_f16 v[76:79], v[88:91], v[216:219], v[76:79]
	v_mfma_f32_16x16x32_f16 v[68:71], v[100:103], v[216:219], v[68:71]
	v_mfma_f32_16x16x32_f16 v[140:143], v[144:147], v[160:163], v[140:143]
	v_mfma_f32_16x16x32_f16 v[132:135], v[152:155], v[160:163], v[132:135]
	v_mfma_f32_16x16x32_f16 v[120:123], v[144:147], v[186:189], v[120:123]
	v_mfma_f32_16x16x32_f16 v[112:115], v[152:155], v[186:189], v[112:115]
	v_mfma_f32_16x16x32_f16 v[104:107], v[144:147], v[194:197], v[104:107]
	v_mfma_f32_16x16x32_f16 v[80:83], v[152:155], v[194:197], v[80:83]
	v_mfma_f32_16x16x32_f16 v[72:75], v[144:147], v[212:215], v[72:75]
	v_mfma_f32_16x16x32_f16 v[64:67], v[152:155], v[212:215], v[64:67]
	v_mfma_f32_16x16x32_f16 v[140:143], v[148:151], v[164:167], v[140:143]
	v_mfma_f32_16x16x32_f16 v[132:135], v[156:159], v[164:167], v[132:135]
	v_mfma_f32_16x16x32_f16 v[120:123], v[148:151], v[190:193], v[120:123]
	v_mfma_f32_16x16x32_f16 v[112:115], v[156:159], v[190:193], v[112:115]
	v_mfma_f32_16x16x32_f16 v[104:107], v[148:151], v[198:201], v[104:107]
	v_mfma_f32_16x16x32_f16 v[80:83], v[156:159], v[198:201], v[80:83]
	v_mfma_f32_16x16x32_f16 v[72:75], v[148:151], v[216:219], v[72:75]
	v_mfma_f32_16x16x32_f16 v[64:67], v[156:159], v[216:219], v[64:67]
	s_barrier
	s_add_i32 s72, s66, s49
	v_lshl_add_u64 v[202:203], s[40:41], 0, v[170:171]
	s_mov_b32 m0, s72
	ds_read_b128 v[160:163], v210 offset:16384
	ds_read_b128 v[164:167], v210 offset:17408
	ds_read_b128 v[186:189], v210 offset:18432
	ds_read_b128 v[190:193], v210 offset:19456
	ds_read_b128 v[194:197], v210 offset:20480
	ds_read_b128 v[198:201], v210 offset:21504
	ds_read_b128 v[212:215], v210 offset:22528
	ds_read_b128 v[216:219], v210 offset:23552
	global_load_lds_dwordx4 v[202:203], off
	s_add_i32 m0, s72, 0x2000
	s_add_u32 s72, s40, 0x40000
	v_lshl_add_u64 v[220:221], s[40:41], 0, v[174:175]
	s_addc_u32 s73, s41, 0
	s_add_i32 s74, s67, s49
	global_load_lds_dwordx4 v[220:221], off
	v_lshl_add_u64 v[222:223], s[72:73], 0, v[170:171]
	s_mov_b32 m0, s74
	v_lshl_add_u64 v[224:225], s[44:45], 0, v[172:173]
	global_load_lds_dwordx4 v[222:223], off
	v_lshl_add_u64 v[222:223], s[72:73], 0, v[174:175]
	s_add_i32 m0, s74, 0x2000
	s_nop 0
	global_load_lds_dwordx4 v[222:223], off
	v_lshl_add_u64 v[222:223], s[44:45], 0, v[168:169]
	s_mov_b32 m0, s27
	s_nop 0
	global_load_lds_dwordx4 v[222:223], off
	s_mov_b32 m0, s54
	s_nop 0
	global_load_lds_dwordx4 v[224:225], off
	s_waitcnt vmcnt(8)
	s_waitcnt lgkmcnt(0)
	s_barrier
	s_waitcnt lgkmcnt(0)
	v_mfma_f32_16x16x32_f16 v[60:63], v[84:87], v[160:163], v[60:63]
	v_mfma_f32_16x16x32_f16 v[52:55], v[92:95], v[160:163], v[52:55]
	v_mfma_f32_16x16x32_f16 v[44:47], v[84:87], v[186:189], v[44:47]
	v_mfma_f32_16x16x32_f16 v[36:39], v[92:95], v[186:189], v[36:39]
	v_mfma_f32_16x16x32_f16 v[28:31], v[84:87], v[194:197], v[28:31]
	v_mfma_f32_16x16x32_f16 v[20:23], v[92:95], v[194:197], v[20:23]
	v_mfma_f32_16x16x32_f16 v[12:15], v[84:87], v[212:215], v[12:15]
	v_mfma_f32_16x16x32_f16 v[4:7], v[92:95], v[212:215], v[4:7]
	v_mfma_f32_16x16x32_f16 v[60:63], v[88:91], v[164:167], v[60:63]
	v_mfma_f32_16x16x32_f16 v[52:55], v[100:103], v[164:167], v[52:55]
	v_mfma_f32_16x16x32_f16 v[44:47], v[88:91], v[190:193], v[44:47]
	v_mfma_f32_16x16x32_f16 v[36:39], v[100:103], v[190:193], v[36:39]
	v_mfma_f32_16x16x32_f16 v[28:31], v[88:91], v[198:201], v[28:31]
	v_mfma_f32_16x16x32_f16 v[20:23], v[100:103], v[198:201], v[20:23]
	v_mfma_f32_16x16x32_f16 v[12:15], v[88:91], v[216:219], v[12:15]
	v_mfma_f32_16x16x32_f16 v[4:7], v[100:103], v[216:219], v[4:7]
	v_mfma_f32_16x16x32_f16 v[56:59], v[144:147], v[160:163], v[56:59]
	v_mfma_f32_16x16x32_f16 v[48:51], v[152:155], v[160:163], v[48:51]
	v_mfma_f32_16x16x32_f16 v[40:43], v[144:147], v[186:189], v[40:43]
	v_mfma_f32_16x16x32_f16 v[32:35], v[152:155], v[186:189], v[32:35]
	v_mfma_f32_16x16x32_f16 v[24:27], v[144:147], v[194:197], v[24:27]
	v_mfma_f32_16x16x32_f16 v[16:19], v[152:155], v[194:197], v[16:19]
	v_mfma_f32_16x16x32_f16 v[8:11], v[144:147], v[212:215], v[8:11]
	v_mfma_f32_16x16x32_f16 v[0:3], v[152:155], v[212:215], v[0:3]
	v_mfma_f32_16x16x32_f16 v[56:59], v[148:151], v[164:167], v[56:59]
	v_mfma_f32_16x16x32_f16 v[48:51], v[156:159], v[164:167], v[48:51]
	v_mfma_f32_16x16x32_f16 v[40:43], v[148:151], v[190:193], v[40:43]
	v_mfma_f32_16x16x32_f16 v[32:35], v[156:159], v[190:193], v[32:35]
	v_mfma_f32_16x16x32_f16 v[24:27], v[148:151], v[198:201], v[24:27]
	v_mfma_f32_16x16x32_f16 v[16:19], v[156:159], v[198:201], v[16:19]
	v_mfma_f32_16x16x32_f16 v[8:11], v[148:151], v[216:219], v[8:11]
	v_mfma_f32_16x16x32_f16 v[0:3], v[156:159], v[216:219], v[0:3]
	s_barrier
	s_add_i32 s72, 0, 0x18000
	s_add_i32 s73, 0, 0x1c000
	v_add_u32_e32 v100, s72, v206
	v_add_u32_e32 v156, s73, v206
	ds_read_b128 v[84:87], v100
	ds_read_b128 v[88:91], v100 offset:1024
	ds_read_b128 v[92:95], v100 offset:2048
	ds_read_b128 v[100:103], v100 offset:3072
	ds_read_b128 v[144:147], v156
	ds_read_b128 v[148:151], v156 offset:1024
	ds_read_b128 v[152:155], v156 offset:2048
	ds_read_b128 v[156:159], v156 offset:3072
	s_add_u32 s44, s44, 0x40000
	s_addc_u32 s45, s45, 0
	s_mov_b32 m0, s55
	v_lshl_add_u64 v[226:227], s[44:45], 0, v[168:169]
	ds_read_b128 v[160:163], v210 offset:32768
	ds_read_b128 v[164:167], v210 offset:33792
	ds_read_b128 v[186:189], v210 offset:34816
	ds_read_b128 v[190:193], v210 offset:35840
	ds_read_b128 v[194:197], v210 offset:36864
	ds_read_b128 v[198:201], v210 offset:37888
	ds_read_b128 v[212:215], v210 offset:38912
	ds_read_b128 v[216:219], v210 offset:39936
	global_load_lds_dwordx4 v[226:227], off
	v_lshl_add_u64 v[226:227], s[44:45], 0, v[172:173]
	s_mov_b32 m0, s56
	s_nop 0
	global_load_lds_dwordx4 v[226:227], off
	s_waitcnt vmcnt(8)
	s_waitcnt lgkmcnt(0)
	s_barrier
	s_waitcnt lgkmcnt(0)
	v_mfma_f32_16x16x32_f16 v[136:139], v[84:87], v[160:163], v[136:139]
	v_mfma_f32_16x16x32_f16 v[128:131], v[92:95], v[160:163], v[128:131]
	v_mfma_f32_16x16x32_f16 v[124:127], v[84:87], v[186:189], v[124:127]
	v_mfma_f32_16x16x32_f16 v[116:119], v[92:95], v[186:189], v[116:119]
	v_mfma_f32_16x16x32_f16 v[108:111], v[84:87], v[194:197], v[108:111]
	v_mfma_f32_16x16x32_f16 v[96:99], v[92:95], v[194:197], v[96:99]
	v_mfma_f32_16x16x32_f16 v[76:79], v[84:87], v[212:215], v[76:79]
	v_mfma_f32_16x16x32_f16 v[68:71], v[92:95], v[212:215], v[68:71]
	v_mfma_f32_16x16x32_f16 v[136:139], v[88:91], v[164:167], v[136:139]
	v_mfma_f32_16x16x32_f16 v[128:131], v[100:103], v[164:167], v[128:131]
	v_mfma_f32_16x16x32_f16 v[124:127], v[88:91], v[190:193], v[124:127]
	v_mfma_f32_16x16x32_f16 v[116:119], v[100:103], v[190:193], v[116:119]
	v_mfma_f32_16x16x32_f16 v[108:111], v[88:91], v[198:201], v[108:111]
	v_mfma_f32_16x16x32_f16 v[96:99], v[100:103], v[198:201], v[96:99]
	v_mfma_f32_16x16x32_f16 v[76:79], v[88:91], v[216:219], v[76:79]
	v_mfma_f32_16x16x32_f16 v[68:71], v[100:103], v[216:219], v[68:71]
	v_mfma_f32_16x16x32_f16 v[140:143], v[144:147], v[160:163], v[140:143]
	v_mfma_f32_16x16x32_f16 v[132:135], v[152:155], v[160:163], v[132:135]
	v_mfma_f32_16x16x32_f16 v[120:123], v[144:147], v[186:189], v[120:123]
	v_mfma_f32_16x16x32_f16 v[112:115], v[152:155], v[186:189], v[112:115]
	v_mfma_f32_16x16x32_f16 v[104:107], v[144:147], v[194:197], v[104:107]
	v_mfma_f32_16x16x32_f16 v[80:83], v[152:155], v[194:197], v[80:83]
	v_mfma_f32_16x16x32_f16 v[72:75], v[144:147], v[212:215], v[72:75]
	v_mfma_f32_16x16x32_f16 v[64:67], v[152:155], v[212:215], v[64:67]
	v_mfma_f32_16x16x32_f16 v[140:143], v[148:151], v[164:167], v[140:143]
	v_mfma_f32_16x16x32_f16 v[132:135], v[156:159], v[164:167], v[132:135]
	v_mfma_f32_16x16x32_f16 v[120:123], v[148:151], v[190:193], v[120:123]
	v_mfma_f32_16x16x32_f16 v[112:115], v[156:159], v[190:193], v[112:115]
	v_mfma_f32_16x16x32_f16 v[104:107], v[148:151], v[198:201], v[104:107]
	v_mfma_f32_16x16x32_f16 v[80:83], v[156:159], v[198:201], v[80:83]
	v_mfma_f32_16x16x32_f16 v[72:75], v[148:151], v[216:219], v[72:75]
	v_mfma_f32_16x16x32_f16 v[64:67], v[156:159], v[216:219], v[64:67]
	s_barrier
	s_add_i32 s44, s72, s49
	v_lshl_add_u64 v[202:203], v[202:203], 0, s[12:13]
	s_mov_b32 m0, s44
	ds_read_b128 v[160:163], v210 offset:49152
	ds_read_b128 v[164:167], v210 offset:50176
	ds_read_b128 v[186:189], v210 offset:51200
	ds_read_b128 v[190:193], v210 offset:52224
	ds_read_b128 v[194:197], v210 offset:53248
	ds_read_b128 v[198:201], v210 offset:54272
	ds_read_b128 v[212:215], v210 offset:55296
	ds_read_b128 v[216:219], v210 offset:56320
	global_load_lds_dwordx4 v[202:203], off
	s_add_i32 m0, s44, 0x2000
	s_add_u32 s40, s40, 0x40080
	v_lshl_add_u64 v[202:203], v[220:221], 0, s[12:13]
	s_addc_u32 s41, s41, 0
	s_add_i32 s44, s73, s49
	global_load_lds_dwordx4 v[202:203], off
	v_lshl_add_u64 v[202:203], s[40:41], 0, v[170:171]
	s_mov_b32 m0, s44
	s_nop 0
	global_load_lds_dwordx4 v[202:203], off
	v_lshl_add_u64 v[202:203], s[40:41], 0, v[174:175]
	s_add_i32 m0, s44, 0x2000
	s_nop 0
	global_load_lds_dwordx4 v[202:203], off
	v_lshl_add_u64 v[202:203], v[222:223], 0, s[12:13]
	s_mov_b32 m0, s62
	s_nop 0
	global_load_lds_dwordx4 v[202:203], off
	v_lshl_add_u64 v[202:203], v[224:225], 0, s[12:13]
	s_mov_b32 m0, s63
	s_nop 0
	global_load_lds_dwordx4 v[202:203], off
	s_waitcnt vmcnt(8)
	s_waitcnt lgkmcnt(0)
	s_barrier
	s_waitcnt lgkmcnt(0)
	v_mfma_f32_16x16x32_f16 v[60:63], v[84:87], v[160:163], v[60:63]
	v_mfma_f32_16x16x32_f16 v[52:55], v[92:95], v[160:163], v[52:55]
	v_mfma_f32_16x16x32_f16 v[44:47], v[84:87], v[186:189], v[44:47]
	v_mfma_f32_16x16x32_f16 v[36:39], v[92:95], v[186:189], v[36:39]
	v_mfma_f32_16x16x32_f16 v[28:31], v[84:87], v[194:197], v[28:31]
	v_mfma_f32_16x16x32_f16 v[20:23], v[92:95], v[194:197], v[20:23]
	v_mfma_f32_16x16x32_f16 v[12:15], v[84:87], v[212:215], v[12:15]
	v_mfma_f32_16x16x32_f16 v[4:7], v[92:95], v[212:215], v[4:7]
	v_mfma_f32_16x16x32_f16 v[60:63], v[88:91], v[164:167], v[60:63]
	v_mfma_f32_16x16x32_f16 v[52:55], v[100:103], v[164:167], v[52:55]
	v_mfma_f32_16x16x32_f16 v[44:47], v[88:91], v[190:193], v[44:47]
	v_mfma_f32_16x16x32_f16 v[36:39], v[100:103], v[190:193], v[36:39]
	v_mfma_f32_16x16x32_f16 v[28:31], v[88:91], v[198:201], v[28:31]
	v_mfma_f32_16x16x32_f16 v[20:23], v[100:103], v[198:201], v[20:23]
	v_mfma_f32_16x16x32_f16 v[12:15], v[88:91], v[216:219], v[12:15]
	v_mfma_f32_16x16x32_f16 v[4:7], v[100:103], v[216:219], v[4:7]
	v_mfma_f32_16x16x32_f16 v[56:59], v[144:147], v[160:163], v[56:59]
	v_mfma_f32_16x16x32_f16 v[48:51], v[152:155], v[160:163], v[48:51]
	v_mfma_f32_16x16x32_f16 v[40:43], v[144:147], v[186:189], v[40:43]
	v_mfma_f32_16x16x32_f16 v[32:35], v[152:155], v[186:189], v[32:35]
	v_mfma_f32_16x16x32_f16 v[24:27], v[144:147], v[194:197], v[24:27]
	v_mfma_f32_16x16x32_f16 v[16:19], v[152:155], v[194:197], v[16:19]
	v_mfma_f32_16x16x32_f16 v[8:11], v[144:147], v[212:215], v[8:11]
	v_mfma_f32_16x16x32_f16 v[0:3], v[152:155], v[212:215], v[0:3]
	v_mfma_f32_16x16x32_f16 v[56:59], v[148:151], v[164:167], v[56:59]
	v_mfma_f32_16x16x32_f16 v[48:51], v[156:159], v[164:167], v[48:51]
	v_mfma_f32_16x16x32_f16 v[40:43], v[148:151], v[190:193], v[40:43]
	v_mfma_f32_16x16x32_f16 v[32:35], v[156:159], v[190:193], v[32:35]
	v_mfma_f32_16x16x32_f16 v[24:27], v[148:151], v[198:201], v[24:27]
	v_mfma_f32_16x16x32_f16 v[16:19], v[156:159], v[198:201], v[16:19]
	v_mfma_f32_16x16x32_f16 v[8:11], v[148:151], v[216:219], v[8:11]
	v_mfma_f32_16x16x32_f16 v[0:3], v[156:159], v[216:219], v[0:3]
	s_barrier
	s_add_i32 s71, s71, 2
	s_add_u32 s34, s34, 0x100
	s_addc_u32 s35, s35, 0
	s_add_u32 s69, s69, 0x100
	s_addc_u32 s70, s70, 0
	s_cmp_gt_u32 s71, 13
	s_cbranch_scc0 .LBB0_734
	s_and_b64 vcc, exec, s[14:15]
	s_cbranch_vccz .LBB0_737
	s_barrier

.LBB0_801:
	s_cmp_lt_i32 s91, 11
	s_cselect_b64 s[2:3], -1, 0
	s_xor_b64 s[0:1], s[0:1], -1
	s_or_b64 s[0:1], s[0:1], s[2:3]
	s_and_b64 vcc, exec, s[0:1]
	s_cbranch_vccnz .LBB0_855
	s_waitcnt vmcnt(0)
	s_waitcnt lgkmcnt(0)
	s_setprio 0
	s_barrier
	s_and_saveexec_b64 s[0:1], s[92:93]
	s_cbranch_execz .LBB0_854
	s_add_i32 s2, 0, 0x27ff0
	v_mov_b32_e32 v0, s2
	s_waitcnt vmcnt(0) expcnt(0) lgkmcnt(0)
	ds_read_b32 v2, v0
	s_add_i32 s2, 0, 0x27ff4
	v_mov_b32_e32 v0, s2
	ds_read_b32 v0, v0
	s_waitcnt lgkmcnt(1)
	v_cmp_ne_u32_e32 vcc, 0, v2
	s_cbranch_vccnz .LBB0_818
	s_add_u32 s2, s30, 0x38200
	s_addc_u32 s3, s31, 0
	s_add_u32 s4, s30, 0x38400
	s_addc_u32 s5, s31, 0
	s_add_u32 s6, s30, 0x38500
	s_addc_u32 s7, s31, 0
	s_add_u32 s10, s30, 0x38600
	s_addc_u32 s11, s31, 0
	s_add_u32 s12, s30, 0x38700
	s_addc_u32 s13, s31, 0
	s_add_u32 s14, s30, 0x38800
	s_addc_u32 s15, s31, 0
	s_add_u32 s16, s30, 0x38900
	s_addc_u32 s17, s31, 0
	s_add_u32 s18, s30, 0x38a00
	s_addc_u32 s19, s31, 0
	s_add_u32 s20, s30, 0x38b00
	s_addc_u32 s21, s31, 0
	s_add_u32 s22, s30, 0x38c00
	s_addc_u32 s23, s31, 0
	s_add_u32 s24, s30, 0x38d00
	s_addc_u32 s25, s31, 0
	s_add_u32 s26, s30, 0x38e00
	s_addc_u32 s27, s31, 0
	s_add_u32 s34, s30, 0x38f00
	s_addc_u32 s35, s31, 0
	s_add_u32 s40, s30, 0x39000
	s_addc_u32 s41, s31, 0
	s_add_u32 s44, s30, 0x39100
	s_addc_u32 s45, s31, 0
	s_add_u32 s46, s30, 0x39200
	s_addc_u32 s47, s31, 0
	s_mul_i32 s33, s89, s9
	s_add_u32 s48, s30, 0x39300
	s_mul_i32 s33, s33, s88
	s_addc_u32 s49, s31, 0
	s_mov_b32 s60, 1
	v_mov_b32_e32 v16, 0
	s_branch .LBB0_806

.LBB0_861:
	s_waitcnt lgkmcnt(0)
	v_ashrrev_i32_e32 v1, 31, v8
	v_lshrrev_b32_e32 v1, 26, v1
	v_add_u32_e32 v1, v8, v1
	v_ashrrev_i32_e32 v9, 6, v1
	v_bfe_i32 v1, v8, 27, 1
	v_lshlrev_b32_e32 v0, 4, v8
	v_lshrrev_b32_e32 v1, 22, v1
	v_add_u32_e32 v1, v0, v1
	v_and_b32_e32 v1, 0xfffffc00, v1
	v_sub_u32_e32 v1, v0, v1
	v_lshrrev_b32_e32 v2, 4, v1
	v_bitop3_b32 v1, v2, v1, 32 bitop3:0x6c
	v_ashrrev_i32_e32 v3, 31, v1
	v_lshrrev_b32_e32 v3, 26, v3
	v_add_u32_e32 v3, v1, v3
	v_lshlrev_b32_e32 v2, 3, v9
	v_ashrrev_i32_e32 v10, 6, v3
	v_and_b32_e32 v3, 0xc0, v3
	v_and_b32_e32 v2, -16, v2
	v_sub_u32_e32 v1, v1, v3
	v_mov_b32_e32 v3, 1
	v_add_u32_e32 v2, v10, v2
	v_ashrrev_i16_sdwa v1, v3, sext(v1) dst_sel:DWORD dst_unused:UNUSED_PAD src0_sel:DWORD src1_sel:BYTE_0
	s_ashr_i32 s2, s5, 3
	v_lshlrev_b32_e32 v4, 5, v9
	v_bfe_i32 v11, v1, 0, 16
	v_lshlrev_b32_e32 v1, 1, v2
	v_lshrrev_b32_e32 v5, 2, v2
	v_and_b32_e32 v6, 3, v10
	s_mov_b32 s5, 0x1fffe0
	v_and_b32_e32 v4, 32, v4
	v_and_b32_e32 v1, 24, v1
	v_and_b32_e32 v5, 4, v5
	v_and_or_b32 v6, v2, s5, v6
	v_or3_b32 v1, v6, v5, v1
	v_add_lshl_u32 v4, v4, v11, 1
	v_add_u32_e32 v0, 0x2000, v0
	v_lshl_add_u32 v146, v1, 11, v4
	v_ashrrev_i32_e32 v1, 31, v0
	v_lshrrev_b32_e32 v1, 22, v1
	v_add_u32_e32 v1, v0, v1
	v_ashrrev_i32_e32 v12, 10, v1
	v_mul_i32_i24_e32 v1, 0x400, v12
	v_sub_u32_e32 v0, v0, v1
	v_lshrrev_b32_e32 v1, 4, v0
	v_bitop3_b32 v0, v1, v0, 32 bitop3:0x6c
	v_lshl_add_u32 v144, v2, 11, v4
	v_ashrrev_i32_e32 v2, 31, v0
	v_lshrrev_b32_e32 v2, 26, v2
	v_add_u32_e32 v2, v0, v2
	s_add_u32 s40, s30, 0xd00000
	v_lshlrev_b32_e32 v1, 3, v12
	v_ashrrev_i32_e32 v13, 6, v2
	v_and_b32_e32 v2, 0xc0, v2
	s_addc_u32 s41, s31, 0
	v_and_b32_e32 v1, -16, v1
	v_sub_u32_e32 v0, v0, v2
	s_add_i32 s2, s4, s2
	v_add_u32_e32 v1, v13, v1
	v_ashrrev_i16_sdwa v0, v3, sext(v0) dst_sel:DWORD dst_unused:UNUSED_PAD src0_sel:DWORD src1_sel:BYTE_0
	v_and_b32_e32 v3, 3, v13
	s_mul_hi_i32 s4, s2, 0x2e8ba2e9
	v_and_or_b32 v3, v1, s5, v3
	s_lshr_b32 s5, s4, 31
	s_ashr_i32 s4, s4, 5
	s_add_i32 s4, s4, s5
	v_lshlrev_b32_e32 v4, 5, v12
	v_bfe_i32 v14, v0, 0, 16
	v_lshlrev_b32_e32 v0, 1, v1
	v_lshrrev_b32_e32 v2, 2, v1
	s_lshl_b32 s6, s4, 3
	v_and_b32_e32 v4, 32, v4
	v_and_b32_e32 v0, 24, v0
	v_and_b32_e32 v2, 4, v2
	s_sub_i32 s5, 0x42, s6
	s_mulk_i32 s4, 0xb0
	v_or3_b32 v0, v3, v2, v0
	v_add_lshl_u32 v2, v4, v14, 1
	s_min_u32 s7, s5, 8
	s_sub_i32 s11, s2, s4
	v_lshl_add_u32 v148, v1, 11, v2
	s_sext_i32_i16 s2, s11
	v_cvt_f32_ubyte0_e32 v1, s7
	v_lshl_add_u32 v150, v0, 11, v2
	v_cvt_f32_i32_e32 v0, s2
	v_rcp_iflag_f32_e32 v2, v1
	s_ashr_i32 s10, s12, 6
	s_ashr_i32 s2, s2, 30
	s_ashr_i32 s3, s12, 8
	v_mul_f32_e32 v2, v0, v2
	v_trunc_f32_e32 v2, v2
	v_fma_f32 v0, -v2, v1, v0
	v_cvt_i32_f32_e32 v2, v2
	s_lshl_b32 s44, s10, 10
	s_or_b32 s2, s2, 1
	v_cmp_ge_f32_e64 s[4:5], |v0|, v1
	s_and_b64 s[4:5], s[4:5], exec
	s_cselect_b32 s2, s2, 0
	v_readfirstlane_b32 s4, v2
	s_add_i32 s2, s4, s2
	s_mul_i32 s4, s2, s7
	s_sub_i32 s4, s11, s4
	s_sext_i32_i16 s4, s4
	s_add_i32 s22, s6, s4
	s_ashr_i32 s23, s22, 31
	s_bfe_i64 s[6:7], s[2:3], 0x100000
	s_lshl_b64 s[4:5], s[22:23], 19
	s_lshl_b64 s[6:7], s[6:7], 19
	s_add_u32 s26, s40, s6
	s_addc_u32 s27, s41, s7
	s_add_i32 s23, s44, 0
	s_add_i32 m0, s23, 0x10000
	v_mov_b32_e32 v147, 0
	global_load_lds_dwordx4 v146, s[26:27]
	s_add_i32 m0, s23, 0x12000
	s_add_u32 s6, s26, 0x40000
	global_load_lds_dwordx4 v150, s[26:27]
	s_addc_u32 s7, s27, 0
	s_add_i32 m0, s23, 0x14000
	v_mov_b32_e32 v151, v147
	global_load_lds_dwordx4 v146, s[6:7]
	s_add_i32 m0, s23, 0x16000
	s_add_u32 s24, s42, s4
	s_addc_u32 s25, s43, s5
	s_add_i32 s45, s23, 0x2000
	global_load_lds_dwordx4 v150, s[6:7]
	s_mov_b32 m0, s23
	s_add_u32 s4, s24, 0x40000
	global_load_lds_dwordx4 v144, s[24:25]
	s_mov_b32 m0, s45
	s_addc_u32 s5, s25, 0
	s_add_i32 s46, s23, 0x4000
	global_load_lds_dwordx4 v148, s[24:25]
	s_mov_b32 m0, s46
	s_add_i32 s47, s23, 0x6000
	global_load_lds_dwordx4 v144, s[4:5]
	s_mov_b32 m0, s47
	v_mov_b32_e32 v145, v147
	global_load_lds_dwordx4 v148, s[4:5]
	v_mov_b32_e32 v149, v147
	s_cmp_eq_u32 s3, 1
	s_mov_b32 s48, 0
	v_lshl_add_u64 v[6:7], s[26:27], 0, v[146:147]
	v_lshl_add_u64 v[4:5], s[26:27], 0, v[150:151]
	v_lshl_add_u64 v[0:1], s[24:25], 0, v[144:145]
	s_cselect_b64 s[4:5], -1, 0
	s_cmp_lg_u32 s3, 1
	v_lshl_add_u64 v[2:3], s[24:25], 0, v[148:149]
	s_cbranch_scc1 .LBB0_863
	s_barrier
	s_setprio 1

.LBB0_873:
	ds_read_b128 v[104:107], v171
	ds_read_b128 v[108:111], v171 offset:1024
	ds_read_b128 v[112:115], v171 offset:2048
	ds_read_b128 v[116:119], v171 offset:3072
	ds_read_b128 v[160:163], v172
	ds_read_b128 v[164:167], v172 offset:1024
	ds_read_b128 v[178:181], v172 offset:2048
	ds_read_b128 v[182:185], v172 offset:3072
	s_add_u32 s26, s24, 0xfffc0080
	s_addc_u32 s27, s25, -1
	s_cmp_eq_u32 s67, 12
	s_cselect_b32 s35, s17, s27
	s_cselect_b32 s34, s63, s26
	s_cselect_b32 s27, s15, s66
	s_cselect_b32 s26, s64, s65
	v_lshl_add_u64 v[202:203], s[24:25], 0, v[152:153]
	s_add_i32 m0, s23, 0xc000
	ds_read_b128 v[186:189], v173
	ds_read_b128 v[190:193], v173 offset:1024
	ds_read_b128 v[194:197], v173 offset:2048
	ds_read_b128 v[198:201], v173 offset:3072
	ds_read_b128 v[206:209], v173 offset:4096
	ds_read_b128 v[210:213], v173 offset:5120
	ds_read_b128 v[214:217], v173 offset:6144
	ds_read_b128 v[218:221], v173 offset:7168
	global_load_lds_dwordx4 v[202:203], off
	v_lshl_add_u64 v[202:203], s[24:25], 0, v[154:155]
	s_add_i32 m0, s23, 0xe000
	s_nop 0
	global_load_lds_dwordx4 v[202:203], off
	s_waitcnt vmcnt(8)
	s_waitcnt lgkmcnt(0)
	s_barrier
	s_waitcnt lgkmcnt(0)
	v_mfma_f32_16x16x32_f16 v[140:143], v[104:107], v[186:189], v[140:143]
	v_mfma_f32_16x16x32_f16 v[136:139], v[112:115], v[186:189], v[136:139]
	v_mfma_f32_16x16x32_f16 v[124:127], v[104:107], v[194:197], v[124:127]
	v_mfma_f32_16x16x32_f16 v[120:123], v[112:115], v[194:197], v[120:123]
	v_mfma_f32_16x16x32_f16 v[92:95], v[104:107], v[206:209], v[92:95]
	v_mfma_f32_16x16x32_f16 v[88:91], v[112:115], v[206:209], v[88:91]
	v_mfma_f32_16x16x32_f16 v[76:79], v[104:107], v[214:217], v[76:79]
	v_mfma_f32_16x16x32_f16 v[72:75], v[112:115], v[214:217], v[72:75]
	v_mfma_f32_16x16x32_f16 v[140:143], v[108:111], v[190:193], v[140:143]
	v_mfma_f32_16x16x32_f16 v[136:139], v[116:119], v[190:193], v[136:139]
	v_mfma_f32_16x16x32_f16 v[124:127], v[108:111], v[198:201], v[124:127]
	v_mfma_f32_16x16x32_f16 v[120:123], v[116:119], v[198:201], v[120:123]
	v_mfma_f32_16x16x32_f16 v[92:95], v[108:111], v[210:213], v[92:95]
	v_mfma_f32_16x16x32_f16 v[88:91], v[116:119], v[210:213], v[88:91]
	v_mfma_f32_16x16x32_f16 v[76:79], v[108:111], v[218:221], v[76:79]
	v_mfma_f32_16x16x32_f16 v[72:75], v[116:119], v[218:221], v[72:75]
	v_mfma_f32_16x16x32_f16 v[132:135], v[160:163], v[186:189], v[132:135]
	v_mfma_f32_16x16x32_f16 v[128:131], v[178:181], v[186:189], v[128:131]
	v_mfma_f32_16x16x32_f16 v[100:103], v[160:163], v[194:197], v[100:103]
	v_mfma_f32_16x16x32_f16 v[96:99], v[178:181], v[194:197], v[96:99]
	v_mfma_f32_16x16x32_f16 v[84:87], v[160:163], v[206:209], v[84:87]
	v_mfma_f32_16x16x32_f16 v[80:83], v[178:181], v[206:209], v[80:83]
	v_mfma_f32_16x16x32_f16 v[68:71], v[160:163], v[214:217], v[68:71]
	v_mfma_f32_16x16x32_f16 v[64:67], v[178:181], v[214:217], v[64:67]
	v_mfma_f32_16x16x32_f16 v[132:135], v[164:167], v[190:193], v[132:135]
	v_mfma_f32_16x16x32_f16 v[128:131], v[182:185], v[190:193], v[128:131]
	v_mfma_f32_16x16x32_f16 v[100:103], v[164:167], v[198:201], v[100:103]
	v_mfma_f32_16x16x32_f16 v[96:99], v[182:185], v[198:201], v[96:99]
	v_mfma_f32_16x16x32_f16 v[84:87], v[164:167], v[210:213], v[84:87]
	v_mfma_f32_16x16x32_f16 v[80:83], v[182:185], v[210:213], v[80:83]
	v_mfma_f32_16x16x32_f16 v[68:71], v[164:167], v[218:221], v[68:71]
	v_mfma_f32_16x16x32_f16 v[64:67], v[182:185], v[218:221], v[64:67]
	s_barrier
	s_add_i32 s68, s58, s44
	v_lshl_add_u64 v[202:203], s[26:27], 0, v[146:147]
	s_mov_b32 m0, s68
	ds_read_b128 v[186:189], v173 offset:16384
	ds_read_b128 v[190:193], v173 offset:17408
	ds_read_b128 v[194:197], v173 offset:18432
	ds_read_b128 v[198:201], v173 offset:19456
	ds_read_b128 v[206:209], v173 offset:20480
	ds_read_b128 v[210:213], v173 offset:21504
	ds_read_b128 v[214:217], v173 offset:22528
	ds_read_b128 v[218:221], v173 offset:23552
	global_load_lds_dwordx4 v[202:203], off
	s_add_i32 m0, s68, 0x2000
	s_add_u32 s68, s26, 0x40000
	v_lshl_add_u64 v[222:223], s[26:27], 0, v[150:151]
	s_addc_u32 s69, s27, 0
	s_add_i32 s70, s59, s44
	global_load_lds_dwordx4 v[222:223], off
	v_lshl_add_u64 v[224:225], s[68:69], 0, v[146:147]
	s_mov_b32 m0, s70
	v_lshl_add_u64 v[226:227], s[34:35], 0, v[148:149]
	global_load_lds_dwordx4 v[224:225], off
	v_lshl_add_u64 v[224:225], s[68:69], 0, v[150:151]
	s_add_i32 m0, s70, 0x2000
	s_nop 0
	global_load_lds_dwordx4 v[224:225], off
	v_lshl_add_u64 v[224:225], s[34:35], 0, v[144:145]
	s_mov_b32 m0, s23
	s_nop 0
	global_load_lds_dwordx4 v[224:225], off
	s_mov_b32 m0, s45
	s_nop 0
	global_load_lds_dwordx4 v[226:227], off
	s_waitcnt vmcnt(8)
	s_waitcnt lgkmcnt(0)
	s_barrier
	s_waitcnt lgkmcnt(0)
	v_mfma_f32_16x16x32_f16 v[60:63], v[104:107], v[186:189], v[60:63]
	v_mfma_f32_16x16x32_f16 v[56:59], v[112:115], v[186:189], v[56:59]
	v_mfma_f32_16x16x32_f16 v[44:47], v[104:107], v[194:197], v[44:47]
	v_mfma_f32_16x16x32_f16 v[40:43], v[112:115], v[194:197], v[40:43]
	v_mfma_f32_16x16x32_f16 v[28:31], v[104:107], v[206:209], v[28:31]
	v_mfma_f32_16x16x32_f16 v[24:27], v[112:115], v[206:209], v[24:27]
	v_mfma_f32_16x16x32_f16 v[12:15], v[104:107], v[214:217], v[12:15]
	v_mfma_f32_16x16x32_f16 v[8:11], v[112:115], v[214:217], v[8:11]
	v_mfma_f32_16x16x32_f16 v[60:63], v[108:111], v[190:193], v[60:63]
	v_mfma_f32_16x16x32_f16 v[56:59], v[116:119], v[190:193], v[56:59]
	v_mfma_f32_16x16x32_f16 v[44:47], v[108:111], v[198:201], v[44:47]
	v_mfma_f32_16x16x32_f16 v[40:43], v[116:119], v[198:201], v[40:43]
	v_mfma_f32_16x16x32_f16 v[28:31], v[108:111], v[210:213], v[28:31]
	v_mfma_f32_16x16x32_f16 v[24:27], v[116:119], v[210:213], v[24:27]
	v_mfma_f32_16x16x32_f16 v[12:15], v[108:111], v[218:221], v[12:15]
	v_mfma_f32_16x16x32_f16 v[8:11], v[116:119], v[218:221], v[8:11]
	v_mfma_f32_16x16x32_f16 v[52:55], v[160:163], v[186:189], v[52:55]
	v_mfma_f32_16x16x32_f16 v[48:51], v[178:181], v[186:189], v[48:51]
	v_mfma_f32_16x16x32_f16 v[36:39], v[160:163], v[194:197], v[36:39]
	v_mfma_f32_16x16x32_f16 v[32:35], v[178:181], v[194:197], v[32:35]
	v_mfma_f32_16x16x32_f16 v[20:23], v[160:163], v[206:209], v[20:23]
	v_mfma_f32_16x16x32_f16 v[16:19], v[178:181], v[206:209], v[16:19]
	v_mfma_f32_16x16x32_f16 v[4:7], v[160:163], v[214:217], v[4:7]
	v_mfma_f32_16x16x32_f16 v[0:3], v[178:181], v[214:217], v[0:3]
	v_mfma_f32_16x16x32_f16 v[52:55], v[164:167], v[190:193], v[52:55]
	v_mfma_f32_16x16x32_f16 v[48:51], v[182:185], v[190:193], v[48:51]
	v_mfma_f32_16x16x32_f16 v[36:39], v[164:167], v[198:201], v[36:39]
	v_mfma_f32_16x16x32_f16 v[32:35], v[182:185], v[198:201], v[32:35]
	v_mfma_f32_16x16x32_f16 v[20:23], v[164:167], v[210:213], v[20:23]
	v_mfma_f32_16x16x32_f16 v[16:19], v[182:185], v[210:213], v[16:19]
	v_mfma_f32_16x16x32_f16 v[4:7], v[164:167], v[218:221], v[4:7]
	v_mfma_f32_16x16x32_f16 v[0:3], v[182:185], v[218:221], v[0:3]
	s_barrier
	s_add_i32 s68, 0, 0x18000
	s_add_i32 s69, 0, 0x1c000
	v_add_u32_e32 v116, s68, v169
	v_add_u32_e32 v177, s69, v169
	ds_read_b128 v[104:107], v116
	ds_read_b128 v[108:111], v116 offset:1024
	ds_read_b128 v[112:115], v116 offset:2048
	ds_read_b128 v[116:119], v116 offset:3072
	ds_read_b128 v[160:163], v177
	ds_read_b128 v[164:167], v177 offset:1024
	ds_read_b128 v[178:181], v177 offset:2048
	ds_read_b128 v[182:185], v177 offset:3072
	s_add_u32 s34, s34, 0x40000
	s_addc_u32 s35, s35, 0
	s_mov_b32 m0, s46
	v_lshl_add_u64 v[228:229], s[34:35], 0, v[144:145]
	ds_read_b128 v[186:189], v173 offset:32768
	ds_read_b128 v[190:193], v173 offset:33792
	ds_read_b128 v[194:197], v173 offset:34816
	ds_read_b128 v[198:201], v173 offset:35840
	ds_read_b128 v[206:209], v173 offset:36864
	ds_read_b128 v[210:213], v173 offset:37888
	ds_read_b128 v[214:217], v173 offset:38912
	ds_read_b128 v[218:221], v173 offset:39936
	global_load_lds_dwordx4 v[228:229], off
	v_lshl_add_u64 v[228:229], s[34:35], 0, v[148:149]
	s_mov_b32 m0, s47
	s_nop 0
	global_load_lds_dwordx4 v[228:229], off
	s_waitcnt vmcnt(8)
	s_waitcnt lgkmcnt(0)
	s_barrier
	s_waitcnt lgkmcnt(0)
	v_mfma_f32_16x16x32_f16 v[140:143], v[104:107], v[186:189], v[140:143]
	v_mfma_f32_16x16x32_f16 v[136:139], v[112:115], v[186:189], v[136:139]
	v_mfma_f32_16x16x32_f16 v[124:127], v[104:107], v[194:197], v[124:127]
	v_mfma_f32_16x16x32_f16 v[120:123], v[112:115], v[194:197], v[120:123]
	v_mfma_f32_16x16x32_f16 v[92:95], v[104:107], v[206:209], v[92:95]
	v_mfma_f32_16x16x32_f16 v[88:91], v[112:115], v[206:209], v[88:91]
	v_mfma_f32_16x16x32_f16 v[76:79], v[104:107], v[214:217], v[76:79]
	v_mfma_f32_16x16x32_f16 v[72:75], v[112:115], v[214:217], v[72:75]
	v_mfma_f32_16x16x32_f16 v[140:143], v[108:111], v[190:193], v[140:143]
	v_mfma_f32_16x16x32_f16 v[136:139], v[116:119], v[190:193], v[136:139]
	v_mfma_f32_16x16x32_f16 v[124:127], v[108:111], v[198:201], v[124:127]
	v_mfma_f32_16x16x32_f16 v[120:123], v[116:119], v[198:201], v[120:123]
	v_mfma_f32_16x16x32_f16 v[92:95], v[108:111], v[210:213], v[92:95]
	v_mfma_f32_16x16x32_f16 v[88:91], v[116:119], v[210:213], v[88:91]
	v_mfma_f32_16x16x32_f16 v[76:79], v[108:111], v[218:221], v[76:79]
	v_mfma_f32_16x16x32_f16 v[72:75], v[116:119], v[218:221], v[72:75]
	v_mfma_f32_16x16x32_f16 v[132:135], v[160:163], v[186:189], v[132:135]
	v_mfma_f32_16x16x32_f16 v[128:131], v[178:181], v[186:189], v[128:131]
	v_mfma_f32_16x16x32_f16 v[100:103], v[160:163], v[194:197], v[100:103]
	v_mfma_f32_16x16x32_f16 v[96:99], v[178:181], v[194:197], v[96:99]
	v_mfma_f32_16x16x32_f16 v[84:87], v[160:163], v[206:209], v[84:87]
	v_mfma_f32_16x16x32_f16 v[80:83], v[178:181], v[206:209], v[80:83]
	v_mfma_f32_16x16x32_f16 v[68:71], v[160:163], v[214:217], v[68:71]
	v_mfma_f32_16x16x32_f16 v[64:67], v[178:181], v[214:217], v[64:67]
	v_mfma_f32_16x16x32_f16 v[132:135], v[164:167], v[190:193], v[132:135]
	v_mfma_f32_16x16x32_f16 v[128:131], v[182:185], v[190:193], v[128:131]
	v_mfma_f32_16x16x32_f16 v[100:103], v[164:167], v[198:201], v[100:103]
	v_mfma_f32_16x16x32_f16 v[96:99], v[182:185], v[198:201], v[96:99]
	v_mfma_f32_16x16x32_f16 v[84:87], v[164:167], v[210:213], v[84:87]
	v_mfma_f32_16x16x32_f16 v[80:83], v[182:185], v[210:213], v[80:83]
	v_mfma_f32_16x16x32_f16 v[68:71], v[164:167], v[218:221], v[68:71]
	v_mfma_f32_16x16x32_f16 v[64:67], v[182:185], v[218:221], v[64:67]
	s_barrier
	s_add_i32 s34, s68, s44
	v_lshl_add_u64 v[202:203], v[202:203], 0, s[10:11]
	s_mov_b32 m0, s34
	ds_read_b128 v[186:189], v173 offset:49152
	ds_read_b128 v[190:193], v173 offset:50176
	ds_read_b128 v[194:197], v173 offset:51200
	ds_read_b128 v[198:201], v173 offset:52224
	ds_read_b128 v[206:209], v173 offset:53248
	ds_read_b128 v[210:213], v173 offset:54272
	ds_read_b128 v[214:217], v173 offset:55296
	ds_read_b128 v[218:221], v173 offset:56320
	global_load_lds_dwordx4 v[202:203], off
	s_add_i32 m0, s34, 0x2000
	s_add_u32 s26, s26, 0x40080
	v_lshl_add_u64 v[202:203], v[222:223], 0, s[10:11]
	s_addc_u32 s27, s27, 0
	s_add_i32 s34, s69, s44
	global_load_lds_dwordx4 v[202:203], off
	v_lshl_add_u64 v[202:203], s[26:27], 0, v[146:147]
	s_mov_b32 m0, s34
	s_nop 0
	global_load_lds_dwordx4 v[202:203], off
	v_lshl_add_u64 v[202:203], s[26:27], 0, v[150:151]
	s_add_i32 m0, s34, 0x2000
	s_nop 0
	global_load_lds_dwordx4 v[202:203], off
	v_lshl_add_u64 v[202:203], v[224:225], 0, s[10:11]
	s_mov_b32 m0, s55
	s_nop 0
	global_load_lds_dwordx4 v[202:203], off
	v_lshl_add_u64 v[202:203], v[226:227], 0, s[10:11]
	s_mov_b32 m0, s56
	s_nop 0
	global_load_lds_dwordx4 v[202:203], off
	s_waitcnt vmcnt(8)
	s_waitcnt lgkmcnt(0)
	s_barrier
	s_waitcnt lgkmcnt(0)
	v_mfma_f32_16x16x32_f16 v[60:63], v[104:107], v[186:189], v[60:63]
	v_mfma_f32_16x16x32_f16 v[56:59], v[112:115], v[186:189], v[56:59]
	v_mfma_f32_16x16x32_f16 v[44:47], v[104:107], v[194:197], v[44:47]
	v_mfma_f32_16x16x32_f16 v[40:43], v[112:115], v[194:197], v[40:43]
	v_mfma_f32_16x16x32_f16 v[28:31], v[104:107], v[206:209], v[28:31]
	v_mfma_f32_16x16x32_f16 v[24:27], v[112:115], v[206:209], v[24:27]
	v_mfma_f32_16x16x32_f16 v[12:15], v[104:107], v[214:217], v[12:15]
	v_mfma_f32_16x16x32_f16 v[8:11], v[112:115], v[214:217], v[8:11]
	v_mfma_f32_16x16x32_f16 v[60:63], v[108:111], v[190:193], v[60:63]
	v_mfma_f32_16x16x32_f16 v[56:59], v[116:119], v[190:193], v[56:59]
	v_mfma_f32_16x16x32_f16 v[44:47], v[108:111], v[198:201], v[44:47]
	v_mfma_f32_16x16x32_f16 v[40:43], v[116:119], v[198:201], v[40:43]
	v_mfma_f32_16x16x32_f16 v[28:31], v[108:111], v[210:213], v[28:31]
	v_mfma_f32_16x16x32_f16 v[24:27], v[116:119], v[210:213], v[24:27]
	v_mfma_f32_16x16x32_f16 v[12:15], v[108:111], v[218:221], v[12:15]
	v_mfma_f32_16x16x32_f16 v[8:11], v[116:119], v[218:221], v[8:11]
	v_mfma_f32_16x16x32_f16 v[52:55], v[160:163], v[186:189], v[52:55]
	v_mfma_f32_16x16x32_f16 v[48:51], v[178:181], v[186:189], v[48:51]
	v_mfma_f32_16x16x32_f16 v[36:39], v[160:163], v[194:197], v[36:39]
	v_mfma_f32_16x16x32_f16 v[32:35], v[178:181], v[194:197], v[32:35]
	v_mfma_f32_16x16x32_f16 v[20:23], v[160:163], v[206:209], v[20:23]
	v_mfma_f32_16x16x32_f16 v[16:19], v[178:181], v[206:209], v[16:19]
	v_mfma_f32_16x16x32_f16 v[4:7], v[160:163], v[214:217], v[4:7]
	v_mfma_f32_16x16x32_f16 v[0:3], v[178:181], v[214:217], v[0:3]
	v_mfma_f32_16x16x32_f16 v[52:55], v[164:167], v[190:193], v[52:55]
	v_mfma_f32_16x16x32_f16 v[48:51], v[182:185], v[190:193], v[48:51]
	v_mfma_f32_16x16x32_f16 v[36:39], v[164:167], v[198:201], v[36:39]
	v_mfma_f32_16x16x32_f16 v[32:35], v[182:185], v[198:201], v[32:35]
	v_mfma_f32_16x16x32_f16 v[20:23], v[164:167], v[210:213], v[20:23]
	v_mfma_f32_16x16x32_f16 v[16:19], v[182:185], v[210:213], v[16:19]
	v_mfma_f32_16x16x32_f16 v[4:7], v[164:167], v[218:221], v[4:7]
	v_mfma_f32_16x16x32_f16 v[0:3], v[182:185], v[218:221], v[0:3]
	s_barrier
	s_add_i32 s67, s67, 2
	s_add_u32 s24, s24, 0x100
	s_addc_u32 s25, s25, 0
	s_add_u32 s65, s65, 0x100
	s_addc_u32 s66, s66, 0
	s_cmp_gt_u32 s67, 13
	s_cbranch_scc0 .LBB0_873
	s_and_b64 vcc, exec, s[12:13]
	s_cbranch_vccz .LBB0_876
	s_barrier

.LBB0_914:
	s_cmp_gt_i32 s91, 12
	s_cselect_b64 s[2:3], -1, 0
	s_and_b64 s[0:1], s[0:1], s[2:3]
	s_andn2_b64 vcc, exec, s[0:1]
	s_cbranch_vccnz .LBB0_968
	s_waitcnt vmcnt(0)
	s_waitcnt lgkmcnt(0)
	s_setprio 0
	s_barrier
	s_and_saveexec_b64 s[0:1], s[92:93]
	s_cbranch_execz .LBB0_967
	s_add_i32 s4, 0, 0x27ff0
	v_mov_b32_e32 v0, s4
	s_waitcnt vmcnt(0) expcnt(0) lgkmcnt(0)
	ds_read_b32 v2, v0
	s_add_i32 s4, 0, 0x27ff4
	v_mov_b32_e32 v0, s4
	ds_read_b32 v0, v0
	s_waitcnt lgkmcnt(1)
	v_cmp_ne_u32_e32 vcc, 0, v2
	s_cbranch_vccnz .LBB0_931
	s_add_u32 s4, s30, 0x38200
	s_addc_u32 s5, s31, 0
	s_add_u32 s6, s30, 0x38400
	s_addc_u32 s7, s31, 0
	s_add_u32 s10, s30, 0x38500
	s_addc_u32 s11, s31, 0
	s_add_u32 s12, s30, 0x38600
	s_addc_u32 s13, s31, 0
	s_add_u32 s14, s30, 0x38700
	s_addc_u32 s15, s31, 0
	s_add_u32 s16, s30, 0x38800
	s_addc_u32 s17, s31, 0
	s_add_u32 s18, s30, 0x38900
	s_addc_u32 s19, s31, 0
	s_add_u32 s20, s30, 0x38a00
	s_addc_u32 s21, s31, 0
	s_add_u32 s22, s30, 0x38b00
	s_addc_u32 s23, s31, 0
	s_add_u32 s24, s30, 0x38c00
	s_addc_u32 s25, s31, 0
	s_add_u32 s26, s30, 0x38d00
	s_addc_u32 s27, s31, 0
	s_add_u32 s34, s30, 0x38e00
	s_addc_u32 s35, s31, 0
	s_add_u32 s40, s30, 0x38f00
	s_addc_u32 s41, s31, 0
	s_add_u32 s44, s30, 0x39000
	s_addc_u32 s45, s31, 0
	s_add_u32 s46, s30, 0x39100
	s_addc_u32 s47, s31, 0
	s_add_u32 s48, s30, 0x39200
	s_addc_u32 s49, s31, 0
	s_mul_i32 s33, s89, s9
	s_add_u32 s54, s30, 0x39300
	s_mul_i32 s33, s33, s88
	s_addc_u32 s55, s31, 0
	s_mov_b32 s62, 1
	v_mov_b32_e32 v16, 0
	s_branch .LBB0_919

.LBB0_977:
.LBB0_978:
	s_waitcnt lgkmcnt(0)
	v_ashrrev_i32_e32 v1, 31, v8
	v_lshrrev_b32_e32 v1, 26, v1
	v_add_u32_e32 v1, v8, v1
	v_ashrrev_i32_e32 v9, 6, v1
	v_bfe_i32 v1, v8, 27, 1
	v_lshlrev_b32_e32 v0, 4, v8
	v_lshrrev_b32_e32 v1, 22, v1
	v_add_u32_e32 v1, v0, v1
	v_and_b32_e32 v1, 0xfffffc00, v1
	v_sub_u32_e32 v1, v0, v1
	v_lshrrev_b32_e32 v2, 4, v1
	v_bitop3_b32 v1, v2, v1, 32 bitop3:0x6c
	v_ashrrev_i32_e32 v3, 31, v1
	v_lshrrev_b32_e32 v3, 26, v3
	v_lshlrev_b32_e32 v2, 3, v9
	v_add_u32_e32 v3, v1, v3
	v_and_b32_e32 v2, -16, v2
	v_ashrrev_i32_e32 v11, 6, v3
	v_and_b32_e32 v3, 0xc0, v3
	v_add_u32_e32 v2, v11, v2
	v_lshlrev_b32_e32 v4, 5, v9
	v_sub_u32_e32 v1, v1, v3
	v_mov_b32_e32 v3, 1
	v_and_b32_e32 v10, 32, v4
	v_ashrrev_i16_sdwa v1, v3, sext(v1) dst_sel:DWORD dst_unused:UNUSED_PAD src0_sel:DWORD src1_sel:BYTE_0
	v_lshlrev_b32_e32 v4, 1, v2
	v_lshrrev_b32_e32 v5, 2, v2
	v_and_b32_e32 v6, 3, v11
	s_mov_b32 s2, 0xffffe0
	v_bfe_i32 v12, v1, 0, 16
	v_and_b32_e32 v4, 24, v4
	v_and_b32_e32 v5, 4, v5
	v_and_or_b32 v6, v2, s2, v6
	s_movk_i32 s1, 0xb00
	v_add_u32_e32 v1, v10, v12
	v_or3_b32 v4, v6, v5, v4
	v_mul_lo_u32 v2, v2, s1
	v_add_lshl_u32 v160, v1, v2, 1
	v_mul_u32_u24_e32 v2, 0xb00, v4
	v_add_u32_e32 v0, 0x2000, v0
	v_add_lshl_u32 v162, v2, v1, 1
	v_ashrrev_i32_e32 v1, 31, v0
	v_lshrrev_b32_e32 v1, 22, v1
	v_add_u32_e32 v1, v0, v1
	v_ashrrev_i32_e32 v13, 10, v1
	v_mul_i32_i24_e32 v1, 0x400, v13
	v_sub_u32_e32 v0, v0, v1
	v_lshrrev_b32_e32 v1, 4, v0
	v_bitop3_b32 v0, v1, v0, 32 bitop3:0x6c
	v_ashrrev_i32_e32 v2, 31, v0
	v_lshrrev_b32_e32 v2, 26, v2
	v_lshlrev_b32_e32 v1, 3, v13
	v_add_u32_e32 v2, v0, v2
	v_and_b32_e32 v1, -16, v1
	v_ashrrev_i32_e32 v14, 6, v2
	v_lshlrev_b32_e32 v4, 5, v13
	s_add_u32 s10, s30, 0x3380000
	v_add_u32_e32 v1, v14, v1
	v_and_b32_e32 v15, 32, v4
	v_and_b32_e32 v4, 3, v14
	s_addc_u32 s11, s31, 0
	v_and_b32_e32 v2, 0xc0, v2
	v_and_or_b32 v4, v1, s2, v4
	s_ashr_i32 s2, s4, 6
	s_ashr_i32 s0, s4, 8
	v_sub_u32_e32 v0, v0, v2
	s_lshl_b32 s33, s2, 10
	s_mul_i32 s13, s64, 0x160000
	v_ashrrev_i16_sdwa v0, v3, sext(v0) dst_sel:DWORD dst_unused:UNUSED_PAD src0_sel:DWORD src1_sel:BYTE_0
	v_lshlrev_b32_e32 v2, 1, v1
	v_lshrrev_b32_e32 v3, 2, v1
	s_mul_hi_i32 s12, s64, 0x160000
	s_add_u32 s24, s10, s13
	v_bfe_i32 v16, v0, 0, 16
	v_and_b32_e32 v2, 24, v2
	v_and_b32_e32 v3, 4, v3
	s_addc_u32 s25, s11, s12
	s_add_i32 s40, s33, 0
	v_add_u32_e32 v0, v15, v16
	v_or3_b32 v2, v4, v3, v2
	v_mul_lo_u32 v1, v1, s1
	s_add_i32 m0, s40, 0x10000
	v_add_lshl_u32 v164, v0, v1, 1
	v_mul_u32_u24_e32 v1, 0xb00, v2
	global_load_lds_dwordx4 v162, s[24:25]
	s_add_i32 m0, s40, 0x12000
	v_add_lshl_u32 v166, v1, v0, 1
	s_add_u32 s12, s24, 0xb0000
	global_load_lds_dwordx4 v166, s[24:25]
	s_addc_u32 s13, s25, 0
	s_add_i32 m0, s40, 0x14000
	s_mul_i32 s5, s63, 0x160000
	global_load_lds_dwordx4 v162, s[12:13]
	s_add_i32 m0, s40, 0x16000
	s_mul_hi_i32 s3, s63, 0x160000
	s_add_u32 s22, s36, s5
	s_addc_u32 s23, s37, s3
	s_add_i32 s41, s40, 0x2000
	global_load_lds_dwordx4 v166, s[12:13]
	s_mov_b32 m0, s40
	s_add_u32 s12, s22, 0xb0000
	global_load_lds_dwordx4 v160, s[22:23]
	s_mov_b32 m0, s41
	s_addc_u32 s13, s23, 0
	s_add_i32 s44, s40, 0x4000
	global_load_lds_dwordx4 v164, s[22:23]
	s_mov_b32 m0, s44
	s_add_i32 s45, s40, 0x6000
	global_load_lds_dwordx4 v160, s[12:13]
	s_mov_b32 m0, s45
	v_mov_b32_e32 v163, 0
	global_load_lds_dwordx4 v164, s[12:13]
	v_mov_b32_e32 v167, v163
	v_mov_b32_e32 v161, v163
	v_mov_b32_e32 v165, v163
	s_cmp_eq_u32 s0, 1
	s_mov_b32 s46, 0
	v_lshl_add_u64 v[6:7], s[24:25], 0, v[162:163]
	v_lshl_add_u64 v[4:5], s[24:25], 0, v[166:167]
	v_lshl_add_u64 v[0:1], s[22:23], 0, v[160:161]
	s_cselect_b64 s[14:15], -1, 0
	s_cmp_lg_u32 s0, 1
	v_lshl_add_u64 v[2:3], s[22:23], 0, v[164:165]
	s_cbranch_scc1 .LBB0_980
	s_barrier
	s_setprio 1

.LBB0_1045:
	s_cmp_lt_i32 s91, 14
	s_cselect_b64 s[0:1], -1, 0
	s_xor_b64 s[2:3], s[6:7], -1
	s_or_b64 s[0:1], s[2:3], s[0:1]
	s_and_b64 vcc, exec, s[0:1]
	s_cbranch_vccnz .LBB0_1099
	s_waitcnt vmcnt(0)
	s_waitcnt lgkmcnt(0)
	s_setprio 0
	s_barrier
	s_and_saveexec_b64 s[0:1], s[92:93]
	s_cbranch_execz .LBB0_1098
	s_add_i32 s2, 0, 0x27ff0
	v_mov_b32_e32 v0, s2
	s_waitcnt vmcnt(0) expcnt(0) lgkmcnt(0)
	ds_read_b32 v2, v0
	s_add_i32 s2, 0, 0x27ff4
	v_mov_b32_e32 v0, s2
	ds_read_b32 v0, v0
	s_waitcnt lgkmcnt(1)
	v_cmp_ne_u32_e32 vcc, 0, v2
	s_cbranch_vccnz .LBB0_1062
	s_add_u32 s2, s30, 0x38200
	s_addc_u32 s3, s31, 0
	s_add_u32 s4, s30, 0x38400
	s_addc_u32 s5, s31, 0
	s_add_u32 s6, s30, 0x38500
	s_addc_u32 s7, s31, 0
	s_add_u32 s10, s30, 0x38600
	s_addc_u32 s11, s31, 0
	s_add_u32 s12, s30, 0x38700
	s_addc_u32 s13, s31, 0
	s_add_u32 s14, s30, 0x38800
	s_addc_u32 s15, s31, 0
	s_add_u32 s16, s30, 0x38900
	s_addc_u32 s17, s31, 0
	s_add_u32 s18, s30, 0x38a00
	s_addc_u32 s19, s31, 0
	s_add_u32 s20, s30, 0x38b00
	s_addc_u32 s21, s31, 0
	s_add_u32 s22, s30, 0x38c00
	s_addc_u32 s23, s31, 0
	s_add_u32 s24, s30, 0x38d00
	s_addc_u32 s25, s31, 0
	s_add_u32 s26, s30, 0x38e00
	s_addc_u32 s27, s31, 0
	s_add_u32 s34, s30, 0x38f00
	s_addc_u32 s35, s31, 0
	s_add_u32 s40, s30, 0x39000
	s_addc_u32 s41, s31, 0
	s_add_u32 s44, s30, 0x39100
	s_addc_u32 s45, s31, 0
	s_add_u32 s46, s30, 0x39200
	s_addc_u32 s47, s31, 0
	s_mul_i32 s33, s89, s9
	s_add_u32 s48, s30, 0x39300
	s_mul_i32 s33, s33, s88
	s_addc_u32 s49, s31, 0
	s_mov_b32 s60, 1
	v_mov_b32_e32 v16, 0
	s_branch .LBB0_1050

.LBB0_1105:
	s_waitcnt lgkmcnt(0)
	v_ashrrev_i32_e32 v1, 31, v8
	v_lshrrev_b32_e32 v1, 26, v1
	v_add_u32_e32 v1, v8, v1
	v_ashrrev_i32_e32 v9, 6, v1
	v_bfe_i32 v1, v8, 27, 1
	v_lshlrev_b32_e32 v0, 4, v8
	v_lshrrev_b32_e32 v1, 22, v1
	v_add_u32_e32 v1, v0, v1
	v_and_b32_e32 v1, 0xfffffc00, v1
	v_sub_u32_e32 v1, v0, v1
	v_lshrrev_b32_e32 v2, 4, v1
	v_bitop3_b32 v1, v2, v1, 32 bitop3:0x6c
	v_ashrrev_i32_e32 v3, 31, v1
	v_lshrrev_b32_e32 v3, 26, v3
	v_add_u32_e32 v3, v1, v3
	v_lshlrev_b32_e32 v2, 3, v9
	v_ashrrev_i32_e32 v10, 6, v3
	v_and_b32_e32 v3, 0xc0, v3
	v_and_b32_e32 v2, -16, v2
	v_sub_u32_e32 v1, v1, v3
	v_mov_b32_e32 v3, 1
	v_add_u32_e32 v2, v10, v2
	v_ashrrev_i16_sdwa v1, v3, sext(v1) dst_sel:DWORD dst_unused:UNUSED_PAD src0_sel:DWORD src1_sel:BYTE_0
	s_ashr_i32 s2, s5, 3
	v_lshlrev_b32_e32 v4, 5, v9
	v_bfe_i32 v11, v1, 0, 16
	v_lshlrev_b32_e32 v1, 1, v2
	v_lshrrev_b32_e32 v5, 2, v2
	v_and_b32_e32 v6, 3, v10
	s_mov_b32 s5, 0x1fffe0
	v_and_b32_e32 v4, 32, v4
	v_and_b32_e32 v1, 24, v1
	v_and_b32_e32 v5, 4, v5
	v_and_or_b32 v6, v2, s5, v6
	v_or3_b32 v1, v6, v5, v1
	v_add_lshl_u32 v4, v4, v11, 1
	v_add_u32_e32 v0, 0x2000, v0
	v_lshl_add_u32 v146, v1, 11, v4
	v_ashrrev_i32_e32 v1, 31, v0
	v_lshrrev_b32_e32 v1, 22, v1
	v_add_u32_e32 v1, v0, v1
	v_ashrrev_i32_e32 v12, 10, v1
	v_mul_i32_i24_e32 v1, 0x400, v12
	v_sub_u32_e32 v0, v0, v1
	v_lshrrev_b32_e32 v1, 4, v0
	v_bitop3_b32 v0, v1, v0, 32 bitop3:0x6c
	v_lshl_add_u32 v144, v2, 11, v4
	v_ashrrev_i32_e32 v2, 31, v0
	v_lshrrev_b32_e32 v2, 26, v2
	v_add_u32_e32 v2, v0, v2
	s_add_u32 s40, s30, 0x1800000
	v_lshlrev_b32_e32 v1, 3, v12
	v_ashrrev_i32_e32 v13, 6, v2
	v_and_b32_e32 v2, 0xc0, v2
	s_addc_u32 s41, s31, 0
	v_and_b32_e32 v1, -16, v1
	v_sub_u32_e32 v0, v0, v2
	s_add_i32 s2, s4, s2
	v_add_u32_e32 v1, v13, v1
	v_ashrrev_i16_sdwa v0, v3, sext(v0) dst_sel:DWORD dst_unused:UNUSED_PAD src0_sel:DWORD src1_sel:BYTE_0
	v_and_b32_e32 v3, 3, v13
	s_mul_hi_i32 s4, s2, 0x2e8ba2e9
	v_and_or_b32 v3, v1, s5, v3
	s_lshr_b32 s5, s4, 31
	s_ashr_i32 s4, s4, 5
	s_add_i32 s4, s4, s5
	v_lshlrev_b32_e32 v4, 5, v12
	v_bfe_i32 v14, v0, 0, 16
	v_lshlrev_b32_e32 v0, 1, v1
	v_lshrrev_b32_e32 v2, 2, v1
	s_lshl_b32 s6, s4, 3
	v_and_b32_e32 v4, 32, v4
	v_and_b32_e32 v0, 24, v0
	v_and_b32_e32 v2, 4, v2
	s_sub_i32 s5, 0x42, s6
	s_mulk_i32 s4, 0xb0
	v_or3_b32 v0, v3, v2, v0
	v_add_lshl_u32 v2, v4, v14, 1
	s_min_u32 s7, s5, 8
	s_sub_i32 s11, s2, s4
	v_lshl_add_u32 v148, v1, 11, v2
	s_sext_i32_i16 s2, s11
	v_cvt_f32_ubyte0_e32 v1, s7
	v_lshl_add_u32 v150, v0, 11, v2
	v_cvt_f32_i32_e32 v0, s2
	v_rcp_iflag_f32_e32 v2, v1
	s_ashr_i32 s10, s12, 6
	s_ashr_i32 s2, s2, 30
	s_ashr_i32 s3, s12, 8
	v_mul_f32_e32 v2, v0, v2
	v_trunc_f32_e32 v2, v2
	v_fma_f32 v0, -v2, v1, v0
	v_cvt_i32_f32_e32 v2, v2
	s_lshl_b32 s44, s10, 10
	s_or_b32 s2, s2, 1
	v_cmp_ge_f32_e64 s[4:5], |v0|, v1
	s_and_b64 s[4:5], s[4:5], exec
	s_cselect_b32 s2, s2, 0
	v_readfirstlane_b32 s4, v2
	s_add_i32 s2, s4, s2
	s_mul_i32 s4, s2, s7
	s_sub_i32 s4, s11, s4
	s_sext_i32_i16 s4, s4
	s_add_i32 s22, s6, s4
	s_ashr_i32 s23, s22, 31
	s_bfe_i64 s[6:7], s[2:3], 0x100000
	s_lshl_b64 s[4:5], s[22:23], 19
	s_lshl_b64 s[6:7], s[6:7], 19
	s_add_u32 s26, s40, s6
	s_addc_u32 s27, s41, s7
	s_add_i32 s23, s44, 0
	s_add_i32 m0, s23, 0x10000
	v_mov_b32_e32 v147, 0
	global_load_lds_dwordx4 v146, s[26:27]
	s_add_i32 m0, s23, 0x12000
	s_add_u32 s6, s26, 0x40000
	global_load_lds_dwordx4 v150, s[26:27]
	s_addc_u32 s7, s27, 0
	s_add_i32 m0, s23, 0x14000
	v_mov_b32_e32 v151, v147
	global_load_lds_dwordx4 v146, s[6:7]
	s_add_i32 m0, s23, 0x16000
	s_add_u32 s24, s42, s4
	s_addc_u32 s25, s43, s5
	s_add_i32 s45, s23, 0x2000
	global_load_lds_dwordx4 v150, s[6:7]
	s_mov_b32 m0, s23
	s_add_u32 s4, s24, 0x40000
	global_load_lds_dwordx4 v144, s[24:25]
	s_mov_b32 m0, s45
	s_addc_u32 s5, s25, 0
	s_add_i32 s46, s23, 0x4000
	global_load_lds_dwordx4 v148, s[24:25]
	s_mov_b32 m0, s46
	s_add_i32 s47, s23, 0x6000
	global_load_lds_dwordx4 v144, s[4:5]
	s_mov_b32 m0, s47
	v_mov_b32_e32 v145, v147
	global_load_lds_dwordx4 v148, s[4:5]
	v_mov_b32_e32 v149, v147
	s_cmp_eq_u32 s3, 1
	s_mov_b32 s48, 0
	v_lshl_add_u64 v[6:7], s[26:27], 0, v[146:147]
	v_lshl_add_u64 v[4:5], s[26:27], 0, v[150:151]
	v_lshl_add_u64 v[0:1], s[24:25], 0, v[144:145]
	s_cselect_b64 s[4:5], -1, 0
	s_cmp_lg_u32 s3, 1
	v_lshl_add_u64 v[2:3], s[24:25], 0, v[148:149]
	s_cbranch_scc1 .LBB0_1107
	s_barrier
	s_setprio 1

.LBB0_1142:
	s_cmp_gt_i32 s91, 15
	s_cselect_b64 s[2:3], -1, 0
	s_and_b64 s[0:1], s[0:1], s[2:3]
	v_readlane_b32 s44, v240, 1
	s_andn2_b64 vcc, exec, s[0:1]
	v_readlane_b32 s52, v240, 9
	v_readlane_b32 s53, v240, 10
	v_readlane_b32 s54, v240, 11
	v_readlane_b32 s55, v240, 12
	v_readlane_b32 s56, v240, 13
	v_readlane_b32 s57, v240, 14
	v_readlane_b32 s45, v240, 2
	v_readlane_b32 s46, v240, 3
	v_readlane_b32 s47, v240, 4
	v_readlane_b32 s48, v240, 5
	v_readlane_b32 s49, v240, 6
	v_readlane_b32 s50, v240, 7
	v_readlane_b32 s51, v240, 8
	v_readlane_b32 s58, v240, 15
	v_readlane_b32 s59, v240, 16
	s_cbranch_vccnz .LBB0_1196
	s_waitcnt vmcnt(0)
	s_waitcnt lgkmcnt(0)
	s_setprio 0
	s_barrier
	s_and_saveexec_b64 s[0:1], s[92:93]
	s_cbranch_execz .LBB0_1195
	s_add_i32 s4, 0, 0x27ff0
	v_mov_b32_e32 v0, s4
	s_waitcnt vmcnt(0) expcnt(0) lgkmcnt(0)
	ds_read_b32 v2, v0
	s_add_i32 s4, 0, 0x27ff4
	v_mov_b32_e32 v0, s4
	ds_read_b32 v0, v0
	s_waitcnt lgkmcnt(1)
	v_cmp_ne_u32_e32 vcc, 0, v2
	s_cbranch_vccnz .LBB0_1159
	s_add_u32 s4, s30, 0x38200
	s_addc_u32 s5, s31, 0
	s_add_u32 s6, s30, 0x38400
	s_addc_u32 s7, s31, 0
	s_add_u32 s10, s30, 0x38500
	s_addc_u32 s11, s31, 0
	s_add_u32 s12, s30, 0x38600
	s_addc_u32 s13, s31, 0
	s_add_u32 s14, s30, 0x38700
	s_addc_u32 s15, s31, 0
	s_add_u32 s16, s30, 0x38800
	s_addc_u32 s17, s31, 0
	s_add_u32 s18, s30, 0x38900
	s_addc_u32 s19, s31, 0
	s_add_u32 s20, s30, 0x38a00
	s_addc_u32 s21, s31, 0
	s_add_u32 s22, s30, 0x38b00
	s_addc_u32 s23, s31, 0
	s_add_u32 s24, s30, 0x38c00
	s_addc_u32 s25, s31, 0
	s_add_u32 s26, s30, 0x38d00
	s_addc_u32 s27, s31, 0
	s_add_u32 s34, s30, 0x38e00
	s_addc_u32 s35, s31, 0
	s_add_u32 s40, s30, 0x38f00
	s_addc_u32 s41, s31, 0
	s_add_u32 s44, s30, 0x39000
	s_addc_u32 s45, s31, 0
	s_add_u32 s46, s30, 0x39100
	s_addc_u32 s47, s31, 0
	s_add_u32 s48, s30, 0x39200
	s_addc_u32 s49, s31, 0
	s_mul_i32 s33, s89, s9
	s_add_u32 s50, s30, 0x39300
	s_mul_i32 s33, s33, s88
	s_addc_u32 s51, s31, 0
	s_mov_b32 s58, 1
	v_mov_b32_e32 v16, 0
	s_branch .LBB0_1147

.LBB0_1203:
	s_andn2_b64 vcc, exec, s[0:1]
	s_cbranch_vccnz .LBB0_1246
	s_waitcnt lgkmcnt(0)
	v_ashrrev_i32_e32 v1, 31, v8
	v_lshrrev_b32_e32 v1, 26, v1
	v_add_u32_e32 v1, v8, v1
	v_ashrrev_i32_e32 v9, 6, v1
	v_bfe_i32 v1, v8, 27, 1
	v_lshlrev_b32_e32 v0, 4, v8
	v_lshrrev_b32_e32 v1, 22, v1
	v_add_u32_e32 v1, v0, v1
	v_and_b32_e32 v1, 0xfffffc00, v1
	v_sub_u32_e32 v1, v0, v1
	v_lshrrev_b32_e32 v2, 4, v1
	v_bitop3_b32 v1, v2, v1, 32 bitop3:0x6c
	v_ashrrev_i32_e32 v3, 31, v1
	v_lshrrev_b32_e32 v3, 26, v3
	v_lshlrev_b32_e32 v2, 3, v9
	v_add_u32_e32 v3, v1, v3
	v_and_b32_e32 v2, -16, v2
	v_ashrrev_i32_e32 v11, 6, v3
	v_and_b32_e32 v3, 0xc0, v3
	v_add_u32_e32 v2, v11, v2
	v_lshlrev_b32_e32 v4, 5, v9
	v_sub_u32_e32 v1, v1, v3
	v_mov_b32_e32 v3, 1
	v_and_b32_e32 v10, 32, v4
	v_ashrrev_i16_sdwa v1, v3, sext(v1) dst_sel:DWORD dst_unused:UNUSED_PAD src0_sel:DWORD src1_sel:BYTE_0
	v_lshlrev_b32_e32 v4, 1, v2
	v_lshrrev_b32_e32 v5, 2, v2
	v_and_b32_e32 v6, 3, v11
	s_mov_b32 s2, 0xffffe0
	v_bfe_i32 v12, v1, 0, 16
	v_and_b32_e32 v4, 24, v4
	v_and_b32_e32 v5, 4, v5
	v_and_or_b32 v6, v2, s2, v6
	s_movk_i32 s1, 0xb00
	v_add_u32_e32 v1, v10, v12
	v_or3_b32 v4, v6, v5, v4
	v_mul_lo_u32 v2, v2, s1
	v_add_lshl_u32 v160, v1, v2, 1
	v_mul_u32_u24_e32 v2, 0xb00, v4
	v_add_u32_e32 v0, 0x2000, v0
	v_add_lshl_u32 v162, v2, v1, 1
	v_ashrrev_i32_e32 v1, 31, v0
	v_lshrrev_b32_e32 v1, 22, v1
	v_add_u32_e32 v1, v0, v1
	v_ashrrev_i32_e32 v13, 10, v1
	v_mul_i32_i24_e32 v1, 0x400, v13
	v_sub_u32_e32 v0, v0, v1
	v_lshrrev_b32_e32 v1, 4, v0
	v_bitop3_b32 v0, v1, v0, 32 bitop3:0x6c
	v_ashrrev_i32_e32 v2, 31, v0
	v_lshrrev_b32_e32 v2, 26, v2
	v_lshlrev_b32_e32 v1, 3, v13
	v_add_u32_e32 v2, v0, v2
	v_and_b32_e32 v1, -16, v1
	v_ashrrev_i32_e32 v14, 6, v2
	v_lshlrev_b32_e32 v4, 5, v13
	s_add_u32 s10, s30, 0x3900000
	v_add_u32_e32 v1, v14, v1
	v_and_b32_e32 v15, 32, v4
	v_and_b32_e32 v4, 3, v14
	s_addc_u32 s11, s31, 0
	v_and_b32_e32 v2, 0xc0, v2
	v_and_or_b32 v4, v1, s2, v4
	s_ashr_i32 s2, s4, 6
	s_ashr_i32 s0, s4, 8
	v_sub_u32_e32 v0, v0, v2
	s_lshl_b32 s33, s2, 10
	s_mul_i32 s13, s60, 0x160000
	v_ashrrev_i16_sdwa v0, v3, sext(v0) dst_sel:DWORD dst_unused:UNUSED_PAD src0_sel:DWORD src1_sel:BYTE_0
	v_lshlrev_b32_e32 v2, 1, v1
	v_lshrrev_b32_e32 v3, 2, v1
	s_mul_hi_i32 s12, s60, 0x160000
	s_add_u32 s24, s10, s13
	v_bfe_i32 v16, v0, 0, 16
	v_and_b32_e32 v2, 24, v2
	v_and_b32_e32 v3, 4, v3
	s_addc_u32 s25, s11, s12
	s_add_i32 s40, s33, 0
	v_add_u32_e32 v0, v15, v16
	v_or3_b32 v2, v4, v3, v2
	v_mul_lo_u32 v1, v1, s1
	s_add_i32 m0, s40, 0x10000
	v_add_lshl_u32 v164, v0, v1, 1
	v_mul_u32_u24_e32 v1, 0xb00, v2
	global_load_lds_dwordx4 v162, s[24:25]
	s_add_i32 m0, s40, 0x12000
	v_add_lshl_u32 v166, v1, v0, 1
	s_add_u32 s12, s24, 0xb0000
	global_load_lds_dwordx4 v166, s[24:25]
	s_addc_u32 s13, s25, 0
	s_add_i32 m0, s40, 0x14000
	s_mul_i32 s5, s59, 0x160000
	global_load_lds_dwordx4 v162, s[12:13]
	s_add_i32 m0, s40, 0x16000
	s_mul_hi_i32 s3, s59, 0x160000
	s_add_u32 s22, s36, s5
	s_addc_u32 s23, s37, s3
	s_add_i32 s41, s40, 0x2000
	global_load_lds_dwordx4 v166, s[12:13]
	s_mov_b32 m0, s40
	s_add_u32 s12, s22, 0xb0000
	global_load_lds_dwordx4 v160, s[22:23]
	s_mov_b32 m0, s41
	s_addc_u32 s13, s23, 0
	s_add_i32 s44, s40, 0x4000
	global_load_lds_dwordx4 v164, s[22:23]
	s_mov_b32 m0, s44
	s_add_i32 s45, s40, 0x6000
	global_load_lds_dwordx4 v160, s[12:13]
	s_mov_b32 m0, s45
	v_mov_b32_e32 v163, 0
	global_load_lds_dwordx4 v164, s[12:13]
	v_mov_b32_e32 v167, v163
	v_mov_b32_e32 v161, v163
	v_mov_b32_e32 v165, v163
	s_cmp_eq_u32 s0, 1
	s_mov_b32 s46, 0
	v_lshl_add_u64 v[6:7], s[24:25], 0, v[162:163]
	v_lshl_add_u64 v[4:5], s[24:25], 0, v[166:167]
	v_lshl_add_u64 v[0:1], s[22:23], 0, v[160:161]
	s_cselect_b64 s[14:15], -1, 0
	s_cmp_lg_u32 s0, 1
	v_lshl_add_u64 v[2:3], s[22:23], 0, v[164:165]
	s_cbranch_scc1 .LBB0_1206
	s_barrier
	s_setprio 1

.LBB0_1220:
	ds_read_b128 v[80:83], v208
	ds_read_b128 v[84:87], v208 offset:1024
	ds_read_b128 v[92:95], v208 offset:2048
	ds_read_b128 v[96:99], v208 offset:3072
	ds_read_b128 v[144:147], v209
	ds_read_b128 v[148:151], v209 offset:1024
	ds_read_b128 v[152:155], v209 offset:2048
	ds_read_b128 v[156:159], v209 offset:3072
	s_add_u32 s24, s22, 0x100
	s_addc_u32 s25, s23, 0
	s_cmp_eq_u32 s63, 40
	s_cselect_b32 s35, s1, s25
	s_cselect_b32 s34, s0, s24
	s_cselect_b32 s27, s21, s62
	s_cselect_b32 s26, s20, s61
	v_lshl_add_u64 v[202:203], s[22:23], 0, v[168:169]
	s_add_i32 m0, s40, 0xc000
	ds_read_b128 v[178:181], v210
	ds_read_b128 v[182:185], v210 offset:1024
	ds_read_b128 v[186:189], v210 offset:2048
	ds_read_b128 v[190:193], v210 offset:3072
	ds_read_b128 v[194:197], v210 offset:4096
	ds_read_b128 v[198:201], v210 offset:5120
	ds_read_b128 v[212:215], v210 offset:6144
	ds_read_b128 v[216:219], v210 offset:7168
	global_load_lds_dwordx4 v[202:203], off
	v_lshl_add_u64 v[202:203], s[22:23], 0, v[170:171]
	s_add_i32 m0, s40, 0xe000
	s_nop 0
	global_load_lds_dwordx4 v[202:203], off
	s_waitcnt vmcnt(8)
	s_waitcnt lgkmcnt(0)
	s_barrier
	s_waitcnt lgkmcnt(0)
	v_mfma_f32_16x16x32_f16 v[140:143], v[80:83], v[178:181], v[140:143]
	v_mfma_f32_16x16x32_f16 v[136:139], v[92:95], v[178:181], v[136:139]
	v_mfma_f32_16x16x32_f16 v[124:127], v[80:83], v[186:189], v[124:127]
	v_mfma_f32_16x16x32_f16 v[120:123], v[92:95], v[186:189], v[120:123]
	v_mfma_f32_16x16x32_f16 v[108:111], v[80:83], v[194:197], v[108:111]
	v_mfma_f32_16x16x32_f16 v[104:107], v[92:95], v[194:197], v[104:107]
	v_mfma_f32_16x16x32_f16 v[76:79], v[80:83], v[212:215], v[76:79]
	v_mfma_f32_16x16x32_f16 v[72:75], v[92:95], v[212:215], v[72:75]
	v_mfma_f32_16x16x32_f16 v[140:143], v[84:87], v[182:185], v[140:143]
	v_mfma_f32_16x16x32_f16 v[136:139], v[96:99], v[182:185], v[136:139]
	v_mfma_f32_16x16x32_f16 v[124:127], v[84:87], v[190:193], v[124:127]
	v_mfma_f32_16x16x32_f16 v[120:123], v[96:99], v[190:193], v[120:123]
	v_mfma_f32_16x16x32_f16 v[108:111], v[84:87], v[198:201], v[108:111]
	v_mfma_f32_16x16x32_f16 v[104:107], v[96:99], v[198:201], v[104:107]
	v_mfma_f32_16x16x32_f16 v[76:79], v[84:87], v[216:219], v[76:79]
	v_mfma_f32_16x16x32_f16 v[72:75], v[96:99], v[216:219], v[72:75]
	v_mfma_f32_16x16x32_f16 v[132:135], v[144:147], v[178:181], v[132:135]
	v_mfma_f32_16x16x32_f16 v[128:131], v[152:155], v[178:181], v[128:131]
	v_mfma_f32_16x16x32_f16 v[116:119], v[144:147], v[186:189], v[116:119]
	v_mfma_f32_16x16x32_f16 v[112:115], v[152:155], v[186:189], v[112:115]
	v_mfma_f32_16x16x32_f16 v[100:103], v[144:147], v[194:197], v[100:103]
	v_mfma_f32_16x16x32_f16 v[88:91], v[152:155], v[194:197], v[88:91]
	v_mfma_f32_16x16x32_f16 v[68:71], v[144:147], v[212:215], v[68:71]
	v_mfma_f32_16x16x32_f16 v[64:67], v[152:155], v[212:215], v[64:67]
	v_mfma_f32_16x16x32_f16 v[132:135], v[148:151], v[182:185], v[132:135]
	v_mfma_f32_16x16x32_f16 v[128:131], v[156:159], v[182:185], v[128:131]
	v_mfma_f32_16x16x32_f16 v[116:119], v[148:151], v[190:193], v[116:119]
	v_mfma_f32_16x16x32_f16 v[112:115], v[156:159], v[190:193], v[112:115]
	v_mfma_f32_16x16x32_f16 v[100:103], v[148:151], v[198:201], v[100:103]
	v_mfma_f32_16x16x32_f16 v[88:91], v[156:159], v[198:201], v[88:91]
	v_mfma_f32_16x16x32_f16 v[68:71], v[148:151], v[216:219], v[68:71]
	v_mfma_f32_16x16x32_f16 v[64:67], v[156:159], v[216:219], v[64:67]
	s_barrier
	s_add_i32 s22, s55, s33
	v_lshl_add_u64 v[202:203], s[26:27], 0, v[162:163]
	s_mov_b32 m0, s22
	ds_read_b128 v[178:181], v210 offset:16384
	ds_read_b128 v[182:185], v210 offset:17408
	ds_read_b128 v[186:189], v210 offset:18432
	ds_read_b128 v[190:193], v210 offset:19456
	ds_read_b128 v[194:197], v210 offset:20480
	ds_read_b128 v[198:201], v210 offset:21504
	ds_read_b128 v[212:215], v210 offset:22528
	ds_read_b128 v[216:219], v210 offset:23552
	global_load_lds_dwordx4 v[202:203], off
	s_add_i32 m0, s22, 0x2000
	s_add_u32 s22, s26, 0xb0000
	v_lshl_add_u64 v[220:221], s[26:27], 0, v[166:167]
	s_addc_u32 s23, s27, 0
	s_add_i32 s64, s56, s33
	global_load_lds_dwordx4 v[220:221], off
	v_lshl_add_u64 v[222:223], s[22:23], 0, v[162:163]
	s_mov_b32 m0, s64
	v_lshl_add_u64 v[224:225], s[34:35], 0, v[164:165]
	global_load_lds_dwordx4 v[222:223], off
	v_lshl_add_u64 v[222:223], s[22:23], 0, v[166:167]
	s_add_i32 m0, s64, 0x2000
	s_nop 0
	global_load_lds_dwordx4 v[222:223], off
	v_lshl_add_u64 v[222:223], s[34:35], 0, v[160:161]
	s_mov_b32 m0, s40
	s_nop 0
	global_load_lds_dwordx4 v[222:223], off
	s_mov_b32 m0, s41
	s_nop 0
	global_load_lds_dwordx4 v[224:225], off
	s_waitcnt vmcnt(8)
	s_waitcnt lgkmcnt(0)
	s_barrier
	s_waitcnt lgkmcnt(0)
	v_mfma_f32_16x16x32_f16 v[60:63], v[80:83], v[178:181], v[60:63]
	v_mfma_f32_16x16x32_f16 v[56:59], v[92:95], v[178:181], v[56:59]
	v_mfma_f32_16x16x32_f16 v[44:47], v[80:83], v[186:189], v[44:47]
	v_mfma_f32_16x16x32_f16 v[40:43], v[92:95], v[186:189], v[40:43]
	v_mfma_f32_16x16x32_f16 v[28:31], v[80:83], v[194:197], v[28:31]
	v_mfma_f32_16x16x32_f16 v[24:27], v[92:95], v[194:197], v[24:27]
	v_mfma_f32_16x16x32_f16 v[12:15], v[80:83], v[212:215], v[12:15]
	v_mfma_f32_16x16x32_f16 v[8:11], v[92:95], v[212:215], v[8:11]
	v_mfma_f32_16x16x32_f16 v[60:63], v[84:87], v[182:185], v[60:63]
	v_mfma_f32_16x16x32_f16 v[56:59], v[96:99], v[182:185], v[56:59]
	v_mfma_f32_16x16x32_f16 v[44:47], v[84:87], v[190:193], v[44:47]
	v_mfma_f32_16x16x32_f16 v[40:43], v[96:99], v[190:193], v[40:43]
	v_mfma_f32_16x16x32_f16 v[28:31], v[84:87], v[198:201], v[28:31]
	v_mfma_f32_16x16x32_f16 v[24:27], v[96:99], v[198:201], v[24:27]
	v_mfma_f32_16x16x32_f16 v[12:15], v[84:87], v[216:219], v[12:15]
	v_mfma_f32_16x16x32_f16 v[8:11], v[96:99], v[216:219], v[8:11]
	v_mfma_f32_16x16x32_f16 v[52:55], v[144:147], v[178:181], v[52:55]
	v_mfma_f32_16x16x32_f16 v[48:51], v[152:155], v[178:181], v[48:51]
	v_mfma_f32_16x16x32_f16 v[36:39], v[144:147], v[186:189], v[36:39]
	v_mfma_f32_16x16x32_f16 v[32:35], v[152:155], v[186:189], v[32:35]
	v_mfma_f32_16x16x32_f16 v[20:23], v[144:147], v[194:197], v[20:23]
	v_mfma_f32_16x16x32_f16 v[16:19], v[152:155], v[194:197], v[16:19]
	v_mfma_f32_16x16x32_f16 v[4:7], v[144:147], v[212:215], v[4:7]
	v_mfma_f32_16x16x32_f16 v[0:3], v[152:155], v[212:215], v[0:3]
	v_mfma_f32_16x16x32_f16 v[52:55], v[148:151], v[182:185], v[52:55]
	v_mfma_f32_16x16x32_f16 v[48:51], v[156:159], v[182:185], v[48:51]
	v_mfma_f32_16x16x32_f16 v[36:39], v[148:151], v[190:193], v[36:39]
	v_mfma_f32_16x16x32_f16 v[32:35], v[156:159], v[190:193], v[32:35]
	v_mfma_f32_16x16x32_f16 v[20:23], v[148:151], v[198:201], v[20:23]
	v_mfma_f32_16x16x32_f16 v[16:19], v[156:159], v[198:201], v[16:19]
	v_mfma_f32_16x16x32_f16 v[4:7], v[148:151], v[216:219], v[4:7]
	v_mfma_f32_16x16x32_f16 v[0:3], v[156:159], v[216:219], v[0:3]
	s_barrier
	s_add_i32 s64, 0, 0x18000
	s_add_i32 s65, 0, 0x1c000
	v_add_u32_e32 v96, s64, v206
	v_add_u32_e32 v156, s65, v206
	ds_read_b128 v[80:83], v96
	ds_read_b128 v[84:87], v96 offset:1024
	ds_read_b128 v[92:95], v96 offset:2048
	ds_read_b128 v[96:99], v96 offset:3072
	ds_read_b128 v[144:147], v156
	ds_read_b128 v[148:151], v156 offset:1024
	ds_read_b128 v[152:155], v156 offset:2048
	ds_read_b128 v[156:159], v156 offset:3072
	s_add_u32 s22, s34, 0xb0000
	s_addc_u32 s23, s35, 0
	s_mov_b32 m0, s44
	v_lshl_add_u64 v[226:227], s[22:23], 0, v[160:161]
	ds_read_b128 v[178:181], v210 offset:32768
	ds_read_b128 v[182:185], v210 offset:33792
	ds_read_b128 v[186:189], v210 offset:34816
	ds_read_b128 v[190:193], v210 offset:35840
	ds_read_b128 v[194:197], v210 offset:36864
	ds_read_b128 v[198:201], v210 offset:37888
	ds_read_b128 v[212:215], v210 offset:38912
	ds_read_b128 v[216:219], v210 offset:39936
	global_load_lds_dwordx4 v[226:227], off
	v_lshl_add_u64 v[226:227], s[22:23], 0, v[164:165]
	s_mov_b32 m0, s45
	s_nop 0
	global_load_lds_dwordx4 v[226:227], off
	s_waitcnt vmcnt(8)
	s_waitcnt lgkmcnt(0)
	s_barrier
	s_waitcnt lgkmcnt(0)
	v_mfma_f32_16x16x32_f16 v[140:143], v[80:83], v[178:181], v[140:143]
	v_mfma_f32_16x16x32_f16 v[136:139], v[92:95], v[178:181], v[136:139]
	v_mfma_f32_16x16x32_f16 v[124:127], v[80:83], v[186:189], v[124:127]
	v_mfma_f32_16x16x32_f16 v[120:123], v[92:95], v[186:189], v[120:123]
	v_mfma_f32_16x16x32_f16 v[108:111], v[80:83], v[194:197], v[108:111]
	v_mfma_f32_16x16x32_f16 v[104:107], v[92:95], v[194:197], v[104:107]
	v_mfma_f32_16x16x32_f16 v[76:79], v[80:83], v[212:215], v[76:79]
	v_mfma_f32_16x16x32_f16 v[72:75], v[92:95], v[212:215], v[72:75]
	v_mfma_f32_16x16x32_f16 v[140:143], v[84:87], v[182:185], v[140:143]
	v_mfma_f32_16x16x32_f16 v[136:139], v[96:99], v[182:185], v[136:139]
	v_mfma_f32_16x16x32_f16 v[124:127], v[84:87], v[190:193], v[124:127]
	v_mfma_f32_16x16x32_f16 v[120:123], v[96:99], v[190:193], v[120:123]
	v_mfma_f32_16x16x32_f16 v[108:111], v[84:87], v[198:201], v[108:111]
	v_mfma_f32_16x16x32_f16 v[104:107], v[96:99], v[198:201], v[104:107]
	v_mfma_f32_16x16x32_f16 v[76:79], v[84:87], v[216:219], v[76:79]
	v_mfma_f32_16x16x32_f16 v[72:75], v[96:99], v[216:219], v[72:75]
	v_mfma_f32_16x16x32_f16 v[132:135], v[144:147], v[178:181], v[132:135]
	v_mfma_f32_16x16x32_f16 v[128:131], v[152:155], v[178:181], v[128:131]
	v_mfma_f32_16x16x32_f16 v[116:119], v[144:147], v[186:189], v[116:119]
	v_mfma_f32_16x16x32_f16 v[112:115], v[152:155], v[186:189], v[112:115]
	v_mfma_f32_16x16x32_f16 v[100:103], v[144:147], v[194:197], v[100:103]
	v_mfma_f32_16x16x32_f16 v[88:91], v[152:155], v[194:197], v[88:91]
	v_mfma_f32_16x16x32_f16 v[68:71], v[144:147], v[212:215], v[68:71]
	v_mfma_f32_16x16x32_f16 v[64:67], v[152:155], v[212:215], v[64:67]
	v_mfma_f32_16x16x32_f16 v[132:135], v[148:151], v[182:185], v[132:135]
	v_mfma_f32_16x16x32_f16 v[128:131], v[156:159], v[182:185], v[128:131]
	v_mfma_f32_16x16x32_f16 v[116:119], v[148:151], v[190:193], v[116:119]
	v_mfma_f32_16x16x32_f16 v[112:115], v[156:159], v[190:193], v[112:115]
	v_mfma_f32_16x16x32_f16 v[100:103], v[148:151], v[198:201], v[100:103]
	v_mfma_f32_16x16x32_f16 v[88:91], v[156:159], v[198:201], v[88:91]
	v_mfma_f32_16x16x32_f16 v[68:71], v[148:151], v[216:219], v[68:71]
	v_mfma_f32_16x16x32_f16 v[64:67], v[156:159], v[216:219], v[64:67]
	s_barrier
	s_add_i32 s22, s64, s33
	v_lshl_add_u64 v[202:203], v[202:203], 0, s[16:17]
	s_mov_b32 m0, s22
	ds_read_b128 v[178:181], v210 offset:49152
	ds_read_b128 v[182:185], v210 offset:50176
	ds_read_b128 v[186:189], v210 offset:51200
	ds_read_b128 v[190:193], v210 offset:52224
	ds_read_b128 v[194:197], v210 offset:53248
	ds_read_b128 v[198:201], v210 offset:54272
	ds_read_b128 v[212:215], v210 offset:55296
	ds_read_b128 v[216:219], v210 offset:56320
	global_load_lds_dwordx4 v[202:203], off
	s_add_i32 m0, s22, 0x2000
	s_add_u32 s22, s26, 0xb0080
	v_lshl_add_u64 v[202:203], v[220:221], 0, s[16:17]
	s_addc_u32 s23, s27, 0
	s_add_i32 s26, s65, s33
	global_load_lds_dwordx4 v[202:203], off
	v_lshl_add_u64 v[202:203], s[22:23], 0, v[162:163]
	s_mov_b32 m0, s26
	s_nop 0
	global_load_lds_dwordx4 v[202:203], off
	v_lshl_add_u64 v[202:203], s[22:23], 0, v[166:167]
	s_add_i32 m0, s26, 0x2000
	s_nop 0
	global_load_lds_dwordx4 v[202:203], off
	v_lshl_add_u64 v[202:203], v[222:223], 0, s[16:17]
	s_mov_b32 m0, s51
	s_nop 0
	global_load_lds_dwordx4 v[202:203], off
	v_lshl_add_u64 v[202:203], v[224:225], 0, s[16:17]
	s_mov_b32 m0, s52
	s_nop 0
	global_load_lds_dwordx4 v[202:203], off
	s_waitcnt vmcnt(8)
	s_waitcnt lgkmcnt(0)
	s_barrier
	s_waitcnt lgkmcnt(0)
	v_mfma_f32_16x16x32_f16 v[60:63], v[80:83], v[178:181], v[60:63]
	v_mfma_f32_16x16x32_f16 v[56:59], v[92:95], v[178:181], v[56:59]
	v_mfma_f32_16x16x32_f16 v[44:47], v[80:83], v[186:189], v[44:47]
	v_mfma_f32_16x16x32_f16 v[40:43], v[92:95], v[186:189], v[40:43]
	v_mfma_f32_16x16x32_f16 v[28:31], v[80:83], v[194:197], v[28:31]
	v_mfma_f32_16x16x32_f16 v[24:27], v[92:95], v[194:197], v[24:27]
	v_mfma_f32_16x16x32_f16 v[12:15], v[80:83], v[212:215], v[12:15]
	v_mfma_f32_16x16x32_f16 v[8:11], v[92:95], v[212:215], v[8:11]
	v_mfma_f32_16x16x32_f16 v[60:63], v[84:87], v[182:185], v[60:63]
	v_mfma_f32_16x16x32_f16 v[56:59], v[96:99], v[182:185], v[56:59]
	v_mfma_f32_16x16x32_f16 v[44:47], v[84:87], v[190:193], v[44:47]
	v_mfma_f32_16x16x32_f16 v[40:43], v[96:99], v[190:193], v[40:43]
	v_mfma_f32_16x16x32_f16 v[28:31], v[84:87], v[198:201], v[28:31]
	v_mfma_f32_16x16x32_f16 v[24:27], v[96:99], v[198:201], v[24:27]
	v_mfma_f32_16x16x32_f16 v[12:15], v[84:87], v[216:219], v[12:15]
	v_mfma_f32_16x16x32_f16 v[8:11], v[96:99], v[216:219], v[8:11]
	v_mfma_f32_16x16x32_f16 v[52:55], v[144:147], v[178:181], v[52:55]
	v_mfma_f32_16x16x32_f16 v[48:51], v[152:155], v[178:181], v[48:51]
	v_mfma_f32_16x16x32_f16 v[36:39], v[144:147], v[186:189], v[36:39]
	v_mfma_f32_16x16x32_f16 v[32:35], v[152:155], v[186:189], v[32:35]
	v_mfma_f32_16x16x32_f16 v[20:23], v[144:147], v[194:197], v[20:23]
	v_mfma_f32_16x16x32_f16 v[16:19], v[152:155], v[194:197], v[16:19]
	v_mfma_f32_16x16x32_f16 v[4:7], v[144:147], v[212:215], v[4:7]
	v_mfma_f32_16x16x32_f16 v[0:3], v[152:155], v[212:215], v[0:3]
	v_mfma_f32_16x16x32_f16 v[52:55], v[148:151], v[182:185], v[52:55]
	v_mfma_f32_16x16x32_f16 v[48:51], v[156:159], v[182:185], v[48:51]
	v_mfma_f32_16x16x32_f16 v[36:39], v[148:151], v[190:193], v[36:39]
	v_mfma_f32_16x16x32_f16 v[32:35], v[156:159], v[190:193], v[32:35]
	v_mfma_f32_16x16x32_f16 v[20:23], v[148:151], v[198:201], v[20:23]
	v_mfma_f32_16x16x32_f16 v[16:19], v[156:159], v[198:201], v[16:19]
	v_mfma_f32_16x16x32_f16 v[4:7], v[148:151], v[216:219], v[4:7]
	v_mfma_f32_16x16x32_f16 v[0:3], v[156:159], v[216:219], v[0:3]
	s_barrier
	s_add_i32 s63, s63, 2
	s_add_u32 s61, s61, 0x100
	s_addc_u32 s62, s62, 0
	s_cmp_gt_u32 s63, 41
	s_mov_b64 s[22:23], s[24:25]
	s_cbranch_scc0 .LBB0_1220
	s_and_b64 vcc, exec, s[18:19]
	s_cbranch_vccz .LBB0_1223
	s_barrier

.LBB0_1269:
	s_cmp_lt_i32 s91, 17
	s_cselect_b64 s[0:1], -1, 0
	s_xor_b64 s[2:3], s[6:7], -1
	s_or_b64 s[0:1], s[2:3], s[0:1]
	s_and_b64 vcc, exec, s[0:1]
	s_cbranch_vccnz .LBB0_1323
	s_waitcnt vmcnt(0)
	s_waitcnt lgkmcnt(0)
	s_setprio 0
	s_barrier
	s_and_saveexec_b64 s[0:1], s[92:93]
	s_cbranch_execz .LBB0_1322
	s_add_i32 s2, 0, 0x27ff0
	v_mov_b32_e32 v0, s2
	s_waitcnt vmcnt(0) expcnt(0) lgkmcnt(0)
	ds_read_b32 v2, v0
	s_add_i32 s2, 0, 0x27ff4
	v_mov_b32_e32 v0, s2
	ds_read_b32 v0, v0
	s_waitcnt lgkmcnt(1)
	v_cmp_ne_u32_e32 vcc, 0, v2
	s_cbranch_vccnz .LBB0_1286
	s_add_u32 s2, s30, 0x38200
	s_addc_u32 s3, s31, 0
	s_add_u32 s4, s30, 0x38400
	s_addc_u32 s5, s31, 0
	s_add_u32 s6, s30, 0x38500
	s_addc_u32 s7, s31, 0
	s_add_u32 s10, s30, 0x38600
	s_addc_u32 s11, s31, 0
	s_add_u32 s12, s30, 0x38700
	s_addc_u32 s13, s31, 0
	s_add_u32 s14, s30, 0x38800
	s_addc_u32 s15, s31, 0
	s_add_u32 s16, s30, 0x38900
	s_addc_u32 s17, s31, 0
	s_add_u32 s18, s30, 0x38a00
	s_addc_u32 s19, s31, 0
	s_add_u32 s20, s30, 0x38b00
	s_addc_u32 s21, s31, 0
	s_add_u32 s22, s30, 0x38c00
	s_addc_u32 s23, s31, 0
	s_add_u32 s24, s30, 0x38d00
	s_addc_u32 s25, s31, 0
	s_add_u32 s26, s30, 0x38e00
	s_addc_u32 s27, s31, 0
	s_add_u32 s34, s30, 0x38f00
	s_addc_u32 s35, s31, 0
	s_add_u32 s40, s30, 0x39000
	s_addc_u32 s41, s31, 0
	s_add_u32 s44, s30, 0x39100
	s_addc_u32 s45, s31, 0
	s_add_u32 s46, s30, 0x39200
	s_addc_u32 s47, s31, 0
	s_mul_i32 s33, s89, s9
	s_add_u32 s48, s30, 0x39300
	s_mul_i32 s33, s33, s88
	s_addc_u32 s49, s31, 0
	s_mov_b32 s56, 1
	v_mov_b32_e32 v16, 0
	s_branch .LBB0_1274

.LBB0_1323:
	s_cmp_lt_i32 s90, 18
	s_cselect_b64 s[6:7], -1, 0
	s_cmp_gt_i32 s90, 17
	s_cselect_b64 s[0:1], -1, 0
	s_cmp_lt_i32 s91, 18
	s_cselect_b64 s[2:3], -1, 0
	s_or_b64 s[0:1], s[0:1], s[2:3]
	s_and_b64 vcc, exec, s[0:1]
	s_cbranch_vccnz .LBB0_1343
	s_add_u32 s20, s30, 0x1a2000
	s_addc_u32 s21, s31, 0
	s_add_u32 s22, s30, 0x4a00000
	s_addc_u32 s23, s31, 0
	v_mov_b32_e32 v10, v204
	s_cmpk_gt_i32 s8, 0x2ff
	v_readfirstlane_b32 s3, v10
	s_cbranch_scc1 .LBB0_1340
	v_lshlrev_b32_e32 v0, 4, v10
	s_waitcnt lgkmcnt(0)
	v_add_u32_e32 v1, 0x2000, v0
	v_ashrrev_i32_e32 v2, 31, v1
	v_lshrrev_b32_e32 v2, 22, v2
	v_add_u32_e32 v2, v1, v2
	v_ashrrev_i32_e32 v8, 10, v2
	v_mul_i32_i24_e32 v2, 0x400, v8
	v_sub_u32_e32 v1, v1, v2
	v_lshrrev_b32_e32 v2, 4, v1
	v_bitop3_b32 v1, v2, v1, 32 bitop3:0x6c
	v_ashrrev_i32_e32 v2, 31, v1
	v_lshrrev_b32_e32 v2, 26, v2
	v_add_u32_e32 v2, v1, v2
	v_lshlrev_b32_e32 v3, 3, v8
	v_ashrrev_i32_e32 v9, 6, v2
	v_and_b32_e32 v3, -16, v3
	v_add_u32_e32 v3, v9, v3
	v_and_b32_e32 v4, 3, v9
	s_mov_b32 s0, 0x1fffe0
	v_lshrrev_b32_e32 v5, 2, v3
	v_lshlrev_b32_e32 v6, 1, v3
	v_and_b32_e32 v2, 0xc0, v2
	v_and_or_b32 v4, v3, s0, v4
	v_and_b32_e32 v5, 4, v5
	v_and_b32_e32 v6, 24, v6
	v_sub_u32_e32 v1, v1, v2
	v_mov_b32_e32 v2, 1
	v_or3_b32 v4, v4, v5, v6
	v_lshlrev_b32_e32 v5, 5, v8
	v_ashrrev_i16_sdwa v1, v2, sext(v1) dst_sel:DWORD dst_unused:UNUSED_PAD src0_sel:DWORD src1_sel:BYTE_0
	v_and_b32_e32 v5, 32, v5
	v_bfe_i32 v11, v1, 0, 16
	v_add_lshl_u32 v1, v5, v11, 1
	v_lshl_add_u32 v144, v4, 11, v1
	v_lshl_add_u32 v146, v3, 11, v1
	v_bfe_i32 v1, v10, 27, 1
	v_lshrrev_b32_e32 v1, 22, v1
	v_add_u32_e32 v1, v0, v1
	v_and_b32_e32 v1, 0xfffffc00, v1
	v_sub_u32_e32 v0, v0, v1
	v_lshrrev_b32_e32 v1, 4, v0
	v_ashrrev_i32_e32 v3, 31, v10
	v_bitop3_b32 v0, v1, v0, 32 bitop3:0x6c
	v_lshrrev_b32_e32 v3, 26, v3
	v_ashrrev_i32_e32 v1, 31, v0
	v_add_u32_e32 v3, v10, v3
	v_lshrrev_b32_e32 v1, 26, v1
	v_ashrrev_i32_e32 v13, 6, v3
	v_add_u32_e32 v1, v0, v1
	v_lshlrev_b32_e32 v3, 3, v13
	v_ashrrev_i32_e32 v12, 6, v1
	v_and_b32_e32 v3, -16, v3
	v_add_u32_e32 v3, v12, v3
	v_and_b32_e32 v4, 3, v12
	s_ashr_i32 s52, s8, 31
	v_and_or_b32 v4, v3, s0, v4
	s_lshr_b32 s0, s52, 29
	s_add_i32 s0, s8, s0
	s_ashr_i32 s12, s3, 6
	s_ashr_i32 s1, s0, 3
	s_and_b32 s0, s0, -8
	s_ashr_i32 s14, s3, 8
	s_lshl_b32 s33, s12, 10
	s_sub_i32 s0, s8, s0
	s_cmp_lt_i32 s0, 0
	s_movk_i32 s53, 0x61
	s_cselect_b32 s2, s53, 0x60
	s_mul_i32 s0, s0, s2
	s_add_i32 s0, s0, s1
	s_mul_hi_i32 s1, s0, 0x2aaaaaab
	s_lshr_b32 s2, s1, 31
	s_ashr_i32 s1, s1, 4
	s_add_i32 s1, s1, s2
	s_lshl_b32 s4, s1, 3
	s_mulk_i32 s1, 0x60
	s_sub_i32 s0, s0, s1
	s_bfe_i32 s1, s0, 0x80000
	s_bfe_u32 s1, s1, 0x3000c
	s_add_i32 s1, s0, s1
	s_bfe_i32 s2, s1, 0x80000
	s_and_b32 s1, s1, 0xf8
	s_sub_i32 s0, s0, s1
	s_sext_i32_i16 s2, s2
	s_sext_i32_i8 s0, s0
	v_lshrrev_b32_e32 v5, 2, v3
	v_lshlrev_b32_e32 v6, 1, v3
	v_and_b32_e32 v1, 0xc0, v1
	s_lshr_b32 s2, s2, 3
	s_add_i32 s0, s4, s0
	v_and_b32_e32 v5, 4, v5
	v_and_b32_e32 v6, 24, v6
	v_sub_u32_e32 v0, v0, v1
	s_ashr_i32 s1, s0, 31
	s_bfe_i64 s[10:11], s[2:3], 0x100000
	v_or3_b32 v4, v4, v5, v6
	v_lshlrev_b32_e32 v5, 5, v13
	v_ashrrev_i16_sdwa v0, v2, sext(v0) dst_sel:DWORD dst_unused:UNUSED_PAD src0_sel:DWORD src1_sel:BYTE_0
	s_lshl_b64 s[4:5], s[0:1], 19
	s_lshl_b64 s[10:11], s[10:11], 19
	v_and_b32_e32 v5, 32, v5
	v_bfe_i32 v14, v0, 0, 16
	s_add_u32 s48, s22, s10
	v_add_lshl_u32 v0, v5, v14, 1
	s_addc_u32 s49, s23, s11
	s_add_i32 s54, s33, 0
	v_lshl_add_u32 v148, v4, 11, v0
	s_add_i32 m0, s54, 0x10000
	v_lshl_add_u32 v150, v3, 11, v0
	global_load_lds_dwordx4 v148, s[48:49]
	s_add_i32 m0, s54, 0x12000
	s_add_u32 s10, s48, 0x40000
	global_load_lds_dwordx4 v144, s[48:49]
	s_addc_u32 s11, s49, 0
	s_add_i32 m0, s54, 0x14000
	v_mov_b32_e32 v149, 0
	global_load_lds_dwordx4 v148, s[10:11]
	s_add_i32 m0, s54, 0x16000
	s_add_u32 s46, s42, s4
	s_addc_u32 s47, s43, s5
	s_add_i32 s55, s54, 0x2000
	global_load_lds_dwordx4 v144, s[10:11]
	s_mov_b32 m0, s54
	s_add_u32 s4, s46, 0x40000
	global_load_lds_dwordx4 v150, s[46:47]
	s_mov_b32 m0, s55
	s_addc_u32 s5, s47, 0
	s_add_i32 s56, s54, 0x4000
	global_load_lds_dwordx4 v146, s[46:47]
	s_mov_b32 m0, s56
	s_add_i32 s57, s54, 0x6000
	global_load_lds_dwordx4 v150, s[4:5]
	s_mov_b32 m0, s57
	v_mov_b32_e32 v145, v149
	global_load_lds_dwordx4 v146, s[4:5]
	v_mov_b32_e32 v151, v149
	v_mov_b32_e32 v147, v149
	s_cmp_eq_u32 s14, 1
	s_mov_b32 s58, 0
	v_lshl_add_u64 v[6:7], s[48:49], 0, v[148:149]
	v_lshl_add_u64 v[2:3], s[48:49], 0, v[144:145]
	s_mov_b64 s[4:5], 0x40000
	v_lshl_add_u64 v[0:1], s[46:47], 0, v[150:151]
	s_cselect_b64 s[10:11], -1, 0
	s_cmp_lg_u32 s14, 1
	v_lshl_add_u64 v[4:5], s[46:47], 0, v[146:147]
	s_cbranch_scc1 .LBB0_1327
	s_barrier
	s_setprio 1

.LBB0_1333:
	ds_read_b128 v[128:131], v167
	ds_read_b128 v[132:135], v167 offset:1024
	ds_read_b128 v[136:139], v167 offset:2048
	ds_read_b128 v[140:143], v167 offset:3072
	ds_read_b128 v[160:163], v168
	ds_read_b128 v[172:175], v168 offset:1024
	ds_read_b128 v[178:181], v168 offset:2048
	ds_read_b128 v[182:185], v168 offset:3072
	s_add_u32 s48, s46, 0xfffc0080
	s_addc_u32 s49, s47, -1
	s_cmp_eq_u32 s76, 12
	s_cselect_b32 s51, s35, s49
	s_cselect_b32 s50, s72, s48
	s_cselect_b32 s49, s27, s75
	s_cselect_b32 s48, s73, s74
	v_lshl_add_u64 v[202:203], s[46:47], 0, v[152:153]
	s_add_i32 m0, s54, 0xc000
	ds_read_b128 v[186:189], v169
	ds_read_b128 v[190:193], v169 offset:1024
	ds_read_b128 v[194:197], v169 offset:2048
	ds_read_b128 v[198:201], v169 offset:3072
	ds_read_b128 v[206:209], v169 offset:4096
	ds_read_b128 v[210:213], v169 offset:5120
	ds_read_b128 v[214:217], v169 offset:6144
	ds_read_b128 v[218:221], v169 offset:7168
	global_load_lds_dwordx4 v[202:203], off
	v_lshl_add_u64 v[202:203], s[46:47], 0, v[154:155]
	s_add_i32 m0, s54, 0xe000
	s_nop 0
	global_load_lds_dwordx4 v[202:203], off
	s_waitcnt vmcnt(8)
	s_waitcnt lgkmcnt(0)
	s_barrier
	s_waitcnt lgkmcnt(0)
	v_mfma_f32_16x16x32_f16 v[124:127], v[128:131], v[186:189], v[124:127]
	v_mfma_f32_16x16x32_f16 v[120:123], v[136:139], v[186:189], v[120:123]
	v_mfma_f32_16x16x32_f16 v[108:111], v[128:131], v[194:197], v[108:111]
	v_mfma_f32_16x16x32_f16 v[104:107], v[136:139], v[194:197], v[104:107]
	v_mfma_f32_16x16x32_f16 v[92:95], v[128:131], v[206:209], v[92:95]
	v_mfma_f32_16x16x32_f16 v[88:91], v[136:139], v[206:209], v[88:91]
	v_mfma_f32_16x16x32_f16 v[84:87], v[128:131], v[214:217], v[84:87]
	v_mfma_f32_16x16x32_f16 v[76:79], v[136:139], v[214:217], v[76:79]
	v_mfma_f32_16x16x32_f16 v[124:127], v[132:135], v[190:193], v[124:127]
	v_mfma_f32_16x16x32_f16 v[120:123], v[140:143], v[190:193], v[120:123]
	v_mfma_f32_16x16x32_f16 v[108:111], v[132:135], v[198:201], v[108:111]
	v_mfma_f32_16x16x32_f16 v[104:107], v[140:143], v[198:201], v[104:107]
	v_mfma_f32_16x16x32_f16 v[92:95], v[132:135], v[210:213], v[92:95]
	v_mfma_f32_16x16x32_f16 v[88:91], v[140:143], v[210:213], v[88:91]
	v_mfma_f32_16x16x32_f16 v[84:87], v[132:135], v[218:221], v[84:87]
	v_mfma_f32_16x16x32_f16 v[76:79], v[140:143], v[218:221], v[76:79]
	v_mfma_f32_16x16x32_f16 v[116:119], v[160:163], v[186:189], v[116:119]
	v_mfma_f32_16x16x32_f16 v[112:115], v[178:181], v[186:189], v[112:115]
	v_mfma_f32_16x16x32_f16 v[100:103], v[160:163], v[194:197], v[100:103]
	v_mfma_f32_16x16x32_f16 v[96:99], v[178:181], v[194:197], v[96:99]
	v_mfma_f32_16x16x32_f16 v[80:83], v[160:163], v[206:209], v[80:83]
	v_mfma_f32_16x16x32_f16 v[72:75], v[178:181], v[206:209], v[72:75]
	v_mfma_f32_16x16x32_f16 v[68:71], v[160:163], v[214:217], v[68:71]
	v_mfma_f32_16x16x32_f16 v[64:67], v[178:181], v[214:217], v[64:67]
	v_mfma_f32_16x16x32_f16 v[116:119], v[172:175], v[190:193], v[116:119]
	v_mfma_f32_16x16x32_f16 v[112:115], v[182:185], v[190:193], v[112:115]
	v_mfma_f32_16x16x32_f16 v[100:103], v[172:175], v[198:201], v[100:103]
	v_mfma_f32_16x16x32_f16 v[96:99], v[182:185], v[198:201], v[96:99]
	v_mfma_f32_16x16x32_f16 v[80:83], v[172:175], v[210:213], v[80:83]
	v_mfma_f32_16x16x32_f16 v[72:75], v[182:185], v[210:213], v[72:75]
	v_mfma_f32_16x16x32_f16 v[68:71], v[172:175], v[218:221], v[68:71]
	v_mfma_f32_16x16x32_f16 v[64:67], v[182:185], v[218:221], v[64:67]
	s_barrier
	s_add_i32 s77, s64, s33
	v_lshl_add_u64 v[202:203], s[48:49], 0, v[148:149]
	s_mov_b32 m0, s77
	ds_read_b128 v[186:189], v169 offset:16384
	ds_read_b128 v[190:193], v169 offset:17408
	ds_read_b128 v[194:197], v169 offset:18432
	ds_read_b128 v[198:201], v169 offset:19456
	ds_read_b128 v[206:209], v169 offset:20480
	ds_read_b128 v[210:213], v169 offset:21504
	ds_read_b128 v[214:217], v169 offset:22528
	ds_read_b128 v[218:221], v169 offset:23552
	global_load_lds_dwordx4 v[202:203], off
	s_add_i32 m0, s77, 0x2000
	s_add_u32 s78, s48, 0x40000
	v_lshl_add_u64 v[222:223], s[48:49], 0, v[144:145]
	s_addc_u32 s79, s49, 0
	s_add_i32 s77, s65, s33
	global_load_lds_dwordx4 v[222:223], off
	v_lshl_add_u64 v[224:225], s[78:79], 0, v[148:149]
	s_mov_b32 m0, s77
	v_lshl_add_u64 v[226:227], s[50:51], 0, v[146:147]
	global_load_lds_dwordx4 v[224:225], off
	v_lshl_add_u64 v[224:225], s[78:79], 0, v[144:145]
	s_add_i32 m0, s77, 0x2000
	s_nop 0
	global_load_lds_dwordx4 v[224:225], off
	v_lshl_add_u64 v[224:225], s[50:51], 0, v[150:151]
	s_mov_b32 m0, s54
	s_nop 0
	global_load_lds_dwordx4 v[224:225], off
	s_mov_b32 m0, s55
	s_nop 0
	global_load_lds_dwordx4 v[226:227], off
	s_waitcnt vmcnt(8)
	s_waitcnt lgkmcnt(0)
	s_barrier
	s_waitcnt lgkmcnt(0)
	v_mfma_f32_16x16x32_f16 v[60:63], v[128:131], v[186:189], v[60:63]
	v_mfma_f32_16x16x32_f16 v[56:59], v[136:139], v[186:189], v[56:59]
	v_mfma_f32_16x16x32_f16 v[44:47], v[128:131], v[194:197], v[44:47]
	v_mfma_f32_16x16x32_f16 v[40:43], v[136:139], v[194:197], v[40:43]
	v_mfma_f32_16x16x32_f16 v[28:31], v[128:131], v[206:209], v[28:31]
	v_mfma_f32_16x16x32_f16 v[24:27], v[136:139], v[206:209], v[24:27]
	v_mfma_f32_16x16x32_f16 v[12:15], v[128:131], v[214:217], v[12:15]
	v_mfma_f32_16x16x32_f16 v[8:11], v[136:139], v[214:217], v[8:11]
	v_mfma_f32_16x16x32_f16 v[60:63], v[132:135], v[190:193], v[60:63]
	v_mfma_f32_16x16x32_f16 v[56:59], v[140:143], v[190:193], v[56:59]
	v_mfma_f32_16x16x32_f16 v[44:47], v[132:135], v[198:201], v[44:47]
	v_mfma_f32_16x16x32_f16 v[40:43], v[140:143], v[198:201], v[40:43]
	v_mfma_f32_16x16x32_f16 v[28:31], v[132:135], v[210:213], v[28:31]
	v_mfma_f32_16x16x32_f16 v[24:27], v[140:143], v[210:213], v[24:27]
	v_mfma_f32_16x16x32_f16 v[12:15], v[132:135], v[218:221], v[12:15]
	v_mfma_f32_16x16x32_f16 v[8:11], v[140:143], v[218:221], v[8:11]
	v_mfma_f32_16x16x32_f16 v[52:55], v[160:163], v[186:189], v[52:55]
	v_mfma_f32_16x16x32_f16 v[48:51], v[178:181], v[186:189], v[48:51]
	v_mfma_f32_16x16x32_f16 v[36:39], v[160:163], v[194:197], v[36:39]
	v_mfma_f32_16x16x32_f16 v[32:35], v[178:181], v[194:197], v[32:35]
	v_mfma_f32_16x16x32_f16 v[20:23], v[160:163], v[206:209], v[20:23]
	v_mfma_f32_16x16x32_f16 v[16:19], v[178:181], v[206:209], v[16:19]
	v_mfma_f32_16x16x32_f16 v[4:7], v[160:163], v[214:217], v[4:7]
	v_mfma_f32_16x16x32_f16 v[0:3], v[178:181], v[214:217], v[0:3]
	v_mfma_f32_16x16x32_f16 v[52:55], v[172:175], v[190:193], v[52:55]
	v_mfma_f32_16x16x32_f16 v[48:51], v[182:185], v[190:193], v[48:51]
	v_mfma_f32_16x16x32_f16 v[36:39], v[172:175], v[198:201], v[36:39]
	v_mfma_f32_16x16x32_f16 v[32:35], v[182:185], v[198:201], v[32:35]
	v_mfma_f32_16x16x32_f16 v[20:23], v[172:175], v[210:213], v[20:23]
	v_mfma_f32_16x16x32_f16 v[16:19], v[182:185], v[210:213], v[16:19]
	v_mfma_f32_16x16x32_f16 v[4:7], v[172:175], v[218:221], v[4:7]
	v_mfma_f32_16x16x32_f16 v[0:3], v[182:185], v[218:221], v[0:3]
	s_barrier
	s_add_i32 s77, 0, 0x18000
	s_add_i32 s78, 0, 0x1c000
	v_add_u32_e32 v140, s77, v165
	v_add_u32_e32 v177, s78, v165
	ds_read_b128 v[128:131], v140
	ds_read_b128 v[132:135], v140 offset:1024
	ds_read_b128 v[136:139], v140 offset:2048
	ds_read_b128 v[140:143], v140 offset:3072
	ds_read_b128 v[160:163], v177
	ds_read_b128 v[172:175], v177 offset:1024
	ds_read_b128 v[178:181], v177 offset:2048
	ds_read_b128 v[182:185], v177 offset:3072
	s_add_u32 s50, s50, 0x40000
	s_addc_u32 s51, s51, 0
	s_mov_b32 m0, s56
	v_lshl_add_u64 v[228:229], s[50:51], 0, v[150:151]
	ds_read_b128 v[186:189], v169 offset:32768
	ds_read_b128 v[190:193], v169 offset:33792
	ds_read_b128 v[194:197], v169 offset:34816
	ds_read_b128 v[198:201], v169 offset:35840
	ds_read_b128 v[206:209], v169 offset:36864
	ds_read_b128 v[210:213], v169 offset:37888
	ds_read_b128 v[214:217], v169 offset:38912
	ds_read_b128 v[218:221], v169 offset:39936
	global_load_lds_dwordx4 v[228:229], off
	v_lshl_add_u64 v[228:229], s[50:51], 0, v[146:147]
	s_mov_b32 m0, s57
	s_nop 0
	global_load_lds_dwordx4 v[228:229], off
	s_waitcnt vmcnt(8)
	s_waitcnt lgkmcnt(0)
	s_barrier
	s_waitcnt lgkmcnt(0)
	v_mfma_f32_16x16x32_f16 v[124:127], v[128:131], v[186:189], v[124:127]
	v_mfma_f32_16x16x32_f16 v[120:123], v[136:139], v[186:189], v[120:123]
	v_mfma_f32_16x16x32_f16 v[108:111], v[128:131], v[194:197], v[108:111]
	v_mfma_f32_16x16x32_f16 v[104:107], v[136:139], v[194:197], v[104:107]
	v_mfma_f32_16x16x32_f16 v[92:95], v[128:131], v[206:209], v[92:95]
	v_mfma_f32_16x16x32_f16 v[88:91], v[136:139], v[206:209], v[88:91]
	v_mfma_f32_16x16x32_f16 v[84:87], v[128:131], v[214:217], v[84:87]
	v_mfma_f32_16x16x32_f16 v[76:79], v[136:139], v[214:217], v[76:79]
	v_mfma_f32_16x16x32_f16 v[124:127], v[132:135], v[190:193], v[124:127]
	v_mfma_f32_16x16x32_f16 v[120:123], v[140:143], v[190:193], v[120:123]
	v_mfma_f32_16x16x32_f16 v[108:111], v[132:135], v[198:201], v[108:111]
	v_mfma_f32_16x16x32_f16 v[104:107], v[140:143], v[198:201], v[104:107]
	v_mfma_f32_16x16x32_f16 v[92:95], v[132:135], v[210:213], v[92:95]
	v_mfma_f32_16x16x32_f16 v[88:91], v[140:143], v[210:213], v[88:91]
	v_mfma_f32_16x16x32_f16 v[84:87], v[132:135], v[218:221], v[84:87]
	v_mfma_f32_16x16x32_f16 v[76:79], v[140:143], v[218:221], v[76:79]
	v_mfma_f32_16x16x32_f16 v[116:119], v[160:163], v[186:189], v[116:119]
	v_mfma_f32_16x16x32_f16 v[112:115], v[178:181], v[186:189], v[112:115]
	v_mfma_f32_16x16x32_f16 v[100:103], v[160:163], v[194:197], v[100:103]
	v_mfma_f32_16x16x32_f16 v[96:99], v[178:181], v[194:197], v[96:99]
	v_mfma_f32_16x16x32_f16 v[80:83], v[160:163], v[206:209], v[80:83]
	v_mfma_f32_16x16x32_f16 v[72:75], v[178:181], v[206:209], v[72:75]
	v_mfma_f32_16x16x32_f16 v[68:71], v[160:163], v[214:217], v[68:71]
	v_mfma_f32_16x16x32_f16 v[64:67], v[178:181], v[214:217], v[64:67]
	v_mfma_f32_16x16x32_f16 v[116:119], v[172:175], v[190:193], v[116:119]
	v_mfma_f32_16x16x32_f16 v[112:115], v[182:185], v[190:193], v[112:115]
	v_mfma_f32_16x16x32_f16 v[100:103], v[172:175], v[198:201], v[100:103]
	v_mfma_f32_16x16x32_f16 v[96:99], v[182:185], v[198:201], v[96:99]
	v_mfma_f32_16x16x32_f16 v[80:83], v[172:175], v[210:213], v[80:83]
	v_mfma_f32_16x16x32_f16 v[72:75], v[182:185], v[210:213], v[72:75]
	v_mfma_f32_16x16x32_f16 v[68:71], v[172:175], v[218:221], v[68:71]
	v_mfma_f32_16x16x32_f16 v[64:67], v[182:185], v[218:221], v[64:67]
	s_barrier
	s_add_i32 s50, s77, s33
	v_lshl_add_u64 v[202:203], v[202:203], 0, s[12:13]
	s_mov_b32 m0, s50
	ds_read_b128 v[186:189], v169 offset:49152
	ds_read_b128 v[190:193], v169 offset:50176
	ds_read_b128 v[194:197], v169 offset:51200
	ds_read_b128 v[198:201], v169 offset:52224
	ds_read_b128 v[206:209], v169 offset:53248
	ds_read_b128 v[210:213], v169 offset:54272
	ds_read_b128 v[214:217], v169 offset:55296
	ds_read_b128 v[218:221], v169 offset:56320
	global_load_lds_dwordx4 v[202:203], off
	s_add_i32 m0, s50, 0x2000
	s_add_u32 s48, s48, 0x40080
	v_lshl_add_u64 v[202:203], v[222:223], 0, s[12:13]
	s_addc_u32 s49, s49, 0
	s_add_i32 s50, s78, s33
	global_load_lds_dwordx4 v[202:203], off
	v_lshl_add_u64 v[202:203], s[48:49], 0, v[148:149]
	s_mov_b32 m0, s50
	s_nop 0
	global_load_lds_dwordx4 v[202:203], off
	v_lshl_add_u64 v[202:203], s[48:49], 0, v[144:145]
	s_add_i32 m0, s50, 0x2000
	s_nop 0
	global_load_lds_dwordx4 v[202:203], off
	v_lshl_add_u64 v[202:203], v[224:225], 0, s[12:13]
	s_mov_b32 m0, s61
	s_nop 0
	global_load_lds_dwordx4 v[202:203], off
	v_lshl_add_u64 v[202:203], v[226:227], 0, s[12:13]
	s_mov_b32 m0, s62
	s_nop 0
	global_load_lds_dwordx4 v[202:203], off
	s_waitcnt vmcnt(8)
	s_waitcnt lgkmcnt(0)
	s_barrier
	s_waitcnt lgkmcnt(0)
	v_mfma_f32_16x16x32_f16 v[60:63], v[128:131], v[186:189], v[60:63]
	v_mfma_f32_16x16x32_f16 v[56:59], v[136:139], v[186:189], v[56:59]
	v_mfma_f32_16x16x32_f16 v[44:47], v[128:131], v[194:197], v[44:47]
	v_mfma_f32_16x16x32_f16 v[40:43], v[136:139], v[194:197], v[40:43]
	v_mfma_f32_16x16x32_f16 v[28:31], v[128:131], v[206:209], v[28:31]
	v_mfma_f32_16x16x32_f16 v[24:27], v[136:139], v[206:209], v[24:27]
	v_mfma_f32_16x16x32_f16 v[12:15], v[128:131], v[214:217], v[12:15]
	v_mfma_f32_16x16x32_f16 v[8:11], v[136:139], v[214:217], v[8:11]
	v_mfma_f32_16x16x32_f16 v[60:63], v[132:135], v[190:193], v[60:63]
	v_mfma_f32_16x16x32_f16 v[56:59], v[140:143], v[190:193], v[56:59]
	v_mfma_f32_16x16x32_f16 v[44:47], v[132:135], v[198:201], v[44:47]
	v_mfma_f32_16x16x32_f16 v[40:43], v[140:143], v[198:201], v[40:43]
	v_mfma_f32_16x16x32_f16 v[28:31], v[132:135], v[210:213], v[28:31]
	v_mfma_f32_16x16x32_f16 v[24:27], v[140:143], v[210:213], v[24:27]
	v_mfma_f32_16x16x32_f16 v[12:15], v[132:135], v[218:221], v[12:15]
	v_mfma_f32_16x16x32_f16 v[8:11], v[140:143], v[218:221], v[8:11]
	v_mfma_f32_16x16x32_f16 v[52:55], v[160:163], v[186:189], v[52:55]
	v_mfma_f32_16x16x32_f16 v[48:51], v[178:181], v[186:189], v[48:51]
	v_mfma_f32_16x16x32_f16 v[36:39], v[160:163], v[194:197], v[36:39]
	v_mfma_f32_16x16x32_f16 v[32:35], v[178:181], v[194:197], v[32:35]
	v_mfma_f32_16x16x32_f16 v[20:23], v[160:163], v[206:209], v[20:23]
	v_mfma_f32_16x16x32_f16 v[16:19], v[178:181], v[206:209], v[16:19]
	v_mfma_f32_16x16x32_f16 v[4:7], v[160:163], v[214:217], v[4:7]
	v_mfma_f32_16x16x32_f16 v[0:3], v[178:181], v[214:217], v[0:3]
	v_mfma_f32_16x16x32_f16 v[52:55], v[172:175], v[190:193], v[52:55]
	v_mfma_f32_16x16x32_f16 v[48:51], v[182:185], v[190:193], v[48:51]
	v_mfma_f32_16x16x32_f16 v[36:39], v[172:175], v[198:201], v[36:39]
	v_mfma_f32_16x16x32_f16 v[32:35], v[182:185], v[198:201], v[32:35]
	v_mfma_f32_16x16x32_f16 v[20:23], v[172:175], v[210:213], v[20:23]
	v_mfma_f32_16x16x32_f16 v[16:19], v[182:185], v[210:213], v[16:19]
	v_mfma_f32_16x16x32_f16 v[4:7], v[172:175], v[218:221], v[4:7]
	v_mfma_f32_16x16x32_f16 v[0:3], v[182:185], v[218:221], v[0:3]
	s_barrier
	s_add_i32 s76, s76, 2
	s_add_u32 s46, s46, 0x100
	s_addc_u32 s47, s47, 0
	s_add_u32 s74, s74, 0x100
	s_addc_u32 s75, s75, 0
	s_cmp_gt_u32 s76, 13
	s_cbranch_scc0 .LBB0_1333
	s_and_b64 vcc, exec, s[14:15]
	s_cbranch_vccz .LBB0_1336
	s_barrier

.LBB0_1343:
	s_cmp_lt_i32 s91, 19
	s_cselect_b64 s[0:1], -1, 0
	s_xor_b64 s[2:3], s[6:7], -1
	s_or_b64 s[0:1], s[2:3], s[0:1]
	s_and_b64 vcc, exec, s[0:1]
	s_cbranch_vccnz .LBB0_1397
	s_waitcnt vmcnt(0)
	s_waitcnt lgkmcnt(0)
	s_setprio 0
	s_barrier
	s_and_saveexec_b64 s[0:1], s[92:93]
	s_cbranch_execz .LBB0_1396
	s_add_i32 s2, 0, 0x27ff0
	v_mov_b32_e32 v0, s2
	s_waitcnt vmcnt(0) expcnt(0) lgkmcnt(0)
	ds_read_b32 v2, v0
	s_add_i32 s2, 0, 0x27ff4
	v_mov_b32_e32 v0, s2
	ds_read_b32 v0, v0
	s_waitcnt lgkmcnt(1)
	v_cmp_ne_u32_e32 vcc, 0, v2
	s_cbranch_vccnz .LBB0_1360
	s_add_u32 s2, s30, 0x38200
	s_addc_u32 s3, s31, 0
	s_add_u32 s4, s30, 0x38400
	s_addc_u32 s5, s31, 0
	s_add_u32 s6, s30, 0x38500
	s_addc_u32 s7, s31, 0
	s_add_u32 s10, s30, 0x38600
	s_addc_u32 s11, s31, 0
	s_add_u32 s12, s30, 0x38700
	s_addc_u32 s13, s31, 0
	s_add_u32 s14, s30, 0x38800
	s_addc_u32 s15, s31, 0
	s_add_u32 s16, s30, 0x38900
	s_addc_u32 s17, s31, 0
	s_add_u32 s18, s30, 0x38a00
	s_addc_u32 s19, s31, 0
	s_add_u32 s20, s30, 0x38b00
	s_addc_u32 s21, s31, 0
	s_add_u32 s22, s30, 0x38c00
	s_addc_u32 s23, s31, 0
	s_add_u32 s24, s30, 0x38d00
	s_addc_u32 s25, s31, 0
	s_add_u32 s26, s30, 0x38e00
	s_addc_u32 s27, s31, 0
	s_add_u32 s34, s30, 0x38f00
	s_addc_u32 s35, s31, 0
	s_add_u32 s40, s30, 0x39000
	s_addc_u32 s41, s31, 0
	s_add_u32 s44, s30, 0x39100
	s_addc_u32 s45, s31, 0
	s_add_u32 s46, s30, 0x39200
	s_addc_u32 s47, s31, 0
	s_mul_i32 s33, s89, s9
	s_add_u32 s48, s30, 0x39300
	s_mul_i32 s33, s33, s88
	s_addc_u32 s49, s31, 0
	s_mov_b32 s56, 1
	v_mov_b32_e32 v16, 0
	s_branch .LBB0_1348

.LBB0_1424:
	s_cmp_gt_i32 s91, 20
	s_cselect_b64 s[2:3], -1, 0
	s_and_b64 s[0:1], s[6:7], s[2:3]
	s_andn2_b64 vcc, exec, s[0:1]
	s_cbranch_vccnz .LBB0_1478
	s_waitcnt vmcnt(0)
	s_waitcnt lgkmcnt(0)
	s_setprio 0
	s_barrier
	s_and_saveexec_b64 s[0:1], s[92:93]
	s_cbranch_execz .LBB0_1477
	s_add_i32 s4, 0, 0x27ff0
	s_waitcnt vmcnt(5)
	v_mov_b32_e32 v0, s4
	s_waitcnt vmcnt(0) expcnt(0) lgkmcnt(0)
	ds_read_b32 v2, v0
	s_add_i32 s4, 0, 0x27ff4
	v_mov_b32_e32 v0, s4
	ds_read_b32 v0, v0
	s_waitcnt lgkmcnt(1)
	v_cmp_ne_u32_e32 vcc, 0, v2
	s_cbranch_vccnz .LBB0_1441
	s_add_u32 s4, s30, 0x38200
	s_addc_u32 s5, s31, 0
	s_add_u32 s6, s30, 0x38400
	s_addc_u32 s7, s31, 0
	s_add_u32 s10, s30, 0x38500
	s_addc_u32 s11, s31, 0
	s_add_u32 s12, s30, 0x38600
	s_addc_u32 s13, s31, 0
	s_add_u32 s14, s30, 0x38700
	s_addc_u32 s15, s31, 0
	s_add_u32 s16, s30, 0x38800
	s_addc_u32 s17, s31, 0
	s_add_u32 s18, s30, 0x38900
	s_addc_u32 s19, s31, 0
	s_add_u32 s20, s30, 0x38a00
	s_addc_u32 s21, s31, 0
	s_add_u32 s22, s30, 0x38b00
	s_addc_u32 s23, s31, 0
	s_add_u32 s24, s30, 0x38c00
	s_addc_u32 s25, s31, 0
	s_add_u32 s26, s30, 0x38d00
	s_addc_u32 s27, s31, 0
	s_add_u32 s34, s30, 0x38e00
	s_addc_u32 s35, s31, 0
	s_add_u32 s40, s30, 0x38f00
	s_addc_u32 s41, s31, 0
	s_add_u32 s44, s30, 0x39000
	s_addc_u32 s45, s31, 0
	s_add_u32 s46, s30, 0x39100
	s_addc_u32 s47, s31, 0
	s_add_u32 s48, s30, 0x39200
	s_addc_u32 s49, s31, 0
	s_mul_i32 s33, s89, s9
	s_add_u32 s50, s30, 0x39300
	s_mul_i32 s33, s33, s88
	s_addc_u32 s51, s31, 0
	s_mov_b32 s58, 1
	v_mov_b32_e32 v16, 0
	s_branch .LBB0_1429

.LBB0_1485:
	s_andn2_b64 vcc, exec, s[2:3]
	s_cbranch_vccnz .LBB0_1521
	s_waitcnt lgkmcnt(0)
	v_ashrrev_i32_e32 v1, 31, v8
	v_lshrrev_b32_e32 v1, 26, v1
	v_add_u32_e32 v1, v8, v1
	v_ashrrev_i32_e32 v9, 6, v1
	v_bfe_i32 v1, v8, 27, 1
	v_lshlrev_b32_e32 v0, 4, v8
	v_lshrrev_b32_e32 v1, 22, v1
	v_add_u32_e32 v1, v0, v1
	v_and_b32_e32 v1, 0xfffffc00, v1
	v_sub_u32_e32 v1, v0, v1
	v_lshrrev_b32_e32 v2, 4, v1
	v_bitop3_b32 v1, v2, v1, 32 bitop3:0x6c
	v_ashrrev_i32_e32 v3, 31, v1
	v_lshrrev_b32_e32 v3, 26, v3
	v_add_u32_e32 v3, v1, v3
	v_lshlrev_b32_e32 v2, 3, v9
	v_ashrrev_i32_e32 v10, 6, v3
	v_and_b32_e32 v3, 0xc0, v3
	v_and_b32_e32 v2, -16, v2
	v_sub_u32_e32 v1, v1, v3
	v_mov_b32_e32 v3, 1
	v_add_u32_e32 v2, v10, v2
	v_ashrrev_i16_sdwa v1, v3, sext(v1) dst_sel:DWORD dst_unused:UNUSED_PAD src0_sel:DWORD src1_sel:BYTE_0
	v_lshlrev_b32_e32 v4, 5, v9
	v_bfe_i32 v11, v1, 0, 16
	v_lshlrev_b32_e32 v1, 1, v2
	v_lshrrev_b32_e32 v5, 2, v2
	v_and_b32_e32 v6, 3, v10
	s_mov_b32 s3, 0x1fffe0
	v_and_b32_e32 v4, 32, v4
	v_and_b32_e32 v1, 24, v1
	v_and_b32_e32 v5, 4, v5
	v_and_or_b32 v6, v2, s3, v6
	v_or3_b32 v1, v6, v5, v1
	v_add_lshl_u32 v4, v4, v11, 1
	v_add_u32_e32 v0, 0x2000, v0
	v_lshl_add_u32 v180, v1, 11, v4
	v_ashrrev_i32_e32 v1, 31, v0
	v_lshrrev_b32_e32 v1, 22, v1
	v_add_u32_e32 v1, v0, v1
	v_ashrrev_i32_e32 v12, 10, v1
	v_mul_i32_i24_e32 v1, 0x400, v12
	v_sub_u32_e32 v0, v0, v1
	v_lshrrev_b32_e32 v1, 4, v0
	v_bitop3_b32 v0, v1, v0, 32 bitop3:0x6c
	v_lshl_add_u32 v178, v2, 11, v4
	v_ashrrev_i32_e32 v2, 31, v0
	v_lshrrev_b32_e32 v2, 26, v2
	v_add_u32_e32 v2, v0, v2
	v_lshlrev_b32_e32 v1, 3, v12
	v_ashrrev_i32_e32 v13, 6, v2
	v_and_b32_e32 v2, 0xc0, v2
	v_and_b32_e32 v1, -16, v1
	v_sub_u32_e32 v0, v0, v2
	s_add_u32 s33, s30, 0x5000000
	v_add_u32_e32 v1, v13, v1
	v_ashrrev_i16_sdwa v0, v3, sext(v0) dst_sel:DWORD dst_unused:UNUSED_PAD src0_sel:DWORD src1_sel:BYTE_0
	v_and_b32_e32 v3, 3, v13
	s_addc_u32 s46, s31, 0
	v_and_or_b32 v3, v1, s3, v3
	s_ashr_i32 s3, s14, 6
	s_ashr_i32 s27, s26, 31
	s_ashr_i32 s25, s24, 31
	s_ashr_i32 s2, s14, 8
	s_lshl_b32 s47, s3, 10
	s_lshl_b64 s[4:5], s[26:27], 19
	s_lshl_b64 s[6:7], s[24:25], 19
	s_add_u32 s40, s33, s6
	v_lshlrev_b32_e32 v4, 5, v12
	v_bfe_i32 v14, v0, 0, 16
	v_lshlrev_b32_e32 v0, 1, v1
	v_lshrrev_b32_e32 v2, 2, v1
	s_addc_u32 s41, s46, s7
	s_add_i32 s27, s47, 0
	v_and_b32_e32 v4, 32, v4
	v_and_b32_e32 v0, 24, v0
	v_and_b32_e32 v2, 4, v2
	s_add_i32 m0, s27, 0x10000
	v_or3_b32 v0, v3, v2, v0
	v_add_lshl_u32 v2, v4, v14, 1
	global_load_lds_dwordx4 v180, s[40:41]
	s_add_i32 m0, s27, 0x12000
	v_lshl_add_u32 v184, v0, 11, v2
	s_add_u32 s6, s40, 0x40000
	global_load_lds_dwordx4 v184, s[40:41]
	s_addc_u32 s7, s41, 0
	s_add_i32 m0, s27, 0x14000
	v_lshl_add_u32 v182, v1, 11, v2
	global_load_lds_dwordx4 v180, s[6:7]
	s_add_i32 m0, s27, 0x16000
	s_add_u32 s34, s36, s4
	s_addc_u32 s35, s37, s5
	s_add_i32 s48, s27, 0x2000
	global_load_lds_dwordx4 v184, s[6:7]
	s_mov_b32 m0, s27
	s_add_u32 s4, s34, 0x40000
	global_load_lds_dwordx4 v178, s[34:35]
	s_mov_b32 m0, s48
	s_addc_u32 s5, s35, 0
	s_add_i32 s49, s27, 0x4000
	global_load_lds_dwordx4 v182, s[34:35]
	s_mov_b32 m0, s49
	s_add_i32 s50, s27, 0x6000
	global_load_lds_dwordx4 v178, s[4:5]
	s_mov_b32 m0, s50
	v_mov_b32_e32 v181, 0
	global_load_lds_dwordx4 v182, s[4:5]
	v_mov_b32_e32 v185, v181
	v_mov_b32_e32 v179, v181
	v_mov_b32_e32 v183, v181
	s_cmp_eq_u32 s2, 1
	s_mov_b32 s51, 0
	v_lshl_add_u64 v[6:7], s[40:41], 0, v[180:181]
	v_lshl_add_u64 v[4:5], s[40:41], 0, v[184:185]
	v_lshl_add_u64 v[0:1], s[34:35], 0, v[178:179]
	s_cselect_b64 s[6:7], -1, 0
	s_cmp_lg_u32 s2, 1
	v_lshl_add_u64 v[2:3], s[34:35], 0, v[182:183]
	s_cbranch_scc1 .LBB0_1488
	s_barrier
	s_setprio 1

.LBB0_1498:
	ds_read_b128 v[80:83], v208
	ds_read_b128 v[84:87], v208 offset:1024
	ds_read_b128 v[88:91], v208 offset:2048
	ds_read_b128 v[92:95], v208 offset:3072
	ds_read_b128 v[96:99], v209
	ds_read_b128 v[104:107], v209 offset:1024
	ds_read_b128 v[108:111], v209 offset:2048
	ds_read_b128 v[112:115], v209 offset:3072
	s_add_u32 s40, s34, 0xfffc0080
	s_addc_u32 s41, s35, -1
	s_cmp_eq_u32 s65, 12
	s_cselect_b32 s45, s19, s41
	s_cselect_b32 s44, s25, s40
	s_cselect_b32 s41, s17, s64
	s_cselect_b32 s40, s62, s63
	v_lshl_add_u64 v[202:203], s[34:35], 0, v[186:187]
	s_add_i32 m0, s27, 0xc000
	ds_read_b128 v[160:163], v210
	ds_read_b128 v[164:167], v210 offset:1024
	ds_read_b128 v[168:171], v210 offset:2048
	ds_read_b128 v[172:175], v210 offset:3072
	ds_read_b128 v[194:197], v210 offset:4096
	ds_read_b128 v[198:201], v210 offset:5120
	ds_read_b128 v[212:215], v210 offset:6144
	ds_read_b128 v[216:219], v210 offset:7168
	global_load_lds_dwordx4 v[202:203], off
	v_lshl_add_u64 v[202:203], s[34:35], 0, v[188:189]
	s_add_i32 m0, s27, 0xe000
	s_nop 0
	global_load_lds_dwordx4 v[202:203], off
	s_waitcnt vmcnt(8)
	s_waitcnt lgkmcnt(0)
	s_barrier
	s_waitcnt lgkmcnt(0)
	v_mfma_f32_16x16x32_f16 v[156:159], v[80:83], v[160:163], v[156:159]
	v_mfma_f32_16x16x32_f16 v[152:155], v[88:91], v[160:163], v[152:155]
	v_mfma_f32_16x16x32_f16 v[140:143], v[80:83], v[168:171], v[140:143]
	v_mfma_f32_16x16x32_f16 v[136:139], v[88:91], v[168:171], v[136:139]
	v_mfma_f32_16x16x32_f16 v[124:127], v[80:83], v[194:197], v[124:127]
	v_mfma_f32_16x16x32_f16 v[120:123], v[88:91], v[194:197], v[120:123]
	v_mfma_f32_16x16x32_f16 v[76:79], v[80:83], v[212:215], v[76:79]
	v_mfma_f32_16x16x32_f16 v[72:75], v[88:91], v[212:215], v[72:75]
	v_mfma_f32_16x16x32_f16 v[156:159], v[84:87], v[164:167], v[156:159]
	v_mfma_f32_16x16x32_f16 v[152:155], v[92:95], v[164:167], v[152:155]
	v_mfma_f32_16x16x32_f16 v[140:143], v[84:87], v[172:175], v[140:143]
	v_mfma_f32_16x16x32_f16 v[136:139], v[92:95], v[172:175], v[136:139]
	v_mfma_f32_16x16x32_f16 v[124:127], v[84:87], v[198:201], v[124:127]
	v_mfma_f32_16x16x32_f16 v[120:123], v[92:95], v[198:201], v[120:123]
	v_mfma_f32_16x16x32_f16 v[76:79], v[84:87], v[216:219], v[76:79]
	v_mfma_f32_16x16x32_f16 v[72:75], v[92:95], v[216:219], v[72:75]
	v_mfma_f32_16x16x32_f16 v[148:151], v[96:99], v[160:163], v[148:151]
	v_mfma_f32_16x16x32_f16 v[144:147], v[108:111], v[160:163], v[144:147]
	v_mfma_f32_16x16x32_f16 v[132:135], v[96:99], v[168:171], v[132:135]
	v_mfma_f32_16x16x32_f16 v[128:131], v[108:111], v[168:171], v[128:131]
	v_mfma_f32_16x16x32_f16 v[116:119], v[96:99], v[194:197], v[116:119]
	v_mfma_f32_16x16x32_f16 v[100:103], v[108:111], v[194:197], v[100:103]
	v_mfma_f32_16x16x32_f16 v[68:71], v[96:99], v[212:215], v[68:71]
	v_mfma_f32_16x16x32_f16 v[64:67], v[108:111], v[212:215], v[64:67]
	v_mfma_f32_16x16x32_f16 v[148:151], v[104:107], v[164:167], v[148:151]
	v_mfma_f32_16x16x32_f16 v[144:147], v[112:115], v[164:167], v[144:147]
	v_mfma_f32_16x16x32_f16 v[132:135], v[104:107], v[172:175], v[132:135]
	v_mfma_f32_16x16x32_f16 v[128:131], v[112:115], v[172:175], v[128:131]
	v_mfma_f32_16x16x32_f16 v[116:119], v[104:107], v[198:201], v[116:119]
	v_mfma_f32_16x16x32_f16 v[100:103], v[112:115], v[198:201], v[100:103]
	v_mfma_f32_16x16x32_f16 v[68:71], v[104:107], v[216:219], v[68:71]
	v_mfma_f32_16x16x32_f16 v[64:67], v[112:115], v[216:219], v[64:67]
	s_barrier
	s_add_i32 s66, s60, s47
	v_lshl_add_u64 v[202:203], s[40:41], 0, v[180:181]
	s_mov_b32 m0, s66
	ds_read_b128 v[160:163], v210 offset:16384
	ds_read_b128 v[164:167], v210 offset:17408
	ds_read_b128 v[168:171], v210 offset:18432
	ds_read_b128 v[172:175], v210 offset:19456
	ds_read_b128 v[194:197], v210 offset:20480
	ds_read_b128 v[198:201], v210 offset:21504
	ds_read_b128 v[212:215], v210 offset:22528
	ds_read_b128 v[216:219], v210 offset:23552
	global_load_lds_dwordx4 v[202:203], off
	s_add_i32 m0, s66, 0x2000
	s_add_u32 s66, s40, 0x40000
	v_lshl_add_u64 v[220:221], s[40:41], 0, v[184:185]
	s_addc_u32 s67, s41, 0
	s_add_i32 s68, s61, s47
	global_load_lds_dwordx4 v[220:221], off
	v_lshl_add_u64 v[222:223], s[66:67], 0, v[180:181]
	s_mov_b32 m0, s68
	v_lshl_add_u64 v[224:225], s[44:45], 0, v[182:183]
	global_load_lds_dwordx4 v[222:223], off
	v_lshl_add_u64 v[222:223], s[66:67], 0, v[184:185]
	s_add_i32 m0, s68, 0x2000
	s_nop 0
	global_load_lds_dwordx4 v[222:223], off
	v_lshl_add_u64 v[222:223], s[44:45], 0, v[178:179]
	s_mov_b32 m0, s27
	s_nop 0
	global_load_lds_dwordx4 v[222:223], off
	s_mov_b32 m0, s48
	s_nop 0
	global_load_lds_dwordx4 v[224:225], off
	s_waitcnt vmcnt(8)
	s_waitcnt lgkmcnt(0)
	s_barrier
	s_waitcnt lgkmcnt(0)
	v_mfma_f32_16x16x32_f16 v[60:63], v[80:83], v[160:163], v[60:63]
	v_mfma_f32_16x16x32_f16 v[56:59], v[88:91], v[160:163], v[56:59]
	v_mfma_f32_16x16x32_f16 v[44:47], v[80:83], v[168:171], v[44:47]
	v_mfma_f32_16x16x32_f16 v[40:43], v[88:91], v[168:171], v[40:43]
	v_mfma_f32_16x16x32_f16 v[28:31], v[80:83], v[194:197], v[28:31]
	v_mfma_f32_16x16x32_f16 v[24:27], v[88:91], v[194:197], v[24:27]
	v_mfma_f32_16x16x32_f16 v[12:15], v[80:83], v[212:215], v[12:15]
	v_mfma_f32_16x16x32_f16 v[8:11], v[88:91], v[212:215], v[8:11]
	v_mfma_f32_16x16x32_f16 v[60:63], v[84:87], v[164:167], v[60:63]
	v_mfma_f32_16x16x32_f16 v[56:59], v[92:95], v[164:167], v[56:59]
	v_mfma_f32_16x16x32_f16 v[44:47], v[84:87], v[172:175], v[44:47]
	v_mfma_f32_16x16x32_f16 v[40:43], v[92:95], v[172:175], v[40:43]
	v_mfma_f32_16x16x32_f16 v[28:31], v[84:87], v[198:201], v[28:31]
	v_mfma_f32_16x16x32_f16 v[24:27], v[92:95], v[198:201], v[24:27]
	v_mfma_f32_16x16x32_f16 v[12:15], v[84:87], v[216:219], v[12:15]
	v_mfma_f32_16x16x32_f16 v[8:11], v[92:95], v[216:219], v[8:11]
	v_mfma_f32_16x16x32_f16 v[52:55], v[96:99], v[160:163], v[52:55]
	v_mfma_f32_16x16x32_f16 v[48:51], v[108:111], v[160:163], v[48:51]
	v_mfma_f32_16x16x32_f16 v[36:39], v[96:99], v[168:171], v[36:39]
	v_mfma_f32_16x16x32_f16 v[32:35], v[108:111], v[168:171], v[32:35]
	v_mfma_f32_16x16x32_f16 v[20:23], v[96:99], v[194:197], v[20:23]
	v_mfma_f32_16x16x32_f16 v[16:19], v[108:111], v[194:197], v[16:19]
	v_mfma_f32_16x16x32_f16 v[4:7], v[96:99], v[212:215], v[4:7]
	v_mfma_f32_16x16x32_f16 v[0:3], v[108:111], v[212:215], v[0:3]
	v_mfma_f32_16x16x32_f16 v[52:55], v[104:107], v[164:167], v[52:55]
	v_mfma_f32_16x16x32_f16 v[48:51], v[112:115], v[164:167], v[48:51]
	v_mfma_f32_16x16x32_f16 v[36:39], v[104:107], v[172:175], v[36:39]
	v_mfma_f32_16x16x32_f16 v[32:35], v[112:115], v[172:175], v[32:35]
	v_mfma_f32_16x16x32_f16 v[20:23], v[104:107], v[198:201], v[20:23]
	v_mfma_f32_16x16x32_f16 v[16:19], v[112:115], v[198:201], v[16:19]
	v_mfma_f32_16x16x32_f16 v[4:7], v[104:107], v[216:219], v[4:7]
	v_mfma_f32_16x16x32_f16 v[0:3], v[112:115], v[216:219], v[0:3]
	s_barrier
	s_add_i32 s66, 0, 0x18000
	s_add_i32 s67, 0, 0x1c000
	v_add_u32_e32 v92, s66, v206
	v_add_u32_e32 v112, s67, v206
	ds_read_b128 v[80:83], v92
	ds_read_b128 v[84:87], v92 offset:1024
	ds_read_b128 v[88:91], v92 offset:2048
	ds_read_b128 v[92:95], v92 offset:3072
	ds_read_b128 v[96:99], v112
	ds_read_b128 v[104:107], v112 offset:1024
	ds_read_b128 v[108:111], v112 offset:2048
	ds_read_b128 v[112:115], v112 offset:3072
	s_add_u32 s44, s44, 0x40000
	s_addc_u32 s45, s45, 0
	s_mov_b32 m0, s49
	v_lshl_add_u64 v[226:227], s[44:45], 0, v[178:179]
	ds_read_b128 v[160:163], v210 offset:32768
	ds_read_b128 v[164:167], v210 offset:33792
	ds_read_b128 v[168:171], v210 offset:34816
	ds_read_b128 v[172:175], v210 offset:35840
	ds_read_b128 v[194:197], v210 offset:36864
	ds_read_b128 v[198:201], v210 offset:37888
	ds_read_b128 v[212:215], v210 offset:38912
	ds_read_b128 v[216:219], v210 offset:39936
	global_load_lds_dwordx4 v[226:227], off
	v_lshl_add_u64 v[226:227], s[44:45], 0, v[182:183]
	s_mov_b32 m0, s50
	s_nop 0
	global_load_lds_dwordx4 v[226:227], off
	s_waitcnt vmcnt(8)
	s_waitcnt lgkmcnt(0)
	s_barrier
	s_waitcnt lgkmcnt(0)
	v_mfma_f32_16x16x32_f16 v[156:159], v[80:83], v[160:163], v[156:159]
	v_mfma_f32_16x16x32_f16 v[152:155], v[88:91], v[160:163], v[152:155]
	v_mfma_f32_16x16x32_f16 v[140:143], v[80:83], v[168:171], v[140:143]
	v_mfma_f32_16x16x32_f16 v[136:139], v[88:91], v[168:171], v[136:139]
	v_mfma_f32_16x16x32_f16 v[124:127], v[80:83], v[194:197], v[124:127]
	v_mfma_f32_16x16x32_f16 v[120:123], v[88:91], v[194:197], v[120:123]
	v_mfma_f32_16x16x32_f16 v[76:79], v[80:83], v[212:215], v[76:79]
	v_mfma_f32_16x16x32_f16 v[72:75], v[88:91], v[212:215], v[72:75]
	v_mfma_f32_16x16x32_f16 v[156:159], v[84:87], v[164:167], v[156:159]
	v_mfma_f32_16x16x32_f16 v[152:155], v[92:95], v[164:167], v[152:155]
	v_mfma_f32_16x16x32_f16 v[140:143], v[84:87], v[172:175], v[140:143]
	v_mfma_f32_16x16x32_f16 v[136:139], v[92:95], v[172:175], v[136:139]
	v_mfma_f32_16x16x32_f16 v[124:127], v[84:87], v[198:201], v[124:127]
	v_mfma_f32_16x16x32_f16 v[120:123], v[92:95], v[198:201], v[120:123]
	v_mfma_f32_16x16x32_f16 v[76:79], v[84:87], v[216:219], v[76:79]
	v_mfma_f32_16x16x32_f16 v[72:75], v[92:95], v[216:219], v[72:75]
	v_mfma_f32_16x16x32_f16 v[148:151], v[96:99], v[160:163], v[148:151]
	v_mfma_f32_16x16x32_f16 v[144:147], v[108:111], v[160:163], v[144:147]
	v_mfma_f32_16x16x32_f16 v[132:135], v[96:99], v[168:171], v[132:135]
	v_mfma_f32_16x16x32_f16 v[128:131], v[108:111], v[168:171], v[128:131]
	v_mfma_f32_16x16x32_f16 v[116:119], v[96:99], v[194:197], v[116:119]
	v_mfma_f32_16x16x32_f16 v[100:103], v[108:111], v[194:197], v[100:103]
	v_mfma_f32_16x16x32_f16 v[68:71], v[96:99], v[212:215], v[68:71]
	v_mfma_f32_16x16x32_f16 v[64:67], v[108:111], v[212:215], v[64:67]
	v_mfma_f32_16x16x32_f16 v[148:151], v[104:107], v[164:167], v[148:151]
	v_mfma_f32_16x16x32_f16 v[144:147], v[112:115], v[164:167], v[144:147]
	v_mfma_f32_16x16x32_f16 v[132:135], v[104:107], v[172:175], v[132:135]
	v_mfma_f32_16x16x32_f16 v[128:131], v[112:115], v[172:175], v[128:131]
	v_mfma_f32_16x16x32_f16 v[116:119], v[104:107], v[198:201], v[116:119]
	v_mfma_f32_16x16x32_f16 v[100:103], v[112:115], v[198:201], v[100:103]
	v_mfma_f32_16x16x32_f16 v[68:71], v[104:107], v[216:219], v[68:71]
	v_mfma_f32_16x16x32_f16 v[64:67], v[112:115], v[216:219], v[64:67]
	s_barrier
	s_add_i32 s44, s66, s47
	v_lshl_add_u64 v[202:203], v[202:203], 0, s[12:13]
	s_mov_b32 m0, s44
	ds_read_b128 v[160:163], v210 offset:49152
	ds_read_b128 v[164:167], v210 offset:50176
	ds_read_b128 v[168:171], v210 offset:51200
	ds_read_b128 v[172:175], v210 offset:52224
	ds_read_b128 v[194:197], v210 offset:53248
	ds_read_b128 v[198:201], v210 offset:54272
	ds_read_b128 v[212:215], v210 offset:55296
	ds_read_b128 v[216:219], v210 offset:56320
	global_load_lds_dwordx4 v[202:203], off
	s_add_i32 m0, s44, 0x2000
	s_add_u32 s40, s40, 0x40080
	v_lshl_add_u64 v[202:203], v[220:221], 0, s[12:13]
	s_addc_u32 s41, s41, 0
	s_add_i32 s44, s67, s47
	global_load_lds_dwordx4 v[202:203], off
	v_lshl_add_u64 v[202:203], s[40:41], 0, v[180:181]
	s_mov_b32 m0, s44
	s_nop 0
	global_load_lds_dwordx4 v[202:203], off
	v_lshl_add_u64 v[202:203], s[40:41], 0, v[184:185]
	s_add_i32 m0, s44, 0x2000
	s_nop 0
	global_load_lds_dwordx4 v[202:203], off
	v_lshl_add_u64 v[202:203], v[222:223], 0, s[12:13]
	s_mov_b32 m0, s56
	s_nop 0
	global_load_lds_dwordx4 v[202:203], off
	v_lshl_add_u64 v[202:203], v[224:225], 0, s[12:13]
	s_mov_b32 m0, s57
	s_nop 0
	global_load_lds_dwordx4 v[202:203], off
	s_waitcnt vmcnt(8)
	s_waitcnt lgkmcnt(0)
	s_barrier
	s_waitcnt lgkmcnt(0)
	v_mfma_f32_16x16x32_f16 v[60:63], v[80:83], v[160:163], v[60:63]
	v_mfma_f32_16x16x32_f16 v[56:59], v[88:91], v[160:163], v[56:59]
	v_mfma_f32_16x16x32_f16 v[44:47], v[80:83], v[168:171], v[44:47]
	v_mfma_f32_16x16x32_f16 v[40:43], v[88:91], v[168:171], v[40:43]
	v_mfma_f32_16x16x32_f16 v[28:31], v[80:83], v[194:197], v[28:31]
	v_mfma_f32_16x16x32_f16 v[24:27], v[88:91], v[194:197], v[24:27]
	v_mfma_f32_16x16x32_f16 v[12:15], v[80:83], v[212:215], v[12:15]
	v_mfma_f32_16x16x32_f16 v[8:11], v[88:91], v[212:215], v[8:11]
	v_mfma_f32_16x16x32_f16 v[60:63], v[84:87], v[164:167], v[60:63]
	v_mfma_f32_16x16x32_f16 v[56:59], v[92:95], v[164:167], v[56:59]
	v_mfma_f32_16x16x32_f16 v[44:47], v[84:87], v[172:175], v[44:47]
	v_mfma_f32_16x16x32_f16 v[40:43], v[92:95], v[172:175], v[40:43]
	v_mfma_f32_16x16x32_f16 v[28:31], v[84:87], v[198:201], v[28:31]
	v_mfma_f32_16x16x32_f16 v[24:27], v[92:95], v[198:201], v[24:27]
	v_mfma_f32_16x16x32_f16 v[12:15], v[84:87], v[216:219], v[12:15]
	v_mfma_f32_16x16x32_f16 v[8:11], v[92:95], v[216:219], v[8:11]
	v_mfma_f32_16x16x32_f16 v[52:55], v[96:99], v[160:163], v[52:55]
	v_mfma_f32_16x16x32_f16 v[48:51], v[108:111], v[160:163], v[48:51]
	v_mfma_f32_16x16x32_f16 v[36:39], v[96:99], v[168:171], v[36:39]
	v_mfma_f32_16x16x32_f16 v[32:35], v[108:111], v[168:171], v[32:35]
	v_mfma_f32_16x16x32_f16 v[20:23], v[96:99], v[194:197], v[20:23]
	v_mfma_f32_16x16x32_f16 v[16:19], v[108:111], v[194:197], v[16:19]
	v_mfma_f32_16x16x32_f16 v[4:7], v[96:99], v[212:215], v[4:7]
	v_mfma_f32_16x16x32_f16 v[0:3], v[108:111], v[212:215], v[0:3]
	v_mfma_f32_16x16x32_f16 v[52:55], v[104:107], v[164:167], v[52:55]
	v_mfma_f32_16x16x32_f16 v[48:51], v[112:115], v[164:167], v[48:51]
	v_mfma_f32_16x16x32_f16 v[36:39], v[104:107], v[172:175], v[36:39]
	v_mfma_f32_16x16x32_f16 v[32:35], v[112:115], v[172:175], v[32:35]
	v_mfma_f32_16x16x32_f16 v[20:23], v[104:107], v[198:201], v[20:23]
	v_mfma_f32_16x16x32_f16 v[16:19], v[112:115], v[198:201], v[16:19]
	v_mfma_f32_16x16x32_f16 v[4:7], v[104:107], v[216:219], v[4:7]
	v_mfma_f32_16x16x32_f16 v[0:3], v[112:115], v[216:219], v[0:3]
	s_barrier
	s_add_i32 s65, s65, 2
	s_add_u32 s34, s34, 0x100
	s_addc_u32 s35, s35, 0
	s_add_u32 s63, s63, 0x100
	s_addc_u32 s64, s64, 0
	s_cmp_gt_u32 s65, 13
	s_cbranch_scc0 .LBB0_1498
	s_and_b64 vcc, exec, s[14:15]
	s_cbranch_vccz .LBB0_1501
	s_barrier

.LBB0_1521:
	s_cmp_lt_i32 s91, 22
	s_cselect_b64 s[2:3], -1, 0
	s_xor_b64 s[0:1], s[0:1], -1
	s_or_b64 s[0:1], s[0:1], s[2:3]
	s_and_b64 vcc, exec, s[0:1]
	s_cbranch_vccnz .LBB0_1575
	s_waitcnt vmcnt(0)
	s_waitcnt lgkmcnt(0)
	s_setprio 0
	s_barrier
	s_and_saveexec_b64 s[0:1], s[92:93]
	s_cbranch_execz .LBB0_1574
	s_add_i32 s2, 0, 0x27ff0
	s_waitcnt vmcnt(5)
	v_mov_b32_e32 v0, s2
	s_waitcnt vmcnt(0) expcnt(0) lgkmcnt(0)
	ds_read_b32 v2, v0
	s_add_i32 s2, 0, 0x27ff4
	v_mov_b32_e32 v0, s2
	ds_read_b32 v0, v0
	s_waitcnt lgkmcnt(1)
	v_cmp_ne_u32_e32 vcc, 0, v2
	s_cbranch_vccnz .LBB0_1538
	s_add_u32 s2, s30, 0x38200
	s_addc_u32 s3, s31, 0
	s_add_u32 s4, s30, 0x38400
	s_addc_u32 s5, s31, 0
	s_add_u32 s6, s30, 0x38500
	s_addc_u32 s7, s31, 0
	s_add_u32 s10, s30, 0x38600
	s_addc_u32 s11, s31, 0
	s_add_u32 s12, s30, 0x38700
	s_addc_u32 s13, s31, 0
	s_add_u32 s14, s30, 0x38800
	s_addc_u32 s15, s31, 0
	s_add_u32 s16, s30, 0x38900
	s_addc_u32 s17, s31, 0
	s_add_u32 s18, s30, 0x38a00
	s_addc_u32 s19, s31, 0
	s_add_u32 s20, s30, 0x38b00
	s_addc_u32 s21, s31, 0
	s_add_u32 s22, s30, 0x38c00
	s_addc_u32 s23, s31, 0
	s_add_u32 s24, s30, 0x38d00
	s_addc_u32 s25, s31, 0
	s_add_u32 s26, s30, 0x38e00
	s_addc_u32 s27, s31, 0
	s_add_u32 s34, s30, 0x38f00
	s_addc_u32 s35, s31, 0
	s_add_u32 s40, s30, 0x39000
	s_addc_u32 s41, s31, 0
	s_add_u32 s44, s30, 0x39100
	s_addc_u32 s45, s31, 0
	s_add_u32 s46, s30, 0x39200
	s_addc_u32 s47, s31, 0
	s_mul_i32 s33, s89, s9
	s_add_u32 s48, s30, 0x39300
	s_mul_i32 s33, s33, s88
	s_addc_u32 s49, s31, 0
	s_mov_b32 s56, 1
	v_mov_b32_e32 v16, 0
	s_branch .LBB0_1526

.LBB0_1575:
	s_cmp_lt_i32 s90, 23
	s_cselect_b64 s[0:1], -1, 0
	s_cmp_gt_i32 s90, 22
	s_cselect_b64 s[2:3], -1, 0
	s_cmp_lt_i32 s91, 23
	s_cselect_b64 s[4:5], -1, 0
	s_or_b64 s[2:3], s[2:3], s[4:5]
	s_and_b64 vcc, exec, s[2:3]
	s_cbranch_vccnz .LBB0_1592
	s_waitcnt vmcnt(4)
	v_mov_b32_e32 v10, v204
	s_cmpk_gt_i32 s8, 0x57f
	v_readfirstlane_b32 s3, v10
	s_cbranch_scc1 .LBB0_1592
	v_lshlrev_b32_e32 v0, 4, v10
	s_waitcnt lgkmcnt(0)
	v_add_u32_e32 v1, 0x2000, v0
	v_ashrrev_i32_e32 v2, 31, v1
	v_lshrrev_b32_e32 v2, 22, v2
	v_add_u32_e32 v2, v1, v2
	v_ashrrev_i32_e32 v8, 10, v2
	v_mul_i32_i24_e32 v2, 0x400, v8
	v_sub_u32_e32 v1, v1, v2
	v_lshrrev_b32_e32 v2, 4, v1
	v_bitop3_b32 v1, v2, v1, 32 bitop3:0x6c
	v_ashrrev_i32_e32 v2, 31, v1
	v_lshrrev_b32_e32 v2, 26, v2
	v_add_u32_e32 v2, v1, v2
	v_lshlrev_b32_e32 v3, 3, v8
	v_ashrrev_i32_e32 v9, 6, v2
	v_and_b32_e32 v3, -16, v3
	v_add_u32_e32 v3, v9, v3
	v_and_b32_e32 v4, 3, v9
	s_mov_b32 s2, 0x1fffe0
	v_lshrrev_b32_e32 v5, 2, v3
	v_lshlrev_b32_e32 v6, 1, v3
	v_and_b32_e32 v2, 0xc0, v2
	v_and_or_b32 v4, v3, s2, v4
	v_and_b32_e32 v5, 4, v5
	v_and_b32_e32 v6, 24, v6
	v_sub_u32_e32 v1, v1, v2
	v_mov_b32_e32 v2, 1
	v_or3_b32 v4, v4, v5, v6
	v_lshlrev_b32_e32 v5, 5, v8
	v_ashrrev_i16_sdwa v1, v2, sext(v1) dst_sel:DWORD dst_unused:UNUSED_PAD src0_sel:DWORD src1_sel:BYTE_0
	v_and_b32_e32 v5, 32, v5
	v_bfe_i32 v11, v1, 0, 16
	v_add_lshl_u32 v1, v5, v11, 1
	v_lshl_add_u32 v144, v4, 11, v1
	v_lshl_add_u32 v146, v3, 11, v1
	v_bfe_i32 v1, v10, 27, 1
	v_lshrrev_b32_e32 v1, 22, v1
	v_add_u32_e32 v1, v0, v1
	v_and_b32_e32 v1, 0xfffffc00, v1
	v_sub_u32_e32 v0, v0, v1
	v_lshrrev_b32_e32 v1, 4, v0
	v_ashrrev_i32_e32 v3, 31, v10
	v_bitop3_b32 v0, v1, v0, 32 bitop3:0x6c
	v_lshrrev_b32_e32 v3, 26, v3
	v_ashrrev_i32_e32 v1, 31, v0
	v_add_u32_e32 v3, v10, v3
	v_lshrrev_b32_e32 v1, 26, v1
	v_ashrrev_i32_e32 v13, 6, v3
	v_add_u32_e32 v1, v0, v1
	v_lshlrev_b32_e32 v3, 3, v13
	s_add_u32 s33, s30, 0x2300000
	v_ashrrev_i32_e32 v12, 6, v1
	v_and_b32_e32 v3, -16, v3
	s_addc_u32 s40, s31, 0
	v_add_u32_e32 v3, v12, v3
	v_and_b32_e32 v4, 3, v12
	s_ashr_i32 s44, s8, 31
	v_and_or_b32 v4, v3, s2, v4
	s_lshr_b32 s2, s44, 29
	s_add_i32 s2, s8, s2
	s_ashr_i32 s10, s3, 6
	s_ashr_i32 s4, s2, 3
	s_and_b32 s2, s2, -8
	s_ashr_i32 s12, s3, 8
	s_lshl_b32 s41, s10, 10
	s_sub_i32 s2, s8, s2
	s_cmp_lt_i32 s2, 0
	s_movk_i32 s45, 0xb1
	s_cselect_b32 s5, s45, 0xb0
	s_mul_i32 s2, s2, s5
	s_add_i32 s2, s2, s4
	s_mul_hi_i32 s4, s2, 0x2e8ba2e9
	s_lshr_b32 s5, s4, 31
	s_ashr_i32 s4, s4, 5
	s_add_i32 s4, s4, s5
	s_lshl_b32 s5, s4, 3
	s_mulk_i32 s4, 0xb0
	s_sub_i32 s4, s2, s4
	s_sext_i32_i16 s2, s4
	s_bfe_u32 s2, s2, 0x3001c
	s_add_i32 s6, s4, s2
	s_sext_i32_i16 s2, s6
	s_and_b32 s6, s6, 0xfff8
	s_sub_i32 s4, s4, s6
	s_sext_i32_i16 s4, s4
	v_lshrrev_b32_e32 v5, 2, v3
	v_lshlrev_b32_e32 v6, 1, v3
	v_and_b32_e32 v1, 0xc0, v1
	s_lshr_b32 s2, s2, 3
	s_add_i32 s22, s5, s4
	v_and_b32_e32 v5, 4, v5
	v_and_b32_e32 v6, 24, v6
	v_sub_u32_e32 v0, v0, v1
	s_ashr_i32 s23, s22, 31
	s_bfe_i64 s[6:7], s[2:3], 0x100000
	v_or3_b32 v4, v4, v5, v6
	v_lshlrev_b32_e32 v5, 5, v13
	v_ashrrev_i16_sdwa v0, v2, sext(v0) dst_sel:DWORD dst_unused:UNUSED_PAD src0_sel:DWORD src1_sel:BYTE_0
	s_lshl_b64 s[4:5], s[22:23], 19
	s_lshl_b64 s[6:7], s[6:7], 19
	v_and_b32_e32 v5, 32, v5
	v_bfe_i32 v14, v0, 0, 16
	s_add_u32 s26, s33, s6
	v_add_lshl_u32 v0, v5, v14, 1
	s_addc_u32 s27, s40, s7
	s_add_i32 s23, s41, 0
	v_lshl_add_u32 v148, v4, 11, v0
	s_add_i32 m0, s23, 0x10000
	v_lshl_add_u32 v150, v3, 11, v0
	global_load_lds_dwordx4 v148, s[26:27]
	s_add_i32 m0, s23, 0x12000
	s_add_u32 s6, s26, 0x40000
	global_load_lds_dwordx4 v144, s[26:27]
	s_addc_u32 s7, s27, 0
	s_add_i32 m0, s23, 0x14000
	v_mov_b32_e32 v149, 0
	global_load_lds_dwordx4 v148, s[6:7]
	s_add_i32 m0, s23, 0x16000
	s_add_u32 s24, s42, s4
	s_addc_u32 s25, s43, s5
	s_add_i32 s46, s23, 0x2000
	global_load_lds_dwordx4 v144, s[6:7]
	s_mov_b32 m0, s23
	s_add_u32 s4, s24, 0x40000
	global_load_lds_dwordx4 v150, s[24:25]
	s_mov_b32 m0, s46
	s_addc_u32 s5, s25, 0
	s_add_i32 s47, s23, 0x4000
	global_load_lds_dwordx4 v146, s[24:25]
	s_mov_b32 m0, s47
	s_add_i32 s48, s23, 0x6000
	global_load_lds_dwordx4 v150, s[4:5]
	s_mov_b32 m0, s48
	v_mov_b32_e32 v145, v149
	global_load_lds_dwordx4 v146, s[4:5]
	v_mov_b32_e32 v151, v149
	v_mov_b32_e32 v147, v149
	s_cmp_eq_u32 s12, 1
	s_mov_b32 s49, 0
	v_lshl_add_u64 v[6:7], s[26:27], 0, v[148:149]
	v_lshl_add_u64 v[4:5], s[26:27], 0, v[144:145]
	v_lshl_add_u64 v[0:1], s[24:25], 0, v[150:151]
	s_cselect_b64 s[4:5], -1, 0
	s_cmp_lg_u32 s12, 1
	v_lshl_add_u64 v[2:3], s[24:25], 0, v[146:147]
	s_cbranch_scc1 .LBB0_1579
	s_barrier
	s_setprio 1

.LBB0_1585:
	ds_read_b128 v[104:107], v171
	ds_read_b128 v[108:111], v171 offset:1024
	ds_read_b128 v[112:115], v171 offset:2048
	ds_read_b128 v[116:119], v171 offset:3072
	ds_read_b128 v[160:163], v172
	ds_read_b128 v[164:167], v172 offset:1024
	ds_read_b128 v[178:181], v172 offset:2048
	ds_read_b128 v[182:185], v172 offset:3072
	s_add_u32 s26, s24, 0xfffc0080
	s_addc_u32 s27, s25, -1
	s_cmp_eq_u32 s64, 12
	s_cselect_b32 s35, s17, s27
	s_cselect_b32 s34, s60, s26
	s_cselect_b32 s27, s15, s63
	s_cselect_b32 s26, s61, s62
	v_lshl_add_u64 v[202:203], s[24:25], 0, v[152:153]
	s_add_i32 m0, s23, 0xc000
	ds_read_b128 v[186:189], v173
	ds_read_b128 v[190:193], v173 offset:1024
	ds_read_b128 v[194:197], v173 offset:2048
	ds_read_b128 v[198:201], v173 offset:3072
	ds_read_b128 v[206:209], v173 offset:4096
	ds_read_b128 v[210:213], v173 offset:5120
	ds_read_b128 v[214:217], v173 offset:6144
	ds_read_b128 v[218:221], v173 offset:7168
	global_load_lds_dwordx4 v[202:203], off
	v_lshl_add_u64 v[202:203], s[24:25], 0, v[154:155]
	s_add_i32 m0, s23, 0xe000
	s_nop 0
	global_load_lds_dwordx4 v[202:203], off
	s_waitcnt vmcnt(8)
	s_waitcnt lgkmcnt(0)
	s_barrier
	s_waitcnt lgkmcnt(0)
	v_mfma_f32_16x16x32_f16 v[140:143], v[104:107], v[186:189], v[140:143]
	v_mfma_f32_16x16x32_f16 v[136:139], v[112:115], v[186:189], v[136:139]
	v_mfma_f32_16x16x32_f16 v[124:127], v[104:107], v[194:197], v[124:127]
	v_mfma_f32_16x16x32_f16 v[120:123], v[112:115], v[194:197], v[120:123]
	v_mfma_f32_16x16x32_f16 v[92:95], v[104:107], v[206:209], v[92:95]
	v_mfma_f32_16x16x32_f16 v[88:91], v[112:115], v[206:209], v[88:91]
	v_mfma_f32_16x16x32_f16 v[76:79], v[104:107], v[214:217], v[76:79]
	v_mfma_f32_16x16x32_f16 v[72:75], v[112:115], v[214:217], v[72:75]
	v_mfma_f32_16x16x32_f16 v[140:143], v[108:111], v[190:193], v[140:143]
	v_mfma_f32_16x16x32_f16 v[136:139], v[116:119], v[190:193], v[136:139]
	v_mfma_f32_16x16x32_f16 v[124:127], v[108:111], v[198:201], v[124:127]
	v_mfma_f32_16x16x32_f16 v[120:123], v[116:119], v[198:201], v[120:123]
	v_mfma_f32_16x16x32_f16 v[92:95], v[108:111], v[210:213], v[92:95]
	v_mfma_f32_16x16x32_f16 v[88:91], v[116:119], v[210:213], v[88:91]
	v_mfma_f32_16x16x32_f16 v[76:79], v[108:111], v[218:221], v[76:79]
	v_mfma_f32_16x16x32_f16 v[72:75], v[116:119], v[218:221], v[72:75]
	v_mfma_f32_16x16x32_f16 v[132:135], v[160:163], v[186:189], v[132:135]
	v_mfma_f32_16x16x32_f16 v[128:131], v[178:181], v[186:189], v[128:131]
	v_mfma_f32_16x16x32_f16 v[100:103], v[160:163], v[194:197], v[100:103]
	v_mfma_f32_16x16x32_f16 v[96:99], v[178:181], v[194:197], v[96:99]
	v_mfma_f32_16x16x32_f16 v[84:87], v[160:163], v[206:209], v[84:87]
	v_mfma_f32_16x16x32_f16 v[80:83], v[178:181], v[206:209], v[80:83]
	v_mfma_f32_16x16x32_f16 v[68:71], v[160:163], v[214:217], v[68:71]
	v_mfma_f32_16x16x32_f16 v[64:67], v[178:181], v[214:217], v[64:67]
	v_mfma_f32_16x16x32_f16 v[132:135], v[164:167], v[190:193], v[132:135]
	v_mfma_f32_16x16x32_f16 v[128:131], v[182:185], v[190:193], v[128:131]
	v_mfma_f32_16x16x32_f16 v[100:103], v[164:167], v[198:201], v[100:103]
	v_mfma_f32_16x16x32_f16 v[96:99], v[182:185], v[198:201], v[96:99]
	v_mfma_f32_16x16x32_f16 v[84:87], v[164:167], v[210:213], v[84:87]
	v_mfma_f32_16x16x32_f16 v[80:83], v[182:185], v[210:213], v[80:83]
	v_mfma_f32_16x16x32_f16 v[68:71], v[164:167], v[218:221], v[68:71]
	v_mfma_f32_16x16x32_f16 v[64:67], v[182:185], v[218:221], v[64:67]
	s_barrier
	s_add_i32 s65, s55, s41
	v_lshl_add_u64 v[202:203], s[26:27], 0, v[148:149]
	s_mov_b32 m0, s65
	ds_read_b128 v[186:189], v173 offset:16384
	ds_read_b128 v[190:193], v173 offset:17408
	ds_read_b128 v[194:197], v173 offset:18432
	ds_read_b128 v[198:201], v173 offset:19456
	ds_read_b128 v[206:209], v173 offset:20480
	ds_read_b128 v[210:213], v173 offset:21504
	ds_read_b128 v[214:217], v173 offset:22528
	ds_read_b128 v[218:221], v173 offset:23552
	global_load_lds_dwordx4 v[202:203], off
	s_add_i32 m0, s65, 0x2000
	s_add_u32 s66, s26, 0x40000
	v_lshl_add_u64 v[222:223], s[26:27], 0, v[144:145]
	s_addc_u32 s67, s27, 0
	s_add_i32 s65, s56, s41
	global_load_lds_dwordx4 v[222:223], off
	v_lshl_add_u64 v[224:225], s[66:67], 0, v[148:149]
	s_mov_b32 m0, s65
	v_lshl_add_u64 v[226:227], s[34:35], 0, v[146:147]
	global_load_lds_dwordx4 v[224:225], off
	v_lshl_add_u64 v[224:225], s[66:67], 0, v[144:145]
	s_add_i32 m0, s65, 0x2000
	s_nop 0
	global_load_lds_dwordx4 v[224:225], off
	v_lshl_add_u64 v[224:225], s[34:35], 0, v[150:151]
	s_mov_b32 m0, s23
	s_nop 0
	global_load_lds_dwordx4 v[224:225], off
	s_mov_b32 m0, s46
	s_nop 0
	global_load_lds_dwordx4 v[226:227], off
	s_waitcnt vmcnt(8)
	s_waitcnt lgkmcnt(0)
	s_barrier
	s_waitcnt lgkmcnt(0)
	v_mfma_f32_16x16x32_f16 v[60:63], v[104:107], v[186:189], v[60:63]
	v_mfma_f32_16x16x32_f16 v[56:59], v[112:115], v[186:189], v[56:59]
	v_mfma_f32_16x16x32_f16 v[44:47], v[104:107], v[194:197], v[44:47]
	v_mfma_f32_16x16x32_f16 v[40:43], v[112:115], v[194:197], v[40:43]
	v_mfma_f32_16x16x32_f16 v[28:31], v[104:107], v[206:209], v[28:31]
	v_mfma_f32_16x16x32_f16 v[24:27], v[112:115], v[206:209], v[24:27]
	v_mfma_f32_16x16x32_f16 v[12:15], v[104:107], v[214:217], v[12:15]
	v_mfma_f32_16x16x32_f16 v[8:11], v[112:115], v[214:217], v[8:11]
	v_mfma_f32_16x16x32_f16 v[60:63], v[108:111], v[190:193], v[60:63]
	v_mfma_f32_16x16x32_f16 v[56:59], v[116:119], v[190:193], v[56:59]
	v_mfma_f32_16x16x32_f16 v[44:47], v[108:111], v[198:201], v[44:47]
	v_mfma_f32_16x16x32_f16 v[40:43], v[116:119], v[198:201], v[40:43]
	v_mfma_f32_16x16x32_f16 v[28:31], v[108:111], v[210:213], v[28:31]
	v_mfma_f32_16x16x32_f16 v[24:27], v[116:119], v[210:213], v[24:27]
	v_mfma_f32_16x16x32_f16 v[12:15], v[108:111], v[218:221], v[12:15]
	v_mfma_f32_16x16x32_f16 v[8:11], v[116:119], v[218:221], v[8:11]
	v_mfma_f32_16x16x32_f16 v[52:55], v[160:163], v[186:189], v[52:55]
	v_mfma_f32_16x16x32_f16 v[48:51], v[178:181], v[186:189], v[48:51]
	v_mfma_f32_16x16x32_f16 v[36:39], v[160:163], v[194:197], v[36:39]
	v_mfma_f32_16x16x32_f16 v[32:35], v[178:181], v[194:197], v[32:35]
	v_mfma_f32_16x16x32_f16 v[20:23], v[160:163], v[206:209], v[20:23]
	v_mfma_f32_16x16x32_f16 v[16:19], v[178:181], v[206:209], v[16:19]
	v_mfma_f32_16x16x32_f16 v[4:7], v[160:163], v[214:217], v[4:7]
	v_mfma_f32_16x16x32_f16 v[0:3], v[178:181], v[214:217], v[0:3]
	v_mfma_f32_16x16x32_f16 v[52:55], v[164:167], v[190:193], v[52:55]
	v_mfma_f32_16x16x32_f16 v[48:51], v[182:185], v[190:193], v[48:51]
	v_mfma_f32_16x16x32_f16 v[36:39], v[164:167], v[198:201], v[36:39]
	v_mfma_f32_16x16x32_f16 v[32:35], v[182:185], v[198:201], v[32:35]
	v_mfma_f32_16x16x32_f16 v[20:23], v[164:167], v[210:213], v[20:23]
	v_mfma_f32_16x16x32_f16 v[16:19], v[182:185], v[210:213], v[16:19]
	v_mfma_f32_16x16x32_f16 v[4:7], v[164:167], v[218:221], v[4:7]
	v_mfma_f32_16x16x32_f16 v[0:3], v[182:185], v[218:221], v[0:3]
	s_barrier
	s_add_i32 s65, 0, 0x18000
	s_add_i32 s66, 0, 0x1c000
	v_add_u32_e32 v116, s65, v169
	v_add_u32_e32 v177, s66, v169
	ds_read_b128 v[104:107], v116
	ds_read_b128 v[108:111], v116 offset:1024
	ds_read_b128 v[112:115], v116 offset:2048
	ds_read_b128 v[116:119], v116 offset:3072
	ds_read_b128 v[160:163], v177
	ds_read_b128 v[164:167], v177 offset:1024
	ds_read_b128 v[178:181], v177 offset:2048
	ds_read_b128 v[182:185], v177 offset:3072
	s_add_u32 s34, s34, 0x40000
	s_addc_u32 s35, s35, 0
	s_mov_b32 m0, s47
	v_lshl_add_u64 v[228:229], s[34:35], 0, v[150:151]
	ds_read_b128 v[186:189], v173 offset:32768
	ds_read_b128 v[190:193], v173 offset:33792
	ds_read_b128 v[194:197], v173 offset:34816
	ds_read_b128 v[198:201], v173 offset:35840
	ds_read_b128 v[206:209], v173 offset:36864
	ds_read_b128 v[210:213], v173 offset:37888
	ds_read_b128 v[214:217], v173 offset:38912
	ds_read_b128 v[218:221], v173 offset:39936
	global_load_lds_dwordx4 v[228:229], off
	v_lshl_add_u64 v[228:229], s[34:35], 0, v[146:147]
	s_mov_b32 m0, s48
	s_nop 0
	global_load_lds_dwordx4 v[228:229], off
	s_waitcnt vmcnt(8)
	s_waitcnt lgkmcnt(0)
	s_barrier
	s_waitcnt lgkmcnt(0)
	v_mfma_f32_16x16x32_f16 v[140:143], v[104:107], v[186:189], v[140:143]
	v_mfma_f32_16x16x32_f16 v[136:139], v[112:115], v[186:189], v[136:139]
	v_mfma_f32_16x16x32_f16 v[124:127], v[104:107], v[194:197], v[124:127]
	v_mfma_f32_16x16x32_f16 v[120:123], v[112:115], v[194:197], v[120:123]
	v_mfma_f32_16x16x32_f16 v[92:95], v[104:107], v[206:209], v[92:95]
	v_mfma_f32_16x16x32_f16 v[88:91], v[112:115], v[206:209], v[88:91]
	v_mfma_f32_16x16x32_f16 v[76:79], v[104:107], v[214:217], v[76:79]
	v_mfma_f32_16x16x32_f16 v[72:75], v[112:115], v[214:217], v[72:75]
	v_mfma_f32_16x16x32_f16 v[140:143], v[108:111], v[190:193], v[140:143]
	v_mfma_f32_16x16x32_f16 v[136:139], v[116:119], v[190:193], v[136:139]
	v_mfma_f32_16x16x32_f16 v[124:127], v[108:111], v[198:201], v[124:127]
	v_mfma_f32_16x16x32_f16 v[120:123], v[116:119], v[198:201], v[120:123]
	v_mfma_f32_16x16x32_f16 v[92:95], v[108:111], v[210:213], v[92:95]
	v_mfma_f32_16x16x32_f16 v[88:91], v[116:119], v[210:213], v[88:91]
	v_mfma_f32_16x16x32_f16 v[76:79], v[108:111], v[218:221], v[76:79]
	v_mfma_f32_16x16x32_f16 v[72:75], v[116:119], v[218:221], v[72:75]
	v_mfma_f32_16x16x32_f16 v[132:135], v[160:163], v[186:189], v[132:135]
	v_mfma_f32_16x16x32_f16 v[128:131], v[178:181], v[186:189], v[128:131]
	v_mfma_f32_16x16x32_f16 v[100:103], v[160:163], v[194:197], v[100:103]
	v_mfma_f32_16x16x32_f16 v[96:99], v[178:181], v[194:197], v[96:99]
	v_mfma_f32_16x16x32_f16 v[84:87], v[160:163], v[206:209], v[84:87]
	v_mfma_f32_16x16x32_f16 v[80:83], v[178:181], v[206:209], v[80:83]
	v_mfma_f32_16x16x32_f16 v[68:71], v[160:163], v[214:217], v[68:71]
	v_mfma_f32_16x16x32_f16 v[64:67], v[178:181], v[214:217], v[64:67]
	v_mfma_f32_16x16x32_f16 v[132:135], v[164:167], v[190:193], v[132:135]
	v_mfma_f32_16x16x32_f16 v[128:131], v[182:185], v[190:193], v[128:131]
	v_mfma_f32_16x16x32_f16 v[100:103], v[164:167], v[198:201], v[100:103]
	v_mfma_f32_16x16x32_f16 v[96:99], v[182:185], v[198:201], v[96:99]
	v_mfma_f32_16x16x32_f16 v[84:87], v[164:167], v[210:213], v[84:87]
	v_mfma_f32_16x16x32_f16 v[80:83], v[182:185], v[210:213], v[80:83]
	v_mfma_f32_16x16x32_f16 v[68:71], v[164:167], v[218:221], v[68:71]
	v_mfma_f32_16x16x32_f16 v[64:67], v[182:185], v[218:221], v[64:67]
	s_barrier
	s_add_i32 s34, s65, s41
	v_lshl_add_u64 v[202:203], v[202:203], 0, s[10:11]
	s_mov_b32 m0, s34
	ds_read_b128 v[186:189], v173 offset:49152
	ds_read_b128 v[190:193], v173 offset:50176
	ds_read_b128 v[194:197], v173 offset:51200
	ds_read_b128 v[198:201], v173 offset:52224
	ds_read_b128 v[206:209], v173 offset:53248
	ds_read_b128 v[210:213], v173 offset:54272
	ds_read_b128 v[214:217], v173 offset:55296
	ds_read_b128 v[218:221], v173 offset:56320
	global_load_lds_dwordx4 v[202:203], off
	s_add_i32 m0, s34, 0x2000
	s_add_u32 s26, s26, 0x40080
	v_lshl_add_u64 v[202:203], v[222:223], 0, s[10:11]
	s_addc_u32 s27, s27, 0
	s_add_i32 s34, s66, s41
	global_load_lds_dwordx4 v[202:203], off
	v_lshl_add_u64 v[202:203], s[26:27], 0, v[148:149]
	s_mov_b32 m0, s34
	s_nop 0
	global_load_lds_dwordx4 v[202:203], off
	v_lshl_add_u64 v[202:203], s[26:27], 0, v[144:145]
	s_add_i32 m0, s34, 0x2000
	s_nop 0
	global_load_lds_dwordx4 v[202:203], off
	v_lshl_add_u64 v[202:203], v[224:225], 0, s[10:11]
	s_mov_b32 m0, s52
	s_nop 0
	global_load_lds_dwordx4 v[202:203], off
	v_lshl_add_u64 v[202:203], v[226:227], 0, s[10:11]
	s_mov_b32 m0, s53
	s_nop 0
	global_load_lds_dwordx4 v[202:203], off
	s_waitcnt vmcnt(8)
	s_waitcnt lgkmcnt(0)
	s_barrier
	s_waitcnt lgkmcnt(0)
	v_mfma_f32_16x16x32_f16 v[60:63], v[104:107], v[186:189], v[60:63]
	v_mfma_f32_16x16x32_f16 v[56:59], v[112:115], v[186:189], v[56:59]
	v_mfma_f32_16x16x32_f16 v[44:47], v[104:107], v[194:197], v[44:47]
	v_mfma_f32_16x16x32_f16 v[40:43], v[112:115], v[194:197], v[40:43]
	v_mfma_f32_16x16x32_f16 v[28:31], v[104:107], v[206:209], v[28:31]
	v_mfma_f32_16x16x32_f16 v[24:27], v[112:115], v[206:209], v[24:27]
	v_mfma_f32_16x16x32_f16 v[12:15], v[104:107], v[214:217], v[12:15]
	v_mfma_f32_16x16x32_f16 v[8:11], v[112:115], v[214:217], v[8:11]
	v_mfma_f32_16x16x32_f16 v[60:63], v[108:111], v[190:193], v[60:63]
	v_mfma_f32_16x16x32_f16 v[56:59], v[116:119], v[190:193], v[56:59]
	v_mfma_f32_16x16x32_f16 v[44:47], v[108:111], v[198:201], v[44:47]
	v_mfma_f32_16x16x32_f16 v[40:43], v[116:119], v[198:201], v[40:43]
	v_mfma_f32_16x16x32_f16 v[28:31], v[108:111], v[210:213], v[28:31]
	v_mfma_f32_16x16x32_f16 v[24:27], v[116:119], v[210:213], v[24:27]
	v_mfma_f32_16x16x32_f16 v[12:15], v[108:111], v[218:221], v[12:15]
	v_mfma_f32_16x16x32_f16 v[8:11], v[116:119], v[218:221], v[8:11]
	v_mfma_f32_16x16x32_f16 v[52:55], v[160:163], v[186:189], v[52:55]
	v_mfma_f32_16x16x32_f16 v[48:51], v[178:181], v[186:189], v[48:51]
	v_mfma_f32_16x16x32_f16 v[36:39], v[160:163], v[194:197], v[36:39]
	v_mfma_f32_16x16x32_f16 v[32:35], v[178:181], v[194:197], v[32:35]
	v_mfma_f32_16x16x32_f16 v[20:23], v[160:163], v[206:209], v[20:23]
	v_mfma_f32_16x16x32_f16 v[16:19], v[178:181], v[206:209], v[16:19]
	v_mfma_f32_16x16x32_f16 v[4:7], v[160:163], v[214:217], v[4:7]
	v_mfma_f32_16x16x32_f16 v[0:3], v[178:181], v[214:217], v[0:3]
	v_mfma_f32_16x16x32_f16 v[52:55], v[164:167], v[190:193], v[52:55]
	v_mfma_f32_16x16x32_f16 v[48:51], v[182:185], v[190:193], v[48:51]
	v_mfma_f32_16x16x32_f16 v[36:39], v[164:167], v[198:201], v[36:39]
	v_mfma_f32_16x16x32_f16 v[32:35], v[182:185], v[198:201], v[32:35]
	v_mfma_f32_16x16x32_f16 v[20:23], v[164:167], v[210:213], v[20:23]
	v_mfma_f32_16x16x32_f16 v[16:19], v[182:185], v[210:213], v[16:19]
	v_mfma_f32_16x16x32_f16 v[4:7], v[164:167], v[218:221], v[4:7]
	v_mfma_f32_16x16x32_f16 v[0:3], v[182:185], v[218:221], v[0:3]
	s_barrier
	s_add_i32 s64, s64, 2
	s_add_u32 s24, s24, 0x100
	s_addc_u32 s25, s25, 0
	s_add_u32 s62, s62, 0x100
	s_addc_u32 s63, s63, 0
	s_cmp_gt_u32 s64, 13
	s_cbranch_scc0 .LBB0_1585
	s_and_b64 vcc, exec, s[12:13]
	s_cbranch_vccz .LBB0_1588
	s_barrier

.LBB0_1592:
	s_cmp_gt_i32 s91, 23
	s_cselect_b64 s[2:3], -1, 0
	s_and_b64 s[0:1], s[0:1], s[2:3]
	s_andn2_b64 vcc, exec, s[0:1]
	s_cbranch_vccnz .LBB0_1646
	s_waitcnt vmcnt(0)
	s_waitcnt lgkmcnt(0)
	s_setprio 0
	s_barrier
	s_and_saveexec_b64 s[0:1], s[92:93]
	s_cbranch_execz .LBB0_1645
	s_add_i32 s4, 0, 0x27ff0
	s_waitcnt vmcnt(5)
	v_mov_b32_e32 v0, s4
	s_waitcnt vmcnt(0) expcnt(0) lgkmcnt(0)
	ds_read_b32 v2, v0
	s_add_i32 s4, 0, 0x27ff4
	v_mov_b32_e32 v0, s4
	ds_read_b32 v0, v0
	s_waitcnt lgkmcnt(1)
	v_cmp_ne_u32_e32 vcc, 0, v2
	s_cbranch_vccnz .LBB0_1609
	s_add_u32 s4, s30, 0x38200
	s_addc_u32 s5, s31, 0
	s_add_u32 s6, s30, 0x38400
	s_addc_u32 s7, s31, 0
	s_add_u32 s10, s30, 0x38500
	s_addc_u32 s11, s31, 0
	s_add_u32 s12, s30, 0x38600
	s_addc_u32 s13, s31, 0
	s_add_u32 s14, s30, 0x38700
	s_addc_u32 s15, s31, 0
	s_add_u32 s16, s30, 0x38800
	s_addc_u32 s17, s31, 0
	s_add_u32 s18, s30, 0x38900
	s_addc_u32 s19, s31, 0
	s_add_u32 s20, s30, 0x38a00
	s_addc_u32 s21, s31, 0
	s_add_u32 s22, s30, 0x38b00
	s_addc_u32 s23, s31, 0
	s_add_u32 s24, s30, 0x38c00
	s_addc_u32 s25, s31, 0
	s_add_u32 s26, s30, 0x38d00
	s_addc_u32 s27, s31, 0
	s_add_u32 s34, s30, 0x38e00
	s_addc_u32 s35, s31, 0
	s_add_u32 s40, s30, 0x38f00
	s_addc_u32 s41, s31, 0
	s_add_u32 s42, s30, 0x39000
	s_addc_u32 s43, s31, 0
	s_add_u32 s44, s30, 0x39100
	s_addc_u32 s45, s31, 0
	s_add_u32 s46, s30, 0x39200
	s_addc_u32 s47, s31, 0
	s_mul_i32 s33, s89, s9
	s_add_u32 s48, s30, 0x39300
	s_mul_i32 s33, s33, s88
	s_addc_u32 s49, s31, 0
	s_mov_b32 s56, 1
	v_mov_b32_e32 v16, 0
	s_branch .LBB0_1597

.LBB0_1652:
	s_waitcnt vmcnt(5) lgkmcnt(0)
	v_ashrrev_i32_e32 v1, 31, v204
	v_lshrrev_b32_e32 v1, 26, v1
	v_add_u32_e32 v1, v204, v1
	s_waitcnt vmcnt(4)
	v_ashrrev_i32_e32 v8, 6, v1
	v_bfe_i32 v1, v204, 27, 1
	v_lshlrev_b32_e32 v0, 4, v204
	v_lshrrev_b32_e32 v1, 22, v1
	v_add_u32_e32 v1, v0, v1
	v_and_b32_e32 v1, 0xfffffc00, v1
	v_sub_u32_e32 v1, v0, v1
	v_lshrrev_b32_e32 v2, 4, v1
	v_bitop3_b32 v1, v2, v1, 32 bitop3:0x6c
	v_ashrrev_i32_e32 v3, 31, v1
	v_lshrrev_b32_e32 v3, 26, v3
	v_lshlrev_b32_e32 v2, 3, v8
	v_add_u32_e32 v3, v1, v3
	v_and_b32_e32 v2, -16, v2
	v_ashrrev_i32_e32 v10, 6, v3
	v_and_b32_e32 v3, 0xc0, v3
	v_add_u32_e32 v2, v10, v2
	v_lshlrev_b32_e32 v4, 5, v8
	v_sub_u32_e32 v1, v1, v3
	v_mov_b32_e32 v3, 1
	v_and_b32_e32 v9, 32, v4
	v_ashrrev_i16_sdwa v1, v3, sext(v1) dst_sel:DWORD dst_unused:UNUSED_PAD src0_sel:DWORD src1_sel:BYTE_0
	v_lshlrev_b32_e32 v4, 1, v2
	v_lshrrev_b32_e32 v5, 2, v2
	v_and_b32_e32 v6, 3, v10
	s_mov_b32 s5, 0xffffe0
	v_bfe_i32 v11, v1, 0, 16
	v_and_b32_e32 v4, 24, v4
	v_and_b32_e32 v5, 4, v5
	v_and_or_b32 v6, v2, s5, v6
	s_movk_i32 s1, 0xb00
	v_add_u32_e32 v1, v9, v11
	v_or3_b32 v4, v6, v5, v4
	v_mul_lo_u32 v2, v2, s1
	v_add_lshl_u32 v128, v1, v2, 1
	v_mul_u32_u24_e32 v2, 0xb00, v4
	v_add_u32_e32 v0, 0x2000, v0
	v_add_lshl_u32 v130, v2, v1, 1
	v_ashrrev_i32_e32 v1, 31, v0
	v_lshrrev_b32_e32 v1, 22, v1
	v_add_u32_e32 v1, v0, v1
	v_ashrrev_i32_e32 v12, 10, v1
	v_mul_i32_i24_e32 v1, 0x400, v12
	v_sub_u32_e32 v0, v0, v1
	v_lshrrev_b32_e32 v1, 4, v0
	v_bitop3_b32 v0, v1, v0, 32 bitop3:0x6c
	s_add_u32 s34, s30, 0x3e80000
	v_ashrrev_i32_e32 v2, 31, v0
	s_addc_u32 s35, s31, 0
	v_lshrrev_b32_e32 v2, 26, v2
	s_add_i32 s3, s3, s4
	v_lshlrev_b32_e32 v1, 3, v12
	v_add_u32_e32 v2, v0, v2
	s_ashr_i32 s4, s3, 31
	v_and_b32_e32 v1, -16, v1
	v_ashrrev_i32_e32 v13, 6, v2
	v_lshlrev_b32_e32 v4, 5, v12
	s_lshr_b32 s4, s4, 27
	v_add_u32_e32 v1, v13, v1
	v_and_b32_e32 v14, 32, v4
	v_and_b32_e32 v4, 3, v13
	s_add_i32 s4, s3, s4
	v_and_or_b32 v4, v1, s5, v4
	s_ashr_i32 s5, s4, 5
	s_and_b32 s4, s4, 0xffe0
	s_sub_i32 s4, s3, s4
	s_bfe_i32 s3, s4, 0x80000
	s_bfe_u32 s3, s3, 0x3000c
	s_add_i32 s6, s4, s3
	s_bfe_i32 s3, s6, 0x80000
	s_and_b32 s6, s6, 0xf8
	s_sub_i32 s4, s4, s6
	s_lshl_b32 s5, s5, 3
	s_sext_i32_i16 s7, s3
	s_sext_i32_i8 s4, s4
	v_and_b32_e32 v2, 0xc0, v2
	s_ashr_i32 s10, s2, 6
	s_add_i32 s56, s5, s4
	s_ashr_i32 s4, s7, 3
	s_ashr_i32 s0, s2, 8
	v_sub_u32_e32 v0, v0, v2
	s_lshl_b32 s40, s10, 10
	s_lshr_b32 s3, s7, 3
	s_mul_hi_i32 s5, s4, 0x160000
	s_mul_i32 s4, s4, 0x160000
	v_ashrrev_i16_sdwa v0, v3, sext(v0) dst_sel:DWORD dst_unused:UNUSED_PAD src0_sel:DWORD src1_sel:BYTE_0
	v_lshlrev_b32_e32 v2, 1, v1
	v_lshrrev_b32_e32 v3, 2, v1
	s_add_u32 s24, s34, s4
	v_bfe_i32 v15, v0, 0, 16
	v_and_b32_e32 v2, 24, v2
	v_and_b32_e32 v3, 4, v3
	s_addc_u32 s25, s35, s5
	s_add_i32 s41, s40, 0
	v_add_u32_e32 v0, v14, v15
	v_or3_b32 v2, v4, v3, v2
	v_mul_lo_u32 v1, v1, s1
	s_add_i32 m0, s41, 0x10000
	v_add_lshl_u32 v132, v0, v1, 1
	v_mul_u32_u24_e32 v1, 0xb00, v2
	global_load_lds_dwordx4 v130, s[24:25]
	s_add_i32 m0, s41, 0x12000
	v_add_lshl_u32 v134, v1, v0, 1
	s_add_u32 s4, s24, 0xb0000
	global_load_lds_dwordx4 v134, s[24:25]
	s_addc_u32 s5, s25, 0
	s_add_i32 m0, s41, 0x14000
	s_mul_i32 s11, s56, 0x160000
	global_load_lds_dwordx4 v130, s[4:5]
	s_add_i32 m0, s41, 0x16000
	s_mul_hi_i32 s6, s56, 0x160000
	s_add_u32 s22, s36, s11
	s_addc_u32 s23, s37, s6
	s_add_i32 s42, s41, 0x2000
	global_load_lds_dwordx4 v134, s[4:5]
	s_mov_b32 m0, s41
	s_add_u32 s4, s22, 0xb0000
	global_load_lds_dwordx4 v128, s[22:23]
	s_mov_b32 m0, s42
	s_addc_u32 s5, s23, 0
	s_add_i32 s43, s41, 0x4000
	global_load_lds_dwordx4 v132, s[22:23]
	s_mov_b32 m0, s43
	s_add_i32 s44, s41, 0x6000
	global_load_lds_dwordx4 v128, s[4:5]
	s_mov_b32 m0, s44
	v_mov_b32_e32 v131, 0
	global_load_lds_dwordx4 v132, s[4:5]
	v_mov_b32_e32 v135, v131
	v_mov_b32_e32 v129, v131
	v_mov_b32_e32 v133, v131
	s_cmp_eq_u32 s0, 1
	s_mov_b32 s45, 0
	v_lshl_add_u64 v[6:7], s[24:25], 0, v[130:131]
	v_lshl_add_u64 v[2:3], s[24:25], 0, v[134:135]
	s_mov_b64 s[4:5], 0xb0000
	v_lshl_add_u64 v[0:1], s[22:23], 0, v[128:129]
	s_cselect_b64 s[6:7], -1, 0
	s_cmp_lg_u32 s0, 1
	v_lshl_add_u64 v[4:5], s[22:23], 0, v[132:133]
	s_cbranch_scc1 .LBB0_1654
	s_barrier
	s_setprio 1

.LBB0_1668:
	ds_read_b128 v[144:147], v169
	ds_read_b128 v[148:151], v169 offset:1024
	ds_read_b128 v[152:155], v169 offset:2048
	ds_read_b128 v[156:159], v169 offset:3072
	ds_read_b128 v[160:163], v170
	ds_read_b128 v[172:175], v170 offset:1024
	ds_read_b128 v[176:179], v170 offset:2048
	ds_read_b128 v[180:183], v170 offset:3072
	s_add_u32 s24, s22, 0x100
	s_addc_u32 s25, s23, 0
	s_cmp_eq_u32 s60, 40
	s_cselect_b32 s31, s3, s25
	s_cselect_b32 s30, s2, s24
	s_cselect_b32 s27, s21, s59
	s_cselect_b32 s26, s20, s58
	v_lshl_add_u64 v[164:165], s[22:23], 0, v[136:137]
	s_add_i32 m0, s41, 0xc000
	ds_read_b128 v[184:187], v171
	ds_read_b128 v[188:191], v171 offset:1024
	ds_read_b128 v[192:195], v171 offset:2048
	ds_read_b128 v[196:199], v171 offset:3072
	ds_read_b128 v[200:203], v171 offset:4096
	ds_read_b128 v[204:207], v171 offset:5120
	ds_read_b128 v[208:211], v171 offset:6144
	ds_read_b128 v[212:215], v171 offset:7168
	global_load_lds_dwordx4 v[164:165], off
	v_lshl_add_u64 v[164:165], s[22:23], 0, v[138:139]
	s_add_i32 m0, s41, 0xe000
	s_nop 0
	global_load_lds_dwordx4 v[164:165], off
	s_waitcnt vmcnt(8)
	s_waitcnt lgkmcnt(0)
	s_barrier
	s_waitcnt lgkmcnt(0)
	v_mfma_f32_16x16x32_f16 v[124:127], v[144:147], v[184:187], v[124:127]
	v_mfma_f32_16x16x32_f16 v[120:123], v[152:155], v[184:187], v[120:123]
	v_mfma_f32_16x16x32_f16 v[116:119], v[144:147], v[192:195], v[116:119]
	v_mfma_f32_16x16x32_f16 v[112:115], v[152:155], v[192:195], v[112:115]
	v_mfma_f32_16x16x32_f16 v[92:95], v[144:147], v[200:203], v[92:95]
	v_mfma_f32_16x16x32_f16 v[88:91], v[152:155], v[200:203], v[88:91]
	v_mfma_f32_16x16x32_f16 v[84:87], v[144:147], v[208:211], v[84:87]
	v_mfma_f32_16x16x32_f16 v[80:83], v[152:155], v[208:211], v[80:83]
	v_mfma_f32_16x16x32_f16 v[124:127], v[148:151], v[188:191], v[124:127]
	v_mfma_f32_16x16x32_f16 v[120:123], v[156:159], v[188:191], v[120:123]
	v_mfma_f32_16x16x32_f16 v[116:119], v[148:151], v[196:199], v[116:119]
	v_mfma_f32_16x16x32_f16 v[112:115], v[156:159], v[196:199], v[112:115]
	v_mfma_f32_16x16x32_f16 v[92:95], v[148:151], v[204:207], v[92:95]
	v_mfma_f32_16x16x32_f16 v[88:91], v[156:159], v[204:207], v[88:91]
	v_mfma_f32_16x16x32_f16 v[84:87], v[148:151], v[212:215], v[84:87]
	v_mfma_f32_16x16x32_f16 v[80:83], v[156:159], v[212:215], v[80:83]
	v_mfma_f32_16x16x32_f16 v[108:111], v[160:163], v[184:187], v[108:111]
	v_mfma_f32_16x16x32_f16 v[104:107], v[176:179], v[184:187], v[104:107]
	v_mfma_f32_16x16x32_f16 v[100:103], v[160:163], v[192:195], v[100:103]
	v_mfma_f32_16x16x32_f16 v[96:99], v[176:179], v[192:195], v[96:99]
	v_mfma_f32_16x16x32_f16 v[76:79], v[160:163], v[200:203], v[76:79]
	v_mfma_f32_16x16x32_f16 v[72:75], v[176:179], v[200:203], v[72:75]
	v_mfma_f32_16x16x32_f16 v[68:71], v[160:163], v[208:211], v[68:71]
	v_mfma_f32_16x16x32_f16 v[64:67], v[176:179], v[208:211], v[64:67]
	v_mfma_f32_16x16x32_f16 v[108:111], v[172:175], v[188:191], v[108:111]
	v_mfma_f32_16x16x32_f16 v[104:107], v[180:183], v[188:191], v[104:107]
	v_mfma_f32_16x16x32_f16 v[100:103], v[172:175], v[196:199], v[100:103]
	v_mfma_f32_16x16x32_f16 v[96:99], v[180:183], v[196:199], v[96:99]
	v_mfma_f32_16x16x32_f16 v[76:79], v[172:175], v[204:207], v[76:79]
	v_mfma_f32_16x16x32_f16 v[72:75], v[180:183], v[204:207], v[72:75]
	v_mfma_f32_16x16x32_f16 v[68:71], v[172:175], v[212:215], v[68:71]
	v_mfma_f32_16x16x32_f16 v[64:67], v[180:183], v[212:215], v[64:67]
	s_barrier
	s_add_i32 s22, s51, s40
	v_lshl_add_u64 v[164:165], s[26:27], 0, v[130:131]
	s_mov_b32 m0, s22
	ds_read_b128 v[184:187], v171 offset:16384
	ds_read_b128 v[188:191], v171 offset:17408
	ds_read_b128 v[192:195], v171 offset:18432
	ds_read_b128 v[196:199], v171 offset:19456
	ds_read_b128 v[200:203], v171 offset:20480
	ds_read_b128 v[204:207], v171 offset:21504
	ds_read_b128 v[208:211], v171 offset:22528
	ds_read_b128 v[212:215], v171 offset:23552
	global_load_lds_dwordx4 v[164:165], off
	s_add_i32 m0, s22, 0x2000
	s_add_u32 s22, s26, 0xb0000
	v_lshl_add_u64 v[216:217], s[26:27], 0, v[134:135]
	s_addc_u32 s23, s27, 0
	s_add_i32 s61, s52, s40
	global_load_lds_dwordx4 v[216:217], off
	v_lshl_add_u64 v[218:219], s[22:23], 0, v[130:131]
	s_mov_b32 m0, s61
	v_lshl_add_u64 v[220:221], s[30:31], 0, v[132:133]
	global_load_lds_dwordx4 v[218:219], off
	v_lshl_add_u64 v[218:219], s[22:23], 0, v[134:135]
	s_add_i32 m0, s61, 0x2000
	s_nop 0
	global_load_lds_dwordx4 v[218:219], off
	v_lshl_add_u64 v[218:219], s[30:31], 0, v[128:129]
	s_mov_b32 m0, s41
	s_nop 0
	global_load_lds_dwordx4 v[218:219], off
	s_mov_b32 m0, s42
	s_nop 0
	global_load_lds_dwordx4 v[220:221], off
	s_waitcnt vmcnt(8)
	s_waitcnt lgkmcnt(0)
	s_barrier
	s_waitcnt lgkmcnt(0)
	v_mfma_f32_16x16x32_f16 v[60:63], v[144:147], v[184:187], v[60:63]
	v_mfma_f32_16x16x32_f16 v[56:59], v[152:155], v[184:187], v[56:59]
	v_mfma_f32_16x16x32_f16 v[52:55], v[144:147], v[192:195], v[52:55]
	v_mfma_f32_16x16x32_f16 v[48:51], v[152:155], v[192:195], v[48:51]
	v_mfma_f32_16x16x32_f16 v[28:31], v[144:147], v[200:203], v[28:31]
	v_mfma_f32_16x16x32_f16 v[24:27], v[152:155], v[200:203], v[24:27]
	v_mfma_f32_16x16x32_f16 v[20:23], v[144:147], v[208:211], v[20:23]
	v_mfma_f32_16x16x32_f16 v[16:19], v[152:155], v[208:211], v[16:19]
	v_mfma_f32_16x16x32_f16 v[60:63], v[148:151], v[188:191], v[60:63]
	v_mfma_f32_16x16x32_f16 v[56:59], v[156:159], v[188:191], v[56:59]
	v_mfma_f32_16x16x32_f16 v[52:55], v[148:151], v[196:199], v[52:55]
	v_mfma_f32_16x16x32_f16 v[48:51], v[156:159], v[196:199], v[48:51]
	v_mfma_f32_16x16x32_f16 v[28:31], v[148:151], v[204:207], v[28:31]
	v_mfma_f32_16x16x32_f16 v[24:27], v[156:159], v[204:207], v[24:27]
	v_mfma_f32_16x16x32_f16 v[20:23], v[148:151], v[212:215], v[20:23]
	v_mfma_f32_16x16x32_f16 v[16:19], v[156:159], v[212:215], v[16:19]
	v_mfma_f32_16x16x32_f16 v[44:47], v[160:163], v[184:187], v[44:47]
	v_mfma_f32_16x16x32_f16 v[40:43], v[176:179], v[184:187], v[40:43]
	v_mfma_f32_16x16x32_f16 v[36:39], v[160:163], v[192:195], v[36:39]
	v_mfma_f32_16x16x32_f16 v[32:35], v[176:179], v[192:195], v[32:35]
	v_mfma_f32_16x16x32_f16 v[12:15], v[160:163], v[200:203], v[12:15]
	v_mfma_f32_16x16x32_f16 v[8:11], v[176:179], v[200:203], v[8:11]
	v_mfma_f32_16x16x32_f16 v[4:7], v[160:163], v[208:211], v[4:7]
	v_mfma_f32_16x16x32_f16 v[0:3], v[176:179], v[208:211], v[0:3]
	v_mfma_f32_16x16x32_f16 v[44:47], v[172:175], v[188:191], v[44:47]
	v_mfma_f32_16x16x32_f16 v[40:43], v[180:183], v[188:191], v[40:43]
	v_mfma_f32_16x16x32_f16 v[36:39], v[172:175], v[196:199], v[36:39]
	v_mfma_f32_16x16x32_f16 v[32:35], v[180:183], v[196:199], v[32:35]
	v_mfma_f32_16x16x32_f16 v[12:15], v[172:175], v[204:207], v[12:15]
	v_mfma_f32_16x16x32_f16 v[8:11], v[180:183], v[204:207], v[8:11]
	v_mfma_f32_16x16x32_f16 v[4:7], v[172:175], v[212:215], v[4:7]
	v_mfma_f32_16x16x32_f16 v[0:3], v[180:183], v[212:215], v[0:3]
	s_barrier
	s_add_i32 s61, 0, 0x18000
	s_add_i32 s62, 0, 0x1c000
	v_add_u32_e32 v156, s61, v167
	v_add_u32_e32 v180, s62, v167
	ds_read_b128 v[144:147], v156
	ds_read_b128 v[148:151], v156 offset:1024
	ds_read_b128 v[152:155], v156 offset:2048
	ds_read_b128 v[156:159], v156 offset:3072
	ds_read_b128 v[160:163], v180
	ds_read_b128 v[172:175], v180 offset:1024
	ds_read_b128 v[176:179], v180 offset:2048
	ds_read_b128 v[180:183], v180 offset:3072
	s_add_u32 s22, s30, 0xb0000
	s_addc_u32 s23, s31, 0
	s_mov_b32 m0, s43
	v_lshl_add_u64 v[222:223], s[22:23], 0, v[128:129]
	ds_read_b128 v[184:187], v171 offset:32768
	ds_read_b128 v[188:191], v171 offset:33792
	ds_read_b128 v[192:195], v171 offset:34816
	ds_read_b128 v[196:199], v171 offset:35840
	ds_read_b128 v[200:203], v171 offset:36864
	ds_read_b128 v[204:207], v171 offset:37888
	ds_read_b128 v[208:211], v171 offset:38912
	ds_read_b128 v[212:215], v171 offset:39936
	global_load_lds_dwordx4 v[222:223], off
	v_lshl_add_u64 v[222:223], s[22:23], 0, v[132:133]
	s_mov_b32 m0, s44
	s_nop 0
	global_load_lds_dwordx4 v[222:223], off
	s_waitcnt vmcnt(8)
	s_waitcnt lgkmcnt(0)
	s_barrier
	s_waitcnt lgkmcnt(0)
	v_mfma_f32_16x16x32_f16 v[124:127], v[144:147], v[184:187], v[124:127]
	v_mfma_f32_16x16x32_f16 v[120:123], v[152:155], v[184:187], v[120:123]
	v_mfma_f32_16x16x32_f16 v[116:119], v[144:147], v[192:195], v[116:119]
	v_mfma_f32_16x16x32_f16 v[112:115], v[152:155], v[192:195], v[112:115]
	v_mfma_f32_16x16x32_f16 v[92:95], v[144:147], v[200:203], v[92:95]
	v_mfma_f32_16x16x32_f16 v[88:91], v[152:155], v[200:203], v[88:91]
	v_mfma_f32_16x16x32_f16 v[84:87], v[144:147], v[208:211], v[84:87]
	v_mfma_f32_16x16x32_f16 v[80:83], v[152:155], v[208:211], v[80:83]
	v_mfma_f32_16x16x32_f16 v[124:127], v[148:151], v[188:191], v[124:127]
	v_mfma_f32_16x16x32_f16 v[120:123], v[156:159], v[188:191], v[120:123]
	v_mfma_f32_16x16x32_f16 v[116:119], v[148:151], v[196:199], v[116:119]
	v_mfma_f32_16x16x32_f16 v[112:115], v[156:159], v[196:199], v[112:115]
	v_mfma_f32_16x16x32_f16 v[92:95], v[148:151], v[204:207], v[92:95]
	v_mfma_f32_16x16x32_f16 v[88:91], v[156:159], v[204:207], v[88:91]
	v_mfma_f32_16x16x32_f16 v[84:87], v[148:151], v[212:215], v[84:87]
	v_mfma_f32_16x16x32_f16 v[80:83], v[156:159], v[212:215], v[80:83]
	v_mfma_f32_16x16x32_f16 v[108:111], v[160:163], v[184:187], v[108:111]
	v_mfma_f32_16x16x32_f16 v[104:107], v[176:179], v[184:187], v[104:107]
	v_mfma_f32_16x16x32_f16 v[100:103], v[160:163], v[192:195], v[100:103]
	v_mfma_f32_16x16x32_f16 v[96:99], v[176:179], v[192:195], v[96:99]
	v_mfma_f32_16x16x32_f16 v[76:79], v[160:163], v[200:203], v[76:79]
	v_mfma_f32_16x16x32_f16 v[72:75], v[176:179], v[200:203], v[72:75]
	v_mfma_f32_16x16x32_f16 v[68:71], v[160:163], v[208:211], v[68:71]
	v_mfma_f32_16x16x32_f16 v[64:67], v[176:179], v[208:211], v[64:67]
	v_mfma_f32_16x16x32_f16 v[108:111], v[172:175], v[188:191], v[108:111]
	v_mfma_f32_16x16x32_f16 v[104:107], v[180:183], v[188:191], v[104:107]
	v_mfma_f32_16x16x32_f16 v[100:103], v[172:175], v[196:199], v[100:103]
	v_mfma_f32_16x16x32_f16 v[96:99], v[180:183], v[196:199], v[96:99]
	v_mfma_f32_16x16x32_f16 v[76:79], v[172:175], v[204:207], v[76:79]
	v_mfma_f32_16x16x32_f16 v[72:75], v[180:183], v[204:207], v[72:75]
	v_mfma_f32_16x16x32_f16 v[68:71], v[172:175], v[212:215], v[68:71]
	v_mfma_f32_16x16x32_f16 v[64:67], v[180:183], v[212:215], v[64:67]
	s_barrier
	s_add_i32 s22, s61, s40
	v_lshl_add_u64 v[164:165], v[164:165], 0, s[10:11]
	s_mov_b32 m0, s22
	ds_read_b128 v[184:187], v171 offset:49152
	ds_read_b128 v[188:191], v171 offset:50176
	ds_read_b128 v[192:195], v171 offset:51200
	ds_read_b128 v[196:199], v171 offset:52224
	ds_read_b128 v[200:203], v171 offset:53248
	ds_read_b128 v[204:207], v171 offset:54272
	ds_read_b128 v[208:211], v171 offset:55296
	ds_read_b128 v[212:215], v171 offset:56320
	global_load_lds_dwordx4 v[164:165], off
	s_add_i32 m0, s22, 0x2000
	s_add_u32 s22, s26, 0xb0080
	v_lshl_add_u64 v[164:165], v[216:217], 0, s[10:11]
	s_addc_u32 s23, s27, 0
	s_add_i32 s26, s62, s40
	global_load_lds_dwordx4 v[164:165], off
	v_lshl_add_u64 v[164:165], s[22:23], 0, v[130:131]
	s_mov_b32 m0, s26
	s_nop 0
	global_load_lds_dwordx4 v[164:165], off
	v_lshl_add_u64 v[164:165], s[22:23], 0, v[134:135]
	s_add_i32 m0, s26, 0x2000
	s_nop 0
	global_load_lds_dwordx4 v[164:165], off
	v_lshl_add_u64 v[164:165], v[218:219], 0, s[10:11]
	s_mov_b32 m0, s48
	s_nop 0
	global_load_lds_dwordx4 v[164:165], off
	v_lshl_add_u64 v[164:165], v[220:221], 0, s[10:11]
	s_mov_b32 m0, s49
	s_nop 0
	global_load_lds_dwordx4 v[164:165], off
	s_waitcnt vmcnt(8)
	s_waitcnt lgkmcnt(0)
	s_barrier
	s_waitcnt lgkmcnt(0)
	v_mfma_f32_16x16x32_f16 v[60:63], v[144:147], v[184:187], v[60:63]
	v_mfma_f32_16x16x32_f16 v[56:59], v[152:155], v[184:187], v[56:59]
	v_mfma_f32_16x16x32_f16 v[52:55], v[144:147], v[192:195], v[52:55]
	v_mfma_f32_16x16x32_f16 v[48:51], v[152:155], v[192:195], v[48:51]
	v_mfma_f32_16x16x32_f16 v[28:31], v[144:147], v[200:203], v[28:31]
	v_mfma_f32_16x16x32_f16 v[24:27], v[152:155], v[200:203], v[24:27]
	v_mfma_f32_16x16x32_f16 v[20:23], v[144:147], v[208:211], v[20:23]
	v_mfma_f32_16x16x32_f16 v[16:19], v[152:155], v[208:211], v[16:19]
	v_mfma_f32_16x16x32_f16 v[60:63], v[148:151], v[188:191], v[60:63]
	v_mfma_f32_16x16x32_f16 v[56:59], v[156:159], v[188:191], v[56:59]
	v_mfma_f32_16x16x32_f16 v[52:55], v[148:151], v[196:199], v[52:55]
	v_mfma_f32_16x16x32_f16 v[48:51], v[156:159], v[196:199], v[48:51]
	v_mfma_f32_16x16x32_f16 v[28:31], v[148:151], v[204:207], v[28:31]
	v_mfma_f32_16x16x32_f16 v[24:27], v[156:159], v[204:207], v[24:27]
	v_mfma_f32_16x16x32_f16 v[20:23], v[148:151], v[212:215], v[20:23]
	v_mfma_f32_16x16x32_f16 v[16:19], v[156:159], v[212:215], v[16:19]
	v_mfma_f32_16x16x32_f16 v[44:47], v[160:163], v[184:187], v[44:47]
	v_mfma_f32_16x16x32_f16 v[40:43], v[176:179], v[184:187], v[40:43]
	v_mfma_f32_16x16x32_f16 v[36:39], v[160:163], v[192:195], v[36:39]
	v_mfma_f32_16x16x32_f16 v[32:35], v[176:179], v[192:195], v[32:35]
	v_mfma_f32_16x16x32_f16 v[12:15], v[160:163], v[200:203], v[12:15]
	v_mfma_f32_16x16x32_f16 v[8:11], v[176:179], v[200:203], v[8:11]
	v_mfma_f32_16x16x32_f16 v[4:7], v[160:163], v[208:211], v[4:7]
	v_mfma_f32_16x16x32_f16 v[0:3], v[176:179], v[208:211], v[0:3]
	v_mfma_f32_16x16x32_f16 v[44:47], v[172:175], v[188:191], v[44:47]
	v_mfma_f32_16x16x32_f16 v[40:43], v[180:183], v[188:191], v[40:43]
	v_mfma_f32_16x16x32_f16 v[36:39], v[172:175], v[196:199], v[36:39]
	v_mfma_f32_16x16x32_f16 v[32:35], v[180:183], v[196:199], v[32:35]
	v_mfma_f32_16x16x32_f16 v[12:15], v[172:175], v[204:207], v[12:15]
	v_mfma_f32_16x16x32_f16 v[8:11], v[180:183], v[204:207], v[8:11]
	v_mfma_f32_16x16x32_f16 v[4:7], v[172:175], v[212:215], v[4:7]
	v_mfma_f32_16x16x32_f16 v[0:3], v[180:183], v[212:215], v[0:3]
	s_barrier
	s_add_i32 s60, s60, 2
	s_add_u32 s58, s58, 0x100
	s_addc_u32 s59, s59, 0
	s_cmp_gt_u32 s60, 41
	s_mov_b64 s[22:23], s[24:25]
	s_cbranch_scc0 .LBB0_1668
	s_and_b64 vcc, exec, s[12:13]
	s_cbranch_vccz .LBB0_1671
	s_barrier
